# gate/up GEMM: next-unit row-scale partial loads issued together and reduced after the epilogue; EpiRes residual loads hoisted; MLA loop: 3-slot K ring with 2-deep DMA prefetch, DMA issue and row sums
# speedup vs baseline: 1.0031x; 1.0031x over previous
; __device__ __forceinline__ unsigned cvt_pk_bf16(float lo, float hi) { unsigned r; asm volatile("v_cvt_pk_bf16_f32 %0, %1, %2" : "=v"(r) : "v"(lo), "v"(hi)); return r; }
;     __device__ __forceinline__ void operator()(const f32x4 (&acc)[2][2][4][2], const Unit& u, int wr, int wc, int fr, int fq, const float (&rs)[2][4]) const {
;     ...
;         const int row0 = u.pm * BM + wr * 64 + fr, col0 = u.pn * HALF + wc * 32 + 8 * fq;
; #pragma unroll
;         for (int ai = 0; ai < 2; ++ai)
; #pragma unroll
;             for (int m = 0; m < 4; ++m) { bf16_t* rowp = O + (size_t)(row0 + ai * HALF + m * 16) * FF + col0;
;                 float r[8], e[8]; const float rsv = rs[ai][m]; const float c1 = -rsv * LOG2E, c2 = rsv * rsv;
; #pragma unroll
;                 for (int j = 0; j < 8; ++j) { const float gv = acc[ai][0][m][j >> 2][j & 3], uv = acc[ai][1][m][j >> 2][j & 3]; e[j] = gv * c1; r[j] = gv * uv; }
;                 __builtin_amdgcn_sched_barrier(0);
; #pragma unroll
;                 for (int j = 0; j < 8; ++j) e[j] = __builtin_amdgcn_exp2f(e[j]);
;                 __builtin_amdgcn_sched_barrier(0);
; #pragma unroll
;                 for (int j = 0; j < 8; ++j) e[j] = 1.0f + e[j];
;                 __builtin_amdgcn_sched_barrier(0);
; #pragma unroll
;                 for (int j = 0; j < 8; ++j) e[j] = __builtin_amdgcn_rcpf(e[j]);
;                 __builtin_amdgcn_sched_barrier(0);
; #pragma unroll
;                 for (int j = 0; j < 8; ++j) r[j] = r[j] * (c2 * e[j]);
;                 u32x4 w; w.x = cvt_pk_bf16(r[0], r[1]); w.y = cvt_pk_bf16(r[2], r[3]); w.z = cvt_pk_bf16(r[4], r[5]); w.w = cvt_pk_bf16(r[6], r[7]);
;                 *(u32x4*)rowp = w; }
.LBB0_607:
	v_cndmask_b32_e64 v130, 0, 1, s[42:43]
	v_cmp_ne_u32_e64 s[40:41], 1, v130
	s_andn2_b64 vcc, exec, s[42:43]
	s_cbranch_vccnz .LBB0_609
	v_lshl_add_u32 v232, s66, 8, v170
	v_ashrrev_i32_e32 v233, 31, v232
	v_lshlrev_b64 v[234:235], 6, v[232:233]
	v_lshl_add_u64 v[234:235], v[142:143], 0, v[234:235]
	v_add_u32_e32 v232, 0x80, v232
	v_ashrrev_i32_e32 v233, 31, v232
	v_lshlrev_b64 v[236:237], 6, v[232:233]
	v_lshl_add_u64 v[236:237], v[142:143], 0, v[236:237]
	global_load_dwordx4 v[200:203], v[234:235], off
	global_load_dwordx4 v[204:207], v[234:235], off offset:1024
	global_load_dwordx4 v[208:211], v[234:235], off offset:2048
	global_load_dwordx4 v[212:215], v[234:235], off offset:3072
	global_load_dwordx4 v[216:219], v[236:237], off
	global_load_dwordx4 v[220:223], v[236:237], off offset:1024
	global_load_dwordx4 v[224:227], v[236:237], off offset:2048
	global_load_dwordx4 v[228:231], v[236:237], off offset:3072
.LBB0_609:
	s_lshl_b32 s0, s44, 8
	v_mov_b32_e32 v130, v168
	v_mov_b32_e32 v131, v166
	s_add_i32 s0, s0, s74
	s_nop 0
	v_add_u32_e32 v181, s0, v131
	s_lshl_b32 s0, s45, 7
	s_or_b32 s0, s0, s28
	v_lshl_add_u32 v164, v130, 3, s0
	v_ashrrev_i32_e32 v165, 31, v164
	v_lshl_add_u64 v[164:165], v[164:165], 1, s[36:37]
	v_mul_f32_e32 v130, 0xbfb8aa3b, v163
	v_mul_f32_e32 v131, v130, v126
	v_mul_f32_e32 v134, v130, v127
	v_mul_f32_e32 v135, v130, v128
	v_mul_f32_e32 v169, v130, v129
	v_mul_f32_e32 v171, v130, v118
	v_mul_f32_e32 v178, v130, v119
	v_mul_f32_e32 v179, v130, v120
	v_mul_f32_e32 v130, v130, v121
	v_mad_i64_i32 v[176:177], s[0:1], v181, s11, v[164:165]
	v_exp_f32_e32 v131, v131
	v_exp_f32_e32 v134, v134
	v_exp_f32_e32 v135, v135
	v_exp_f32_e32 v169, v169
	v_exp_f32_e32 v171, v171
	v_exp_f32_e32 v178, v178
	v_exp_f32_e32 v179, v179
	v_exp_f32_e32 v130, v130
	v_add_f32_e32 v131, 1.0, v131
	v_add_f32_e32 v134, 1.0, v134
	v_add_f32_e32 v135, 1.0, v135
	v_add_f32_e32 v169, 1.0, v169
	v_add_f32_e32 v171, 1.0, v171
	v_add_f32_e32 v183, 1.0, v178
	v_add_f32_e32 v179, 1.0, v179
	v_add_f32_e32 v130, 1.0, v130
	v_rcp_f32_e32 v178, v131
	v_rcp_f32_e32 v182, v134
	v_rcp_f32_e32 v184, v135
	v_rcp_f32_e32 v186, v169
	v_rcp_f32_e32 v188, v171
	v_rcp_f32_e32 v190, v183
	v_rcp_f32_e32 v192, v179
	v_rcp_f32_e32 v194, v130
	v_pk_mul_f32 v[196:197], v[162:163], v[162:163]
	v_mov_b32_e32 v199, v126
	v_mov_b32_e32 v126, v197
	v_mov_b32_e32 v183, v123
	v_mov_b32_e32 v179, v122
	v_pk_mul_f32 v[122:123], v[126:127], v[182:183]
	v_mov_b32_e32 v185, v124
	v_mul_f32_e32 v126, v122, v123
	v_mov_b32_e32 v122, v197
	v_mov_b32_e32 v123, v128
	v_pk_mul_f32 v[122:123], v[122:123], v[184:185]
	v_mov_b32_e32 v128, v197
	v_mov_b32_e32 v187, v125
	v_mul_f32_e32 v124, v122, v123
	v_pk_mul_f32 v[122:123], v[128:129], v[186:187]
	v_mov_b32_e32 v191, v115
	v_mul_f32_e32 v125, v122, v123
	v_mov_b32_e32 v123, v118
	v_mov_b32_e32 v118, v197
	v_mov_b32_e32 v189, v114
	v_pk_mul_f32 v[114:115], v[118:119], v[190:191]
	v_mov_b32_e32 v193, v116
	v_mul_f32_e32 v118, v114, v115
	v_mov_b32_e32 v114, v197
	v_mov_b32_e32 v115, v120
	v_mov_b32_e32 v198, v197
	v_pk_mul_f32 v[114:115], v[114:115], v[192:193]
	v_mov_b32_e32 v120, v197
	v_mov_b32_e32 v195, v117
	v_pk_mul_f32 v[178:179], v[198:199], v[178:179]
	v_mov_b32_e32 v122, v197
	v_mul_f32_e32 v119, v114, v115
	v_pk_mul_f32 v[114:115], v[120:121], v[194:195]
	v_mul_f32_e32 v130, v178, v179
	v_pk_mul_f32 v[122:123], v[122:123], v[188:189]
	v_mul_f32_e32 v117, v114, v115
	v_cvt_pk_bf16_f32 v114, v130, v126
	v_cvt_pk_bf16_f32 v115, v124, v125
	v_mul_f32_e32 v122, v122, v123
	v_cvt_pk_bf16_f32 v116, v122, v118
	v_cvt_pk_bf16_f32 v117, v119, v117
	global_store_dwordx4 v[176:177], v[114:117], off
	s_nop 1
	v_add_u32_e32 v114, 16, v181
	v_mul_f32_e32 v115, 0xbfb8aa3b, v162
	v_mul_f32_e32 v116, v115, v110
	v_mul_f32_e32 v117, v115, v111
	v_mul_f32_e32 v118, v115, v112
	v_mul_f32_e32 v119, v115, v113
	v_mul_f32_e32 v120, v115, v106
	v_mul_f32_e32 v121, v115, v107
	v_mul_f32_e32 v122, v115, v108
	v_mul_f32_e32 v123, v115, v109
	v_mad_i64_i32 v[114:115], s[0:1], v114, s11, v[164:165]
	v_exp_f32_e32 v116, v116
	v_exp_f32_e32 v117, v117
	v_exp_f32_e32 v118, v118
	v_exp_f32_e32 v119, v119
	v_exp_f32_e32 v120, v120
	v_exp_f32_e32 v121, v121
	v_exp_f32_e32 v122, v122
	v_exp_f32_e32 v123, v123
	v_add_f32_e32 v116, 1.0, v116
	v_add_f32_e32 v117, 1.0, v117
	v_add_f32_e32 v124, 1.0, v118
	v_add_f32_e32 v119, 1.0, v119
	v_add_f32_e32 v125, 1.0, v120
	v_add_f32_e32 v121, 1.0, v121
	v_add_f32_e32 v127, 1.0, v122
	v_add_f32_e32 v123, 1.0, v123
	v_rcp_f32_e32 v162, v123
	v_rcp_f32_e32 v116, v116
	v_rcp_f32_e32 v118, v117
	v_rcp_f32_e32 v120, v124
	v_rcp_f32_e32 v122, v119
	v_rcp_f32_e32 v124, v125
	v_rcp_f32_e32 v126, v121
	v_rcp_f32_e32 v128, v127
	v_mov_b32_e32 v197, v110
	v_mov_b32_e32 v117, v102
	v_pk_mul_f32 v[116:117], v[196:197], v[116:117]
	v_mov_b32_e32 v197, v111
	v_mov_b32_e32 v119, v103
	v_pk_mul_f32 v[102:103], v[196:197], v[118:119]
	v_mov_b32_e32 v197, v112
	v_mov_b32_e32 v121, v104
	v_mul_f32_e32 v111, v102, v103
	v_pk_mul_f32 v[102:103], v[196:197], v[120:121]
	v_mov_b32_e32 v197, v113
	v_mov_b32_e32 v123, v105
	v_mul_f32_e32 v104, v102, v103
	v_pk_mul_f32 v[102:103], v[196:197], v[122:123]
	v_mov_b32_e32 v197, v106
	v_mov_b32_e32 v125, v98
	v_mul_f32_e32 v105, v102, v103
	v_pk_mul_f32 v[102:103], v[196:197], v[124:125]
	v_mov_b32_e32 v197, v107
	v_mov_b32_e32 v127, v99
	v_pk_mul_f32 v[98:99], v[196:197], v[126:127]
	v_mov_b32_e32 v197, v108
	v_mov_b32_e32 v129, v100
	v_mul_f32_e32 v102, v102, v103
	v_mul_f32_e32 v103, v98, v99
	v_pk_mul_f32 v[98:99], v[196:197], v[128:129]
	v_mov_b32_e32 v197, v109
	v_mov_b32_e32 v163, v101
; __device__ __forceinline__ unsigned cvt_pk_bf16(float lo, float hi) { unsigned r; asm volatile("v_cvt_pk_bf16_f32 %0, %1, %2" : "=v"(r) : "v"(lo), "v"(hi)); return r; }
;     __device__ __forceinline__ void operator()(const f32x4 (&acc)[2][2][4][2], const Unit& u, int wr, int wc, int fr, int fq, const float (&rs)[2][4]) const {
;     ...
;             for (int m = 0; m < 4; ++m) { bf16_t* rowp = O + (size_t)(row0 + ai * HALF + m * 16) * FF + col0;
;                 float r[8], e[8]; const float rsv = rs[ai][m]; const float c1 = -rsv * LOG2E, c2 = rsv * rsv;
; #pragma unroll
;                 for (int j = 0; j < 8; ++j) { const float gv = acc[ai][0][m][j >> 2][j & 3], uv = acc[ai][1][m][j >> 2][j & 3]; e[j] = gv * c1; r[j] = gv * uv; }
;                 __builtin_amdgcn_sched_barrier(0);
; #pragma unroll
;                 for (int j = 0; j < 8; ++j) e[j] = __builtin_amdgcn_exp2f(e[j]);
;                 __builtin_amdgcn_sched_barrier(0);
; #pragma unroll
;                 for (int j = 0; j < 8; ++j) e[j] = 1.0f + e[j];
;                 __builtin_amdgcn_sched_barrier(0);
; #pragma unroll
;                 for (int j = 0; j < 8; ++j) e[j] = __builtin_amdgcn_rcpf(e[j]);
;                 __builtin_amdgcn_sched_barrier(0);
; #pragma unroll
;                 for (int j = 0; j < 8; ++j) r[j] = r[j] * (c2 * e[j]);
;                 u32x4 w; w.x = cvt_pk_bf16(r[0], r[1]); w.y = cvt_pk_bf16(r[2], r[3]); w.z = cvt_pk_bf16(r[4], r[5]); w.w = cvt_pk_bf16(r[6], r[7]);
;                 *(u32x4*)rowp = w; }
	v_mul_f32_e32 v106, v98, v99
	v_pk_mul_f32 v[98:99], v[196:197], v[162:163]
	v_mul_f32_e32 v110, v116, v117
	v_mul_f32_e32 v101, v98, v99
	v_cvt_pk_bf16_f32 v98, v110, v111
	v_cvt_pk_bf16_f32 v99, v104, v105
	v_cvt_pk_bf16_f32 v100, v102, v103
	v_cvt_pk_bf16_f32 v101, v106, v101
	global_store_dwordx4 v[114:115], v[98:101], off
	s_nop 1
	v_add_u32_e32 v98, 32, v181
	v_mul_f32_e32 v99, 0xbfb8aa3b, v161
	v_mul_f32_e32 v100, v99, v94
	v_mul_f32_e32 v101, v99, v95
	v_mul_f32_e32 v102, v99, v96
	v_mul_f32_e32 v103, v99, v97
	v_mul_f32_e32 v104, v99, v86
	v_mul_f32_e32 v105, v99, v87
	v_mul_f32_e32 v106, v99, v88
	v_mul_f32_e32 v107, v99, v89
	v_mad_i64_i32 v[98:99], s[0:1], v98, s11, v[164:165]
	v_exp_f32_e32 v100, v100
	v_exp_f32_e32 v101, v101
	v_exp_f32_e32 v102, v102
	v_exp_f32_e32 v103, v103
	v_exp_f32_e32 v104, v104
	v_exp_f32_e32 v105, v105
	v_exp_f32_e32 v106, v106
	v_exp_f32_e32 v107, v107
	v_add_f32_e32 v100, 1.0, v100
	v_add_f32_e32 v101, 1.0, v101
	v_add_f32_e32 v108, 1.0, v102
	v_add_f32_e32 v103, 1.0, v103
	v_add_f32_e32 v109, 1.0, v104
	v_add_f32_e32 v105, 1.0, v105
	v_add_f32_e32 v111, 1.0, v106
	v_add_f32_e32 v107, 1.0, v107
	v_rcp_f32_e32 v100, v100
	v_rcp_f32_e32 v102, v101
	v_rcp_f32_e32 v104, v108
	v_rcp_f32_e32 v106, v103
	v_rcp_f32_e32 v108, v109
	v_rcp_f32_e32 v110, v105
	v_rcp_f32_e32 v112, v111
	v_rcp_f32_e32 v114, v107
	v_pk_mul_f32 v[116:117], v[160:161], v[160:161]
	v_mov_b32_e32 v119, v94
	v_mov_b32_e32 v94, v117
	v_mov_b32_e32 v103, v91
	v_mov_b32_e32 v101, v90
	v_pk_mul_f32 v[90:91], v[94:95], v[102:103]
	v_mov_b32_e32 v105, v92
	v_mul_f32_e32 v94, v90, v91
	v_mov_b32_e32 v90, v117
	v_mov_b32_e32 v91, v96
	v_pk_mul_f32 v[90:91], v[90:91], v[104:105]
	v_mov_b32_e32 v96, v117
	v_mov_b32_e32 v107, v93
	v_mul_f32_e32 v92, v90, v91
	v_pk_mul_f32 v[90:91], v[96:97], v[106:107]
	v_mov_b32_e32 v111, v83
	v_mul_f32_e32 v93, v90, v91
	v_mov_b32_e32 v91, v86
	v_mov_b32_e32 v86, v117
	v_mov_b32_e32 v109, v82
	v_pk_mul_f32 v[82:83], v[86:87], v[110:111]
	v_mov_b32_e32 v113, v84
	v_mul_f32_e32 v86, v82, v83
	v_mov_b32_e32 v82, v117
	v_mov_b32_e32 v83, v88
	v_mov_b32_e32 v118, v117
	v_pk_mul_f32 v[82:83], v[82:83], v[112:113]
	v_mov_b32_e32 v88, v117
	v_mov_b32_e32 v115, v85
	v_pk_mul_f32 v[100:101], v[118:119], v[100:101]
	v_mov_b32_e32 v90, v117
	v_mul_f32_e32 v87, v82, v83
	v_pk_mul_f32 v[82:83], v[88:89], v[114:115]
	v_mul_f32_e32 v100, v100, v101
	v_pk_mul_f32 v[90:91], v[90:91], v[108:109]
	v_mul_f32_e32 v85, v82, v83
	v_cvt_pk_bf16_f32 v82, v100, v94
	v_cvt_pk_bf16_f32 v83, v92, v93
	v_mul_f32_e32 v90, v90, v91
	v_cvt_pk_bf16_f32 v84, v90, v86
	v_cvt_pk_bf16_f32 v85, v87, v85
	global_store_dwordx4 v[98:99], v[82:85], off
	s_nop 1
	v_add_u32_e32 v82, 48, v181
	v_mul_f32_e32 v83, 0xbfb8aa3b, v160
	v_mul_f32_e32 v84, v83, v76
	v_mul_f32_e32 v85, v83, v77
	v_mul_f32_e32 v86, v83, v78
	v_mul_f32_e32 v87, v83, v79
	v_mul_f32_e32 v88, v83, v72
	v_mul_f32_e32 v89, v83, v73
	v_mul_f32_e32 v90, v83, v74
	v_mul_f32_e32 v91, v83, v75
	v_mad_i64_i32 v[82:83], s[0:1], v82, s11, v[164:165]
	v_exp_f32_e32 v84, v84
	v_exp_f32_e32 v85, v85
	v_exp_f32_e32 v86, v86
	v_exp_f32_e32 v87, v87
	v_exp_f32_e32 v88, v88
	v_exp_f32_e32 v89, v89
	v_exp_f32_e32 v90, v90
	v_exp_f32_e32 v91, v91
	v_add_f32_e32 v84, 1.0, v84
	v_add_f32_e32 v85, 1.0, v85
	v_add_f32_e32 v92, 1.0, v86
	v_add_f32_e32 v87, 1.0, v87
	v_add_f32_e32 v93, 1.0, v88
	v_add_f32_e32 v89, 1.0, v89
	v_add_f32_e32 v95, 1.0, v90
	v_add_f32_e32 v91, 1.0, v91
	v_rcp_f32_e32 v84, v84
	v_rcp_f32_e32 v86, v85
	v_rcp_f32_e32 v88, v92
	v_rcp_f32_e32 v90, v87
	v_rcp_f32_e32 v92, v93
	v_rcp_f32_e32 v94, v89
	v_rcp_f32_e32 v96, v95
	v_rcp_f32_e32 v98, v91
	v_mov_b32_e32 v117, v76
	v_mov_b32_e32 v85, v68
	v_pk_mul_f32 v[84:85], v[116:117], v[84:85]
	v_mov_b32_e32 v117, v77
	v_mov_b32_e32 v87, v69
	v_pk_mul_f32 v[68:69], v[116:117], v[86:87]
	v_mov_b32_e32 v117, v78
	v_mov_b32_e32 v89, v70
	v_mul_f32_e32 v77, v68, v69
	v_pk_mul_f32 v[68:69], v[116:117], v[88:89]
	v_mov_b32_e32 v117, v79
	v_mov_b32_e32 v91, v71
	v_mul_f32_e32 v70, v68, v69
	v_pk_mul_f32 v[68:69], v[116:117], v[90:91]
	v_mov_b32_e32 v117, v72
	v_mov_b32_e32 v93, v64
	v_mul_f32_e32 v71, v68, v69
	v_pk_mul_f32 v[68:69], v[116:117], v[92:93]
	v_mov_b32_e32 v117, v73
	v_mov_b32_e32 v95, v65
	v_pk_mul_f32 v[64:65], v[116:117], v[94:95]
	v_mov_b32_e32 v117, v74
	v_mov_b32_e32 v97, v66
	v_mul_f32_e32 v68, v68, v69
	v_mul_f32_e32 v69, v64, v65
	v_pk_mul_f32 v[64:65], v[116:117], v[96:97]
	v_mov_b32_e32 v117, v75
	v_mov_b32_e32 v99, v67
	v_mul_f32_e32 v72, v64, v65
	v_pk_mul_f32 v[64:65], v[116:117], v[98:99]
	v_mul_f32_e32 v76, v84, v85
	v_mul_f32_e32 v67, v64, v65
	v_cvt_pk_bf16_f32 v64, v76, v77
	v_cvt_pk_bf16_f32 v65, v70, v71
	v_cvt_pk_bf16_f32 v66, v68, v69
	v_cvt_pk_bf16_f32 v67, v72, v67
	global_store_dwordx4 v[82:83], v[64:67], off
	s_nop 1
	v_add_u32_e32 v64, 0x80, v181
	v_mul_f32_e32 v65, 0xbfb8aa3b, v159
	v_mul_f32_e32 v66, v65, v60
	v_mul_f32_e32 v67, v65, v61
	v_mul_f32_e32 v68, v65, v62
	v_mul_f32_e32 v69, v65, v63
	v_mul_f32_e32 v70, v65, v52
	v_mul_f32_e32 v71, v65, v53
	v_mul_f32_e32 v72, v65, v54
	v_mul_f32_e32 v73, v65, v55
	v_mad_i64_i32 v[64:65], s[0:1], v64, s11, v[164:165]
	v_exp_f32_e32 v66, v66
	v_exp_f32_e32 v67, v67
	v_exp_f32_e32 v68, v68
	v_exp_f32_e32 v69, v69
	v_exp_f32_e32 v70, v70
	v_exp_f32_e32 v71, v71
	v_exp_f32_e32 v72, v72
	v_exp_f32_e32 v73, v73
	v_add_f32_e32 v66, 1.0, v66
	v_add_f32_e32 v67, 1.0, v67
	v_add_f32_e32 v74, 1.0, v68
	v_add_f32_e32 v69, 1.0, v69
	v_add_f32_e32 v75, 1.0, v70
	v_add_f32_e32 v71, 1.0, v71
	v_add_f32_e32 v77, 1.0, v72
	v_add_f32_e32 v73, 1.0, v73
	v_rcp_f32_e32 v66, v66
; __device__ __forceinline__ unsigned cvt_pk_bf16(float lo, float hi) { unsigned r; asm volatile("v_cvt_pk_bf16_f32 %0, %1, %2" : "=v"(r) : "v"(lo), "v"(hi)); return r; }
;     __device__ __forceinline__ void operator()(const f32x4 (&acc)[2][2][4][2], const Unit& u, int wr, int wc, int fr, int fq, const float (&rs)[2][4]) const {
;     ...
;             for (int m = 0; m < 4; ++m) { bf16_t* rowp = O + (size_t)(row0 + ai * HALF + m * 16) * FF + col0;
;                 float r[8], e[8]; const float rsv = rs[ai][m]; const float c1 = -rsv * LOG2E, c2 = rsv * rsv;
; #pragma unroll
;                 for (int j = 0; j < 8; ++j) { const float gv = acc[ai][0][m][j >> 2][j & 3], uv = acc[ai][1][m][j >> 2][j & 3]; e[j] = gv * c1; r[j] = gv * uv; }
;                 __builtin_amdgcn_sched_barrier(0);
; #pragma unroll
;                 for (int j = 0; j < 8; ++j) e[j] = __builtin_amdgcn_exp2f(e[j]);
;                 __builtin_amdgcn_sched_barrier(0);
; #pragma unroll
;                 for (int j = 0; j < 8; ++j) e[j] = 1.0f + e[j];
;                 __builtin_amdgcn_sched_barrier(0);
; #pragma unroll
;                 for (int j = 0; j < 8; ++j) e[j] = __builtin_amdgcn_rcpf(e[j]);
;                 __builtin_amdgcn_sched_barrier(0);
; #pragma unroll
;                 for (int j = 0; j < 8; ++j) r[j] = r[j] * (c2 * e[j]);
;                 u32x4 w; w.x = cvt_pk_bf16(r[0], r[1]); w.y = cvt_pk_bf16(r[2], r[3]); w.z = cvt_pk_bf16(r[4], r[5]); w.w = cvt_pk_bf16(r[6], r[7]);
;                 *(u32x4*)rowp = w; }
	v_rcp_f32_e32 v68, v67
	v_rcp_f32_e32 v70, v74
	v_rcp_f32_e32 v72, v69
	v_rcp_f32_e32 v74, v75
	v_rcp_f32_e32 v76, v71
	v_rcp_f32_e32 v78, v77
	v_rcp_f32_e32 v82, v73
	v_pk_mul_f32 v[84:85], v[158:159], v[158:159]
	v_mov_b32_e32 v87, v60
	v_mov_b32_e32 v60, v85
	v_mov_b32_e32 v69, v57
	v_mov_b32_e32 v67, v56
	v_pk_mul_f32 v[56:57], v[60:61], v[68:69]
	v_mov_b32_e32 v71, v58
	v_mul_f32_e32 v60, v56, v57
	v_mov_b32_e32 v56, v85
	v_mov_b32_e32 v57, v62
	v_pk_mul_f32 v[56:57], v[56:57], v[70:71]
	v_mov_b32_e32 v62, v85
	v_mov_b32_e32 v73, v59
	v_mul_f32_e32 v58, v56, v57
	v_pk_mul_f32 v[56:57], v[62:63], v[72:73]
	v_mov_b32_e32 v77, v49
	v_mul_f32_e32 v59, v56, v57
	v_mov_b32_e32 v57, v52
	v_mov_b32_e32 v52, v85
	v_mov_b32_e32 v75, v48
	v_pk_mul_f32 v[48:49], v[52:53], v[76:77]
	v_mov_b32_e32 v79, v50
	v_mul_f32_e32 v52, v48, v49
	v_mov_b32_e32 v48, v85
	v_mov_b32_e32 v49, v54
	v_mov_b32_e32 v86, v85
	v_pk_mul_f32 v[48:49], v[48:49], v[78:79]
	v_mov_b32_e32 v54, v85
	v_mov_b32_e32 v83, v51
	v_pk_mul_f32 v[66:67], v[86:87], v[66:67]
	v_mov_b32_e32 v56, v85
	v_mul_f32_e32 v53, v48, v49
	v_pk_mul_f32 v[48:49], v[54:55], v[82:83]
	v_mul_f32_e32 v66, v66, v67
	v_pk_mul_f32 v[56:57], v[56:57], v[74:75]
	v_mul_f32_e32 v51, v48, v49
	v_cvt_pk_bf16_f32 v48, v66, v60
	v_cvt_pk_bf16_f32 v49, v58, v59
	v_mul_f32_e32 v56, v56, v57
	v_cvt_pk_bf16_f32 v50, v56, v52
	v_cvt_pk_bf16_f32 v51, v53, v51
	global_store_dwordx4 v[64:65], v[48:51], off
	s_nop 1
	v_add_u32_e32 v48, 0x90, v181
	v_mul_f32_e32 v49, 0xbfb8aa3b, v158
	v_mul_f32_e32 v50, v49, v44
	v_mul_f32_e32 v51, v49, v45
	v_mul_f32_e32 v52, v49, v46
	v_mul_f32_e32 v53, v49, v47
	v_mul_f32_e32 v54, v49, v40
	v_mul_f32_e32 v55, v49, v41
	v_mul_f32_e32 v56, v49, v42
	v_mul_f32_e32 v57, v49, v43
	v_mad_i64_i32 v[48:49], s[0:1], v48, s11, v[164:165]
	v_exp_f32_e32 v50, v50
	v_exp_f32_e32 v51, v51
	v_exp_f32_e32 v52, v52
	v_exp_f32_e32 v53, v53
	v_exp_f32_e32 v54, v54
	v_exp_f32_e32 v55, v55
	v_exp_f32_e32 v56, v56
	v_exp_f32_e32 v57, v57
	v_add_f32_e32 v50, 1.0, v50
	v_add_f32_e32 v51, 1.0, v51
	v_add_f32_e32 v58, 1.0, v52
	v_add_f32_e32 v53, 1.0, v53
	v_add_f32_e32 v59, 1.0, v54
	v_add_f32_e32 v55, 1.0, v55
	v_add_f32_e32 v61, 1.0, v56
	v_add_f32_e32 v57, 1.0, v57
	v_rcp_f32_e32 v50, v50
	v_rcp_f32_e32 v52, v51
	v_rcp_f32_e32 v54, v58
	v_rcp_f32_e32 v56, v53
	v_rcp_f32_e32 v58, v59
	v_rcp_f32_e32 v60, v55
	v_rcp_f32_e32 v62, v61
	v_rcp_f32_e32 v64, v57
	v_mov_b32_e32 v85, v44
	v_mov_b32_e32 v51, v36
	v_pk_mul_f32 v[50:51], v[84:85], v[50:51]
	v_mov_b32_e32 v85, v45
	v_mov_b32_e32 v53, v37
	v_pk_mul_f32 v[36:37], v[84:85], v[52:53]
	v_mov_b32_e32 v85, v46
	v_mov_b32_e32 v55, v38
	v_mul_f32_e32 v45, v36, v37
	v_pk_mul_f32 v[36:37], v[84:85], v[54:55]
	v_mov_b32_e32 v85, v47
	v_mov_b32_e32 v57, v39
	v_mul_f32_e32 v38, v36, v37
	v_pk_mul_f32 v[36:37], v[84:85], v[56:57]
	v_mov_b32_e32 v85, v40
	v_mov_b32_e32 v59, v32
	v_mul_f32_e32 v39, v36, v37
	v_pk_mul_f32 v[36:37], v[84:85], v[58:59]
	v_mov_b32_e32 v85, v41
	v_mov_b32_e32 v61, v33
	v_pk_mul_f32 v[32:33], v[84:85], v[60:61]
	v_mov_b32_e32 v85, v42
	v_mov_b32_e32 v63, v34
	v_mul_f32_e32 v36, v36, v37
	v_mul_f32_e32 v37, v32, v33
	v_pk_mul_f32 v[32:33], v[84:85], v[62:63]
	v_mov_b32_e32 v85, v43
	v_mov_b32_e32 v65, v35
	v_mul_f32_e32 v40, v32, v33
	v_pk_mul_f32 v[32:33], v[84:85], v[64:65]
	v_mul_f32_e32 v44, v50, v51
	v_mul_f32_e32 v35, v32, v33
	v_cvt_pk_bf16_f32 v32, v44, v45
	v_cvt_pk_bf16_f32 v33, v38, v39
	v_cvt_pk_bf16_f32 v34, v36, v37
	v_cvt_pk_bf16_f32 v35, v40, v35
	global_store_dwordx4 v[48:49], v[32:35], off
	s_nop 1
	v_add_u32_e32 v32, 0xa0, v181
	v_mul_f32_e32 v33, 0xbfb8aa3b, v157
	v_mul_f32_e32 v34, v33, v28
	v_mul_f32_e32 v35, v33, v29
	v_mul_f32_e32 v36, v33, v30
	v_mul_f32_e32 v37, v33, v31
	v_mul_f32_e32 v38, v33, v20
	v_mul_f32_e32 v39, v33, v21
	v_mul_f32_e32 v40, v33, v22
	v_mul_f32_e32 v41, v33, v23
	v_mad_i64_i32 v[32:33], s[0:1], v32, s11, v[164:165]
	v_exp_f32_e32 v34, v34
	v_exp_f32_e32 v35, v35
	v_exp_f32_e32 v36, v36
	v_exp_f32_e32 v37, v37
	v_exp_f32_e32 v38, v38
	v_exp_f32_e32 v39, v39
	v_exp_f32_e32 v40, v40
	v_exp_f32_e32 v41, v41
	v_add_f32_e32 v34, 1.0, v34
	v_add_f32_e32 v35, 1.0, v35
	v_add_f32_e32 v42, 1.0, v36
	v_add_f32_e32 v37, 1.0, v37
	v_add_f32_e32 v43, 1.0, v38
	v_add_f32_e32 v39, 1.0, v39
	v_add_f32_e32 v45, 1.0, v40
	v_add_f32_e32 v41, 1.0, v41
	v_rcp_f32_e32 v34, v34
	v_rcp_f32_e32 v36, v35
	v_rcp_f32_e32 v38, v42
	v_rcp_f32_e32 v40, v37
	v_rcp_f32_e32 v42, v43
	v_rcp_f32_e32 v44, v39
	v_rcp_f32_e32 v46, v45
	v_rcp_f32_e32 v48, v41
	v_pk_mul_f32 v[50:51], v[156:157], v[156:157]
	v_mov_b32_e32 v53, v28
	v_mov_b32_e32 v28, v51
	v_mov_b32_e32 v37, v25
	v_mov_b32_e32 v35, v24
	v_pk_mul_f32 v[24:25], v[28:29], v[36:37]
	v_mov_b32_e32 v39, v26
	v_mul_f32_e32 v28, v24, v25
	v_mov_b32_e32 v24, v51
	v_mov_b32_e32 v25, v30
	v_pk_mul_f32 v[24:25], v[24:25], v[38:39]
	v_mov_b32_e32 v30, v51
	v_mov_b32_e32 v41, v27
	v_mul_f32_e32 v26, v24, v25
	v_pk_mul_f32 v[24:25], v[30:31], v[40:41]
	v_mov_b32_e32 v45, v17
	v_mul_f32_e32 v27, v24, v25
	v_mov_b32_e32 v25, v20
	v_mov_b32_e32 v20, v51
	v_mov_b32_e32 v43, v16
	v_pk_mul_f32 v[16:17], v[20:21], v[44:45]
	v_mov_b32_e32 v47, v18
	v_mul_f32_e32 v20, v16, v17
	v_mov_b32_e32 v16, v51
	v_mov_b32_e32 v17, v22
	v_mov_b32_e32 v52, v51
	v_pk_mul_f32 v[16:17], v[16:17], v[46:47]
	v_mov_b32_e32 v22, v51
	v_mov_b32_e32 v49, v19
	v_pk_mul_f32 v[34:35], v[52:53], v[34:35]
; __device__ __forceinline__ unsigned cvt_pk_bf16(float lo, float hi) { unsigned r; asm volatile("v_cvt_pk_bf16_f32 %0, %1, %2" : "=v"(r) : "v"(lo), "v"(hi)); return r; }
;     __device__ __forceinline__ void operator()(const f32x4 (&acc)[2][2][4][2], const Unit& u, int wr, int wc, int fr, int fq, const float (&rs)[2][4]) const {
;     ...
;             for (int m = 0; m < 4; ++m) { bf16_t* rowp = O + (size_t)(row0 + ai * HALF + m * 16) * FF + col0;
;                 float r[8], e[8]; const float rsv = rs[ai][m]; const float c1 = -rsv * LOG2E, c2 = rsv * rsv;
; #pragma unroll
;                 for (int j = 0; j < 8; ++j) { const float gv = acc[ai][0][m][j >> 2][j & 3], uv = acc[ai][1][m][j >> 2][j & 3]; e[j] = gv * c1; r[j] = gv * uv; }
;                 __builtin_amdgcn_sched_barrier(0);
; #pragma unroll
;                 for (int j = 0; j < 8; ++j) e[j] = __builtin_amdgcn_exp2f(e[j]);
;                 __builtin_amdgcn_sched_barrier(0);
; #pragma unroll
;                 for (int j = 0; j < 8; ++j) e[j] = 1.0f + e[j];
;                 __builtin_amdgcn_sched_barrier(0);
; #pragma unroll
;                 for (int j = 0; j < 8; ++j) e[j] = __builtin_amdgcn_rcpf(e[j]);
;                 __builtin_amdgcn_sched_barrier(0);
; #pragma unroll
;                 for (int j = 0; j < 8; ++j) r[j] = r[j] * (c2 * e[j]);
;                 u32x4 w; w.x = cvt_pk_bf16(r[0], r[1]); w.y = cvt_pk_bf16(r[2], r[3]); w.z = cvt_pk_bf16(r[4], r[5]); w.w = cvt_pk_bf16(r[6], r[7]);
;                 *(u32x4*)rowp = w; }
	v_mov_b32_e32 v24, v51
	v_mul_f32_e32 v21, v16, v17
	v_pk_mul_f32 v[16:17], v[22:23], v[48:49]
	v_mul_f32_e32 v34, v34, v35
	v_pk_mul_f32 v[24:25], v[24:25], v[42:43]
	v_mul_f32_e32 v19, v16, v17
	v_cvt_pk_bf16_f32 v16, v34, v28
	v_cvt_pk_bf16_f32 v17, v26, v27
	v_mul_f32_e32 v24, v24, v25
	v_cvt_pk_bf16_f32 v18, v24, v20
	v_cvt_pk_bf16_f32 v19, v21, v19
	global_store_dwordx4 v[32:33], v[16:19], off
	s_nop 1
	v_add_u32_e32 v16, 0xb0, v181
	v_mul_f32_e32 v17, 0xbfb8aa3b, v156
	v_mul_f32_e32 v18, v17, v12
	v_mul_f32_e32 v19, v17, v13
	v_mul_f32_e32 v20, v17, v14
	v_mul_f32_e32 v21, v17, v15
	v_mul_f32_e32 v22, v17, v8
	v_mul_f32_e32 v23, v17, v9
	v_mul_f32_e32 v24, v17, v10
	v_mul_f32_e32 v25, v17, v11
	v_mad_i64_i32 v[16:17], s[0:1], v16, s11, v[164:165]
	v_exp_f32_e32 v18, v18
	v_exp_f32_e32 v19, v19
	v_exp_f32_e32 v20, v20
	v_exp_f32_e32 v21, v21
	v_exp_f32_e32 v22, v22
	v_exp_f32_e32 v23, v23
	v_exp_f32_e32 v24, v24
	v_exp_f32_e32 v25, v25
	v_add_f32_e32 v18, 1.0, v18
	v_add_f32_e32 v19, 1.0, v19
	v_add_f32_e32 v26, 1.0, v20
	v_add_f32_e32 v21, 1.0, v21
	v_add_f32_e32 v27, 1.0, v22
	v_add_f32_e32 v23, 1.0, v23
	v_add_f32_e32 v29, 1.0, v24
	v_add_f32_e32 v25, 1.0, v25
	v_rcp_f32_e32 v18, v18
	v_rcp_f32_e32 v20, v19
	v_rcp_f32_e32 v22, v26
	v_rcp_f32_e32 v24, v21
	v_rcp_f32_e32 v26, v27
	v_rcp_f32_e32 v28, v23
	v_rcp_f32_e32 v30, v29
	v_rcp_f32_e32 v32, v25
	v_mov_b32_e32 v51, v12
	v_mov_b32_e32 v19, v4
	v_pk_mul_f32 v[18:19], v[50:51], v[18:19]
	v_mov_b32_e32 v51, v13
	v_mov_b32_e32 v21, v5
	v_pk_mul_f32 v[4:5], v[50:51], v[20:21]
	v_mov_b32_e32 v51, v14
	v_mov_b32_e32 v23, v6
	v_mul_f32_e32 v13, v4, v5
	v_pk_mul_f32 v[4:5], v[50:51], v[22:23]
	v_mov_b32_e32 v51, v15
	v_mov_b32_e32 v25, v7
	v_mul_f32_e32 v6, v4, v5
	v_pk_mul_f32 v[4:5], v[50:51], v[24:25]
	v_mov_b32_e32 v51, v8
	v_mov_b32_e32 v27, v0
	v_mul_f32_e32 v7, v4, v5
	v_pk_mul_f32 v[4:5], v[50:51], v[26:27]
	v_mov_b32_e32 v51, v9
	v_mov_b32_e32 v29, v1
	v_pk_mul_f32 v[0:1], v[50:51], v[28:29]
	v_mov_b32_e32 v51, v10
	v_mov_b32_e32 v31, v2
	v_mul_f32_e32 v4, v4, v5
	v_mul_f32_e32 v5, v0, v1
	v_pk_mul_f32 v[0:1], v[50:51], v[30:31]
	v_mov_b32_e32 v51, v11
	v_mov_b32_e32 v33, v3
	v_mul_f32_e32 v8, v0, v1
	v_pk_mul_f32 v[0:1], v[50:51], v[32:33]
	s_and_b64 vcc, exec, s[40:41]
	v_mul_f32_e32 v3, v0, v1
	s_mov_b64 s[40:41], -1
	v_mul_f32_e32 v12, v18, v19
	v_cvt_pk_bf16_f32 v0, v12, v13
	v_cvt_pk_bf16_f32 v1, v6, v7
	v_cvt_pk_bf16_f32 v2, v4, v5
	v_cvt_pk_bf16_f32 v3, v8, v3
	global_store_dwordx4 v[16:17], v[0:3], off
	s_cbranch_vccnz .LBB0_600
	s_waitcnt vmcnt(8)
	v_add_f32_e32 v232, v200, v201
	v_add_f32_e32 v233, v202, v203
	v_add_f32_e32 v145, v232, v233
	v_add_f32_e32 v232, v204, v205
	v_add_f32_e32 v233, v206, v207
	v_add_f32_e32 v144, v232, v233
	v_add_f32_e32 v232, v208, v209
	v_add_f32_e32 v233, v210, v211
	v_add_f32_e32 v147, v232, v233
	v_add_f32_e32 v232, v212, v213
	v_add_f32_e32 v233, v214, v215
	v_add_f32_e32 v146, v232, v233
	v_add_f32_e32 v232, v216, v217
	v_add_f32_e32 v233, v218, v219
	v_add_f32_e32 v149, v232, v233
	v_add_f32_e32 v232, v220, v221
	v_add_f32_e32 v233, v222, v223
	v_add_f32_e32 v148, v232, v233
	v_add_f32_e32 v232, v224, v225
	v_add_f32_e32 v233, v226, v227
	v_add_f32_e32 v155, v232, v233
	v_add_f32_e32 v232, v228, v229
	v_add_f32_e32 v233, v230, v231
	v_add_f32_e32 v154, v232, v233
	ds_swizzle_b32 v0, v145 offset:swizzle(SWAP,16)
	ds_swizzle_b32 v2, v144 offset:swizzle(SWAP,16)
	ds_swizzle_b32 v4, v146 offset:swizzle(SWAP,16)
	ds_swizzle_b32 v8, v148 offset:swizzle(SWAP,16)
	ds_swizzle_b32 v10, v154 offset:swizzle(SWAP,16)
	s_waitcnt lgkmcnt(0)
	v_add_f32_e32 v1, v145, v0
	v_add_f32_e32 v0, v144, v2
	v_mov_b32_e32 v3, v1
	v_mov_b32_e32 v2, v0
	s_nop 0
	v_permlane32_swap_b32_e32 v1, v3
	v_permlane32_swap_b32_e32 v0, v2
	v_pk_add_f32 v[0:1], v[0:1], v[2:3]
	ds_swizzle_b32 v2, v147 offset:swizzle(SWAP,16)
	s_mov_b32 s0, 0x358637bd
	v_mov_b64_e32 v[6:7], s[0:1]
	v_pk_fma_f32 v[0:1], v[0:1], s[90:91], v[6:7] op_sel_hi:[1,0,0]
	s_andn2_b64 vcc, exec, s[62:63]
	s_waitcnt lgkmcnt(0)
	v_add_f32_e32 v3, v147, v2
	v_add_f32_e32 v2, v146, v4
	v_mov_b32_e32 v5, v3
	v_mov_b32_e32 v4, v2
	s_nop 0
	v_permlane32_swap_b32_e32 v3, v5
	v_permlane32_swap_b32_e32 v2, v4
	v_pk_add_f32 v[2:3], v[2:3], v[4:5]
	ds_swizzle_b32 v4, v149 offset:swizzle(SWAP,16)
	v_pk_fma_f32 v[2:3], v[2:3], s[90:91], v[6:7] op_sel_hi:[1,0,0]
	v_cmp_gt_f32_e64 s[40:41], s10, v0
	v_cmp_gt_f32_e64 s[42:43], s10, v1
	v_cmp_gt_f32_e64 s[44:45], s10, v2
	s_waitcnt lgkmcnt(0)
	v_add_f32_e32 v5, v149, v4
	v_add_f32_e32 v4, v148, v8
	v_mov_b32_e32 v9, v5
	v_mov_b32_e32 v8, v4
	s_nop 0
	v_permlane32_swap_b32_e32 v5, v9
	v_permlane32_swap_b32_e32 v4, v8
	v_pk_add_f32 v[4:5], v[4:5], v[8:9]
	ds_swizzle_b32 v8, v155 offset:swizzle(SWAP,16)
	v_pk_fma_f32 v[4:5], v[4:5], s[90:91], v[6:7] op_sel_hi:[1,0,0]
	v_cmp_gt_f32_e64 s[48:49], s10, v3
	v_cmp_gt_f32_e64 s[46:47], s10, v4
	v_cmp_gt_f32_e64 s[50:51], s10, v5
	s_waitcnt lgkmcnt(0)
	v_add_f32_e32 v9, v155, v8
	v_add_f32_e32 v8, v154, v10
	v_mov_b32_e32 v11, v9
	v_mov_b32_e32 v10, v8
	s_nop 0
	v_permlane32_swap_b32_e32 v9, v11
	v_permlane32_swap_b32_e32 v8, v10
	v_pk_add_f32 v[8:9], v[8:9], v[10:11]
	s_nop 0
	v_pk_fma_f32 v[6:7], v[8:9], s[90:91], v[6:7] op_sel_hi:[1,0,0]
	s_nop 0
	v_cmp_gt_f32_e64 s[52:53], s10, v6
	v_cmp_gt_f32_e64 s[54:55], s10, v7
	s_cbranch_vccnz .LBB0_599
	s_barrier
	s_branch .LBB0_599

; __device__ __forceinline__ unsigned cvt_pk_bf16(float lo, float hi) { unsigned r; asm volatile("v_cvt_pk_bf16_f32 %0, %1, %2" : "=v"(r) : "v"(lo), "v"(hi)); return r; }
; __device__ __forceinline__ float bf_lo(unsigned w) { return __uint_as_float(w << 16); }
; __device__ __forceinline__ float bf_hi(unsigned w) { return __uint_as_float(w & 0xffff0000u); }
;     __device__ __forceinline__ void operator()(const f32x4 (&acc)[2][2][4][2], const Unit& u, int wr, int wc, int fr, int fq, const float (&rs)[2][4]) const {
;         asm volatile("" : "+v"(fr), "+v"(fq));
;         const int row0 = u.pm * BM + wr * 64 + fr, col0 = u.pn * BM + wc * 32 + 8 * fq;
; #pragma unroll
;         for (int ai = 0; ai < 2; ++ai) {
; #pragma unroll
;             for (int m = 0; m < 4; ++m) { bf16_t* rowp = X + (size_t)(row0 + ai * HALF + m * 16) * DM + col0; float ss = 0.f;
; #pragma unroll
;                 for (int bj = 0; bj < 2; ++bj) { const u32x4 bw = *(const u32x4*)(rowp + bj * HALF); const f32x4 a0 = acc[ai][bj][m][0], a1 = acc[ai][bj][m][1];
;                     u32x4 w; w.x = cvt_pk_bf16(bf_lo(bw.x) + alpha * a0[0], bf_hi(bw.x) + alpha * a0[1]); w.y = cvt_pk_bf16(bf_lo(bw.y) + alpha * a0[2], bf_hi(bw.y) + alpha * a0[3]);
;                     w.z = cvt_pk_bf16(bf_lo(bw.z) + alpha * a1[0], bf_hi(bw.z) + alpha * a1[1]); w.w = cvt_pk_bf16(bf_lo(bw.w) + alpha * a1[2], bf_hi(bw.w) + alpha * a1[3]);
;                     *(u32x4*)(rowp + bj * HALF) = w;
;                     ss += (bf_lo(w.x) * bf_lo(w.x) + bf_hi(w.x) * bf_hi(w.x)) + (bf_lo(w.y) * bf_lo(w.y) + bf_hi(w.y) * bf_hi(w.y));
;                     ss += (bf_lo(w.z) * bf_lo(w.z) + bf_hi(w.z) * bf_hi(w.z)) + (bf_lo(w.w) * bf_lo(w.w) + bf_hi(w.w) * bf_hi(w.w)); }
;                 ss = fq_sum(ss);
;                 if (fq == 0) part[(size_t)(row0 + ai * HALF + m * 16) * 16 + u.pn * 4 + wc] = ss; } }
.LBB0_731:
	s_lshl_b32 s0, s27, 8
	v_mov_b32_e32 v130, v151
	v_mov_b32_e32 v131, v150
	s_add_i32 s0, s0, s71
	s_lshl_b32 s48, s26, 2
	v_add_u32_e32 v148, s0, v130
	s_lshl_b32 s0, s26, 8
	s_or_b32 s0, s0, s72
	v_ashrrev_i32_e32 v149, 31, v148
	v_lshl_add_u32 v146, v131, 3, s0
	v_lshlrev_b64 v[154:155], 11, v[148:149]
	v_ashrrev_i32_e32 v147, 31, v146
	v_lshl_add_u64 v[154:155], s[94:95], 0, v[154:155]
	v_lshl_add_u64 v[158:159], v[146:147], 1, v[154:155]
	global_load_dwordx4 v[182:185], v[158:159], off
	global_load_dwordx4 v[186:189], v[158:159], off offset:256
	v_add_u32_e32 v246, 16, v148
	v_ashrrev_i32_e32 v247, 31, v246
	v_lshlrev_b64 v[246:247], 11, v[246:247]
	v_lshl_add_u64 v[246:247], s[94:95], 0, v[246:247]
	v_lshl_add_u64 v[246:247], v[146:147], 1, v[246:247]
	global_load_dwordx4 v[190:193], v[246:247], off
	global_load_dwordx4 v[194:197], v[246:247], off offset:256
	v_add_u32_e32 v248, 32, v148
	v_ashrrev_i32_e32 v249, 31, v248
	v_lshlrev_b64 v[248:249], 11, v[248:249]
	v_lshl_add_u64 v[248:249], s[94:95], 0, v[248:249]
	v_lshl_add_u64 v[248:249], v[146:147], 1, v[248:249]
	global_load_dwordx4 v[198:201], v[248:249], off
	global_load_dwordx4 v[202:205], v[248:249], off offset:256
	v_add_u32_e32 v246, 48, v148
	v_ashrrev_i32_e32 v247, 31, v246
	v_lshlrev_b64 v[246:247], 11, v[246:247]
	v_lshl_add_u64 v[246:247], s[94:95], 0, v[246:247]
	v_lshl_add_u64 v[246:247], v[146:147], 1, v[246:247]
	global_load_dwordx4 v[206:209], v[246:247], off
	global_load_dwordx4 v[210:213], v[246:247], off offset:256
	v_add_u32_e32 v248, 0x80, v148
	v_ashrrev_i32_e32 v249, 31, v248
	v_lshlrev_b64 v[248:249], 11, v[248:249]
	v_lshl_add_u64 v[248:249], s[94:95], 0, v[248:249]
	v_lshl_add_u64 v[248:249], v[146:147], 1, v[248:249]
	global_load_dwordx4 v[214:217], v[248:249], off
	global_load_dwordx4 v[218:221], v[248:249], off offset:256
	v_add_u32_e32 v246, 0x90, v148
	v_ashrrev_i32_e32 v247, 31, v246
	v_lshlrev_b64 v[246:247], 11, v[246:247]
	v_lshl_add_u64 v[246:247], s[94:95], 0, v[246:247]
	v_lshl_add_u64 v[246:247], v[146:147], 1, v[246:247]
	global_load_dwordx4 v[222:225], v[246:247], off
	global_load_dwordx4 v[226:229], v[246:247], off offset:256
	v_add_u32_e32 v248, 0xa0, v148
	v_ashrrev_i32_e32 v249, 31, v248
	v_lshlrev_b64 v[248:249], 11, v[248:249]
	v_lshl_add_u64 v[248:249], s[94:95], 0, v[248:249]
	v_lshl_add_u64 v[248:249], v[146:147], 1, v[248:249]
	global_load_dwordx4 v[230:233], v[248:249], off
	global_load_dwordx4 v[234:237], v[248:249], off offset:256
	v_add_u32_e32 v246, 0xb0, v148
	v_ashrrev_i32_e32 v247, 31, v246
	v_lshlrev_b64 v[246:247], 11, v[246:247]
	v_lshl_add_u64 v[246:247], s[94:95], 0, v[246:247]
	v_lshl_add_u64 v[246:247], v[146:147], 1, v[246:247]
	global_load_dwordx4 v[238:241], v[246:247], off
	global_load_dwordx4 v[242:245], v[246:247], off offset:256
	s_waitcnt vmcnt(0)
	s_ashr_i32 s49, s48, 31
	v_cmp_eq_u32_e32 vcc, 0, v131
	v_lshlrev_b32_e32 v130, 16, v182
	v_and_b32_e32 v134, 0xffff0000, v182
	v_lshlrev_b32_e32 v135, 16, v183
	v_and_b32_e32 v154, 0xffff0000, v183
	v_lshlrev_b32_e32 v155, 16, v184
	v_and_b32_e32 v156, 0xffff0000, v184
	v_lshlrev_b32_e32 v160, 16, v185
	v_and_b32_e32 v157, 0xffff0000, v185
	v_fmac_f32_e32 v130, 0.5, v126
	v_fmac_f32_e32 v134, 0.5, v127
	v_fmac_f32_e32 v135, 0.5, v128
	v_fmac_f32_e32 v154, 0.5, v129
	v_fmac_f32_e32 v155, 0.5, v122
	v_fmac_f32_e32 v156, 0.5, v123
	v_fmac_f32_e32 v160, 0.5, v124
	v_fmac_f32_e32 v157, 0.5, v125
	v_cvt_pk_bf16_f32 v122, v130, v134
	v_cvt_pk_bf16_f32 v123, v135, v154
	v_cvt_pk_bf16_f32 v124, v155, v156
	v_cvt_pk_bf16_f32 v125, v160, v157
	s_nop 0
	v_lshlrev_b32_e32 v130, 16, v122
	global_store_dwordx4 v[158:159], v[122:125], off
	v_lshlrev_b32_e32 v134, 16, v123
	v_lshlrev_b32_e32 v135, 16, v124
	v_and_b32_e32 v122, 0xffff0000, v122
	v_and_b32_e32 v123, 0xffff0000, v123
	v_and_b32_e32 v124, 0xffff0000, v124
	v_lshlrev_b32_e32 v154, 16, v125
	v_and_b32_e32 v125, 0xffff0000, v125
	v_mul_f32_e32 v122, v122, v122
	v_mul_f32_e32 v123, v123, v123
	v_mul_f32_e32 v124, v124, v124
	v_mul_f32_e32 v125, v125, v125
	v_fmac_f32_e32 v122, v130, v130
	v_fmac_f32_e32 v123, v134, v134
	v_fmac_f32_e32 v124, v135, v135
	v_fmac_f32_e32 v125, v154, v154
	v_add_f32_e32 v122, v122, v123
	v_add_f32_e32 v123, v124, v125
	v_add_f32_e32 v122, v122, v123
	v_lshlrev_b32_e32 v123, 16, v186
	v_and_b32_e32 v124, 0xffff0000, v186
	v_lshlrev_b32_e32 v125, 16, v187
	v_and_b32_e32 v126, 0xffff0000, v187
	v_lshlrev_b32_e32 v127, 16, v188
	v_and_b32_e32 v128, 0xffff0000, v188
	v_lshlrev_b32_e32 v130, 16, v189
	v_and_b32_e32 v129, 0xffff0000, v189
	v_fmac_f32_e32 v123, 0.5, v118
	v_fmac_f32_e32 v124, 0.5, v119
	v_fmac_f32_e32 v125, 0.5, v120
	v_fmac_f32_e32 v126, 0.5, v121
	v_fmac_f32_e32 v127, 0.5, v114
	v_fmac_f32_e32 v128, 0.5, v115
	v_cvt_pk_bf16_f32 v114, v123, v124
	v_cvt_pk_bf16_f32 v115, v125, v126
	v_fmac_f32_e32 v130, 0.5, v116
	v_and_b32_e32 v119, 0xffff0000, v114
	v_and_b32_e32 v121, 0xffff0000, v115
	v_fmac_f32_e32 v129, 0.5, v117
	v_cvt_pk_bf16_f32 v116, v127, v128
	v_cvt_pk_bf16_f32 v117, v130, v129
	v_lshlrev_b32_e32 v118, 16, v114
	v_lshlrev_b32_e32 v120, 16, v115
	v_and_b32_e32 v124, 0xffff0000, v116
	v_and_b32_e32 v126, 0xffff0000, v117
	v_mul_f32_e32 v119, v119, v119
	v_mul_f32_e32 v121, v121, v121
	v_lshlrev_b32_e32 v123, 16, v116
	v_lshlrev_b32_e32 v125, 16, v117
	v_mul_f32_e32 v124, v124, v124
	v_mul_f32_e32 v126, v126, v126
	v_fmac_f32_e32 v119, v118, v118
	v_fmac_f32_e32 v121, v120, v120
	v_fmac_f32_e32 v124, v123, v123
	v_fmac_f32_e32 v126, v125, v125
	v_add_f32_e32 v118, v119, v121
	v_add_f32_e32 v119, v124, v126
	v_add_f32_e32 v118, v122, v118
	v_add_f32_e32 v118, v118, v119
	ds_swizzle_b32 v119, v118 offset:swizzle(SWAP,16)
	global_store_dwordx4 v[158:159], v[114:117], off offset:256
	s_waitcnt lgkmcnt(0)
	s_nop 0
	v_add_f32_e32 v114, v118, v119
	v_mov_b32_e32 v115, v114
	s_nop 1
	v_permlane32_swap_b32_e32 v114, v115
	s_and_saveexec_b64 s[50:51], vcc
	s_cbranch_execz .LBB0_733
	v_lshlrev_b64 v[116:117], 6, v[148:149]
	v_lshl_add_u64 v[116:117], s[96:97], 0, v[116:117]
	v_lshl_add_u64 v[116:117], s[48:49], 2, v[116:117]
	s_lshl_b32 s58, s70, 2
	v_lshl_add_u64 v[116:117], v[116:117], 0, s[58:59]
	v_add_f32_e32 v114, v114, v115
	global_store_dword v[116:117], v114, off
; __device__ __forceinline__ unsigned cvt_pk_bf16(float lo, float hi) { unsigned r; asm volatile("v_cvt_pk_bf16_f32 %0, %1, %2" : "=v"(r) : "v"(lo), "v"(hi)); return r; }
; __device__ __forceinline__ float bf_lo(unsigned w) { return __uint_as_float(w << 16); }
; __device__ __forceinline__ float bf_hi(unsigned w) { return __uint_as_float(w & 0xffff0000u); }
;     __device__ __forceinline__ void operator()(const f32x4 (&acc)[2][2][4][2], const Unit& u, int wr, int wc, int fr, int fq, const float (&rs)[2][4]) const {
;     ...
;             for (int m = 0; m < 4; ++m) { bf16_t* rowp = X + (size_t)(row0 + ai * HALF + m * 16) * DM + col0; float ss = 0.f;
; #pragma unroll
;                 for (int bj = 0; bj < 2; ++bj) { const u32x4 bw = *(const u32x4*)(rowp + bj * HALF); const f32x4 a0 = acc[ai][bj][m][0], a1 = acc[ai][bj][m][1];
;                     u32x4 w; w.x = cvt_pk_bf16(bf_lo(bw.x) + alpha * a0[0], bf_hi(bw.x) + alpha * a0[1]); w.y = cvt_pk_bf16(bf_lo(bw.y) + alpha * a0[2], bf_hi(bw.y) + alpha * a0[3]);
;                     w.z = cvt_pk_bf16(bf_lo(bw.z) + alpha * a1[0], bf_hi(bw.z) + alpha * a1[1]); w.w = cvt_pk_bf16(bf_lo(bw.w) + alpha * a1[2], bf_hi(bw.w) + alpha * a1[3]);
;                     *(u32x4*)(rowp + bj * HALF) = w;
;                     ss += (bf_lo(w.x) * bf_lo(w.x) + bf_hi(w.x) * bf_hi(w.x)) + (bf_lo(w.y) * bf_lo(w.y) + bf_hi(w.y) * bf_hi(w.y));
;                     ss += (bf_lo(w.z) * bf_lo(w.z) + bf_hi(w.z) * bf_hi(w.z)) + (bf_lo(w.w) * bf_lo(w.w) + bf_hi(w.w) * bf_hi(w.w)); }
;                 ss = fq_sum(ss);
;                 if (fq == 0) part[(size_t)(row0 + ai * HALF + m * 16) * 16 + u.pn * 4 + wc] = ss; } }
.LBB0_733:
	s_or_b64 exec, exec, s[50:51]
	v_add_u32_e32 v114, 16, v148
	v_ashrrev_i32_e32 v115, 31, v114
	v_lshlrev_b64 v[116:117], 11, v[114:115]
	v_lshl_add_u64 v[116:117], s[94:95], 0, v[116:117]
	v_lshl_add_u64 v[120:121], v[146:147], 1, v[116:117]
	s_nop 0
	v_lshlrev_b32_e32 v122, 16, v190
	v_and_b32_e32 v116, 0xffff0000, v190
	v_lshlrev_b32_e32 v123, 16, v191
	v_and_b32_e32 v117, 0xffff0000, v191
	v_lshlrev_b32_e32 v124, 16, v192
	v_and_b32_e32 v118, 0xffff0000, v192
	v_lshlrev_b32_e32 v125, 16, v193
	v_and_b32_e32 v119, 0xffff0000, v193
	v_fmac_f32_e32 v122, 0.5, v110
	v_fmac_f32_e32 v116, 0.5, v111
	v_fmac_f32_e32 v123, 0.5, v112
	v_fmac_f32_e32 v117, 0.5, v113
	v_fmac_f32_e32 v124, 0.5, v106
	v_fmac_f32_e32 v118, 0.5, v107
	v_fmac_f32_e32 v125, 0.5, v108
	v_fmac_f32_e32 v119, 0.5, v109
	v_cvt_pk_bf16_f32 v106, v122, v116
	v_cvt_pk_bf16_f32 v107, v123, v117
	v_cvt_pk_bf16_f32 v108, v124, v118
	v_cvt_pk_bf16_f32 v109, v125, v119
	s_nop 0
	v_lshlrev_b32_e32 v116, 16, v106
	global_store_dwordx4 v[120:121], v[106:109], off
	v_lshlrev_b32_e32 v117, 16, v107
	v_lshlrev_b32_e32 v118, 16, v108
	v_and_b32_e32 v106, 0xffff0000, v106
	v_and_b32_e32 v107, 0xffff0000, v107
	v_and_b32_e32 v108, 0xffff0000, v108
	v_lshlrev_b32_e32 v119, 16, v109
	v_and_b32_e32 v109, 0xffff0000, v109
	v_mul_f32_e32 v106, v106, v106
	v_mul_f32_e32 v107, v107, v107
	v_mul_f32_e32 v108, v108, v108
	v_mul_f32_e32 v109, v109, v109
	v_fmac_f32_e32 v106, v116, v116
	v_fmac_f32_e32 v107, v117, v117
	v_fmac_f32_e32 v108, v118, v118
	v_fmac_f32_e32 v109, v119, v119
	v_add_f32_e32 v106, v106, v107
	v_add_f32_e32 v107, v108, v109
	v_add_f32_e32 v106, v106, v107
	v_lshlrev_b32_e32 v107, 16, v194
	v_and_b32_e32 v108, 0xffff0000, v194
	v_lshlrev_b32_e32 v109, 16, v195
	v_and_b32_e32 v110, 0xffff0000, v195
	v_lshlrev_b32_e32 v111, 16, v196
	v_and_b32_e32 v112, 0xffff0000, v196
	v_lshlrev_b32_e32 v116, 16, v197
	v_and_b32_e32 v113, 0xffff0000, v197
	v_fmac_f32_e32 v107, 0.5, v102
	v_fmac_f32_e32 v108, 0.5, v103
	v_fmac_f32_e32 v109, 0.5, v104
	v_fmac_f32_e32 v110, 0.5, v105
	v_fmac_f32_e32 v111, 0.5, v98
	v_fmac_f32_e32 v112, 0.5, v99
	v_cvt_pk_bf16_f32 v98, v107, v108
	v_cvt_pk_bf16_f32 v99, v109, v110
	v_fmac_f32_e32 v116, 0.5, v100
	v_and_b32_e32 v103, 0xffff0000, v98
	v_and_b32_e32 v105, 0xffff0000, v99
	v_fmac_f32_e32 v113, 0.5, v101
	v_cvt_pk_bf16_f32 v100, v111, v112
	v_cvt_pk_bf16_f32 v101, v116, v113
	v_lshlrev_b32_e32 v102, 16, v98
	v_lshlrev_b32_e32 v104, 16, v99
	v_and_b32_e32 v108, 0xffff0000, v100
	v_and_b32_e32 v110, 0xffff0000, v101
	v_mul_f32_e32 v103, v103, v103
	v_mul_f32_e32 v105, v105, v105
	v_lshlrev_b32_e32 v107, 16, v100
	v_lshlrev_b32_e32 v109, 16, v101
	v_mul_f32_e32 v108, v108, v108
	v_mul_f32_e32 v110, v110, v110
	v_fmac_f32_e32 v103, v102, v102
	v_fmac_f32_e32 v105, v104, v104
	v_fmac_f32_e32 v108, v107, v107
	v_fmac_f32_e32 v110, v109, v109
	v_add_f32_e32 v102, v103, v105
	v_add_f32_e32 v103, v108, v110
	v_add_f32_e32 v102, v106, v102
	v_add_f32_e32 v102, v102, v103
	ds_swizzle_b32 v103, v102 offset:swizzle(SWAP,16)
	global_store_dwordx4 v[120:121], v[98:101], off offset:256
	s_waitcnt lgkmcnt(0)
	s_nop 0
	v_add_f32_e32 v98, v102, v103
	v_mov_b32_e32 v99, v98
	s_nop 1
	v_permlane32_swap_b32_e32 v98, v99
	s_and_saveexec_b64 s[50:51], vcc
	s_cbranch_execz .LBB0_735
	v_lshlrev_b64 v[100:101], 6, v[114:115]
	v_lshl_add_u64 v[100:101], s[96:97], 0, v[100:101]
	v_lshl_add_u64 v[100:101], s[48:49], 2, v[100:101]
	s_lshl_b32 s58, s70, 2
	v_lshl_add_u64 v[100:101], v[100:101], 0, s[58:59]
	v_add_f32_e32 v98, v98, v99
	global_store_dword v[100:101], v98, off
.LBB0_735:
	s_or_b64 exec, exec, s[50:51]
	v_add_u32_e32 v98, 32, v148
	v_ashrrev_i32_e32 v99, 31, v98
	v_lshlrev_b64 v[100:101], 11, v[98:99]
	v_lshl_add_u64 v[100:101], s[94:95], 0, v[100:101]
	v_lshl_add_u64 v[104:105], v[146:147], 1, v[100:101]
	s_nop 0
	v_lshlrev_b32_e32 v106, 16, v198
	v_and_b32_e32 v100, 0xffff0000, v198
	v_lshlrev_b32_e32 v107, 16, v199
	v_and_b32_e32 v101, 0xffff0000, v199
	v_lshlrev_b32_e32 v108, 16, v200
	v_and_b32_e32 v102, 0xffff0000, v200
	v_lshlrev_b32_e32 v109, 16, v201
	v_and_b32_e32 v103, 0xffff0000, v201
	v_fmac_f32_e32 v106, 0.5, v94
	v_fmac_f32_e32 v100, 0.5, v95
	v_fmac_f32_e32 v107, 0.5, v96
	v_fmac_f32_e32 v101, 0.5, v97
	v_fmac_f32_e32 v108, 0.5, v90
	v_fmac_f32_e32 v102, 0.5, v91
	v_fmac_f32_e32 v109, 0.5, v92
	v_fmac_f32_e32 v103, 0.5, v93
	v_cvt_pk_bf16_f32 v90, v106, v100
	v_cvt_pk_bf16_f32 v91, v107, v101
	v_cvt_pk_bf16_f32 v92, v108, v102
	v_cvt_pk_bf16_f32 v93, v109, v103
	s_nop 0
	v_lshlrev_b32_e32 v100, 16, v90
	global_store_dwordx4 v[104:105], v[90:93], off
	v_lshlrev_b32_e32 v101, 16, v91
	v_lshlrev_b32_e32 v102, 16, v92
	v_and_b32_e32 v90, 0xffff0000, v90
	v_and_b32_e32 v91, 0xffff0000, v91
	v_and_b32_e32 v92, 0xffff0000, v92
	v_lshlrev_b32_e32 v103, 16, v93
	v_and_b32_e32 v93, 0xffff0000, v93
	v_mul_f32_e32 v90, v90, v90
	v_mul_f32_e32 v91, v91, v91
	v_mul_f32_e32 v92, v92, v92
	v_mul_f32_e32 v93, v93, v93
	v_fmac_f32_e32 v90, v100, v100
	v_fmac_f32_e32 v91, v101, v101
	v_fmac_f32_e32 v92, v102, v102
	v_fmac_f32_e32 v93, v103, v103
	v_add_f32_e32 v90, v90, v91
	v_add_f32_e32 v91, v92, v93
	v_add_f32_e32 v90, v90, v91
	v_lshlrev_b32_e32 v91, 16, v202
	v_and_b32_e32 v92, 0xffff0000, v202
	v_lshlrev_b32_e32 v93, 16, v203
	v_and_b32_e32 v94, 0xffff0000, v203
	v_lshlrev_b32_e32 v95, 16, v204
	v_and_b32_e32 v96, 0xffff0000, v204
	v_lshlrev_b32_e32 v100, 16, v205
	v_and_b32_e32 v97, 0xffff0000, v205
	v_fmac_f32_e32 v91, 0.5, v86
	v_fmac_f32_e32 v92, 0.5, v87
	v_fmac_f32_e32 v93, 0.5, v88
	v_fmac_f32_e32 v94, 0.5, v89
	v_fmac_f32_e32 v95, 0.5, v82
	v_fmac_f32_e32 v96, 0.5, v83
	v_cvt_pk_bf16_f32 v82, v91, v92
	v_cvt_pk_bf16_f32 v83, v93, v94
	v_fmac_f32_e32 v100, 0.5, v84
	v_and_b32_e32 v87, 0xffff0000, v82
	v_and_b32_e32 v89, 0xffff0000, v83
	v_fmac_f32_e32 v97, 0.5, v85
	v_cvt_pk_bf16_f32 v84, v95, v96
	v_cvt_pk_bf16_f32 v85, v100, v97
	v_lshlrev_b32_e32 v86, 16, v82
	v_lshlrev_b32_e32 v88, 16, v83
	v_and_b32_e32 v92, 0xffff0000, v84
	v_and_b32_e32 v94, 0xffff0000, v85
	v_mul_f32_e32 v87, v87, v87
	v_mul_f32_e32 v89, v89, v89
	v_lshlrev_b32_e32 v91, 16, v84
	v_lshlrev_b32_e32 v93, 16, v85
	v_mul_f32_e32 v92, v92, v92
	v_mul_f32_e32 v94, v94, v94
	v_fmac_f32_e32 v87, v86, v86
	v_fmac_f32_e32 v89, v88, v88
	v_fmac_f32_e32 v92, v91, v91
	v_fmac_f32_e32 v94, v93, v93
	v_add_f32_e32 v86, v87, v89
	v_add_f32_e32 v87, v92, v94
	v_add_f32_e32 v86, v90, v86
	v_add_f32_e32 v86, v86, v87
	ds_swizzle_b32 v87, v86 offset:swizzle(SWAP,16)
	global_store_dwordx4 v[104:105], v[82:85], off offset:256
	s_waitcnt lgkmcnt(0)
	s_nop 0
	v_add_f32_e32 v82, v86, v87
	v_mov_b32_e32 v83, v82
	s_nop 1
	v_permlane32_swap_b32_e32 v82, v83
	s_and_saveexec_b64 s[50:51], vcc
	s_cbranch_execz .LBB0_737
; __device__ __forceinline__ unsigned cvt_pk_bf16(float lo, float hi) { unsigned r; asm volatile("v_cvt_pk_bf16_f32 %0, %1, %2" : "=v"(r) : "v"(lo), "v"(hi)); return r; }
; __device__ __forceinline__ float bf_lo(unsigned w) { return __uint_as_float(w << 16); }
; __device__ __forceinline__ float bf_hi(unsigned w) { return __uint_as_float(w & 0xffff0000u); }
;     __device__ __forceinline__ void operator()(const f32x4 (&acc)[2][2][4][2], const Unit& u, int wr, int wc, int fr, int fq, const float (&rs)[2][4]) const {
;     ...
;             for (int m = 0; m < 4; ++m) { bf16_t* rowp = X + (size_t)(row0 + ai * HALF + m * 16) * DM + col0; float ss = 0.f;
; #pragma unroll
;                 for (int bj = 0; bj < 2; ++bj) { const u32x4 bw = *(const u32x4*)(rowp + bj * HALF); const f32x4 a0 = acc[ai][bj][m][0], a1 = acc[ai][bj][m][1];
;                     u32x4 w; w.x = cvt_pk_bf16(bf_lo(bw.x) + alpha * a0[0], bf_hi(bw.x) + alpha * a0[1]); w.y = cvt_pk_bf16(bf_lo(bw.y) + alpha * a0[2], bf_hi(bw.y) + alpha * a0[3]);
;                     w.z = cvt_pk_bf16(bf_lo(bw.z) + alpha * a1[0], bf_hi(bw.z) + alpha * a1[1]); w.w = cvt_pk_bf16(bf_lo(bw.w) + alpha * a1[2], bf_hi(bw.w) + alpha * a1[3]);
;                     *(u32x4*)(rowp + bj * HALF) = w;
;                     ss += (bf_lo(w.x) * bf_lo(w.x) + bf_hi(w.x) * bf_hi(w.x)) + (bf_lo(w.y) * bf_lo(w.y) + bf_hi(w.y) * bf_hi(w.y));
;                     ss += (bf_lo(w.z) * bf_lo(w.z) + bf_hi(w.z) * bf_hi(w.z)) + (bf_lo(w.w) * bf_lo(w.w) + bf_hi(w.w) * bf_hi(w.w)); }
;                 ss = fq_sum(ss);
;                 if (fq == 0) part[(size_t)(row0 + ai * HALF + m * 16) * 16 + u.pn * 4 + wc] = ss; } }
	v_lshlrev_b64 v[84:85], 6, v[98:99]
	v_lshl_add_u64 v[84:85], s[96:97], 0, v[84:85]
	v_lshl_add_u64 v[84:85], s[48:49], 2, v[84:85]
	s_lshl_b32 s58, s70, 2
	v_lshl_add_u64 v[84:85], v[84:85], 0, s[58:59]
	v_add_f32_e32 v82, v82, v83
	global_store_dword v[84:85], v82, off
.LBB0_737:
	s_or_b64 exec, exec, s[50:51]
	v_add_u32_e32 v82, 48, v148
	v_ashrrev_i32_e32 v83, 31, v82
	v_lshlrev_b64 v[84:85], 11, v[82:83]
	v_lshl_add_u64 v[84:85], s[94:95], 0, v[84:85]
	v_lshl_add_u64 v[84:85], v[146:147], 1, v[84:85]
	s_nop 0
	v_lshlrev_b32_e32 v90, 16, v206
	v_and_b32_e32 v86, 0xffff0000, v206
	v_lshlrev_b32_e32 v91, 16, v207
	v_and_b32_e32 v87, 0xffff0000, v207
	v_lshlrev_b32_e32 v92, 16, v208
	v_and_b32_e32 v88, 0xffff0000, v208
	v_lshlrev_b32_e32 v93, 16, v209
	v_and_b32_e32 v89, 0xffff0000, v209
	v_fmac_f32_e32 v90, 0.5, v76
	v_fmac_f32_e32 v86, 0.5, v77
	v_fmac_f32_e32 v91, 0.5, v78
	v_fmac_f32_e32 v87, 0.5, v79
	v_fmac_f32_e32 v92, 0.5, v72
	v_fmac_f32_e32 v88, 0.5, v73
	v_fmac_f32_e32 v93, 0.5, v74
	v_fmac_f32_e32 v89, 0.5, v75
	v_cvt_pk_bf16_f32 v72, v90, v86
	v_cvt_pk_bf16_f32 v73, v91, v87
	v_cvt_pk_bf16_f32 v74, v92, v88
	v_cvt_pk_bf16_f32 v75, v93, v89
	s_nop 0
	v_lshlrev_b32_e32 v86, 16, v72
	global_store_dwordx4 v[84:85], v[72:75], off
	v_lshlrev_b32_e32 v87, 16, v73
	v_lshlrev_b32_e32 v88, 16, v74
	v_and_b32_e32 v72, 0xffff0000, v72
	v_and_b32_e32 v73, 0xffff0000, v73
	v_and_b32_e32 v74, 0xffff0000, v74
	v_lshlrev_b32_e32 v89, 16, v75
	v_and_b32_e32 v75, 0xffff0000, v75
	v_mul_f32_e32 v72, v72, v72
	v_mul_f32_e32 v73, v73, v73
	v_mul_f32_e32 v74, v74, v74
	v_mul_f32_e32 v75, v75, v75
	v_fmac_f32_e32 v72, v86, v86
	v_fmac_f32_e32 v73, v87, v87
	v_fmac_f32_e32 v74, v88, v88
	v_fmac_f32_e32 v75, v89, v89
	v_add_f32_e32 v72, v72, v73
	v_add_f32_e32 v73, v74, v75
	v_add_f32_e32 v72, v72, v73
	v_lshlrev_b32_e32 v73, 16, v210
	v_and_b32_e32 v74, 0xffff0000, v210
	v_lshlrev_b32_e32 v75, 16, v211
	v_and_b32_e32 v76, 0xffff0000, v211
	v_lshlrev_b32_e32 v77, 16, v212
	v_and_b32_e32 v78, 0xffff0000, v212
	v_lshlrev_b32_e32 v86, 16, v213
	v_and_b32_e32 v79, 0xffff0000, v213
	v_fmac_f32_e32 v73, 0.5, v68
	v_fmac_f32_e32 v74, 0.5, v69
	v_fmac_f32_e32 v75, 0.5, v70
	v_fmac_f32_e32 v76, 0.5, v71
	v_fmac_f32_e32 v77, 0.5, v64
	v_fmac_f32_e32 v78, 0.5, v65
	v_cvt_pk_bf16_f32 v64, v73, v74
	v_cvt_pk_bf16_f32 v65, v75, v76
	v_fmac_f32_e32 v86, 0.5, v66
	v_and_b32_e32 v69, 0xffff0000, v64
	v_and_b32_e32 v71, 0xffff0000, v65
	v_fmac_f32_e32 v79, 0.5, v67
	v_cvt_pk_bf16_f32 v66, v77, v78
	v_cvt_pk_bf16_f32 v67, v86, v79
	v_lshlrev_b32_e32 v68, 16, v64
	v_lshlrev_b32_e32 v70, 16, v65
	v_and_b32_e32 v74, 0xffff0000, v66
	v_and_b32_e32 v76, 0xffff0000, v67
	v_mul_f32_e32 v69, v69, v69
	v_mul_f32_e32 v71, v71, v71
	v_lshlrev_b32_e32 v73, 16, v66
	v_lshlrev_b32_e32 v75, 16, v67
	v_mul_f32_e32 v74, v74, v74
	v_mul_f32_e32 v76, v76, v76
	v_fmac_f32_e32 v69, v68, v68
	v_fmac_f32_e32 v71, v70, v70
	v_fmac_f32_e32 v74, v73, v73
	v_fmac_f32_e32 v76, v75, v75
	v_add_f32_e32 v68, v69, v71
	v_add_f32_e32 v69, v74, v76
	v_add_f32_e32 v68, v72, v68
	v_add_f32_e32 v68, v68, v69
	ds_swizzle_b32 v69, v68 offset:swizzle(SWAP,16)
	global_store_dwordx4 v[84:85], v[64:67], off offset:256
	s_waitcnt lgkmcnt(0)
	s_nop 0
	v_add_f32_e32 v64, v68, v69
	v_mov_b32_e32 v65, v64
	s_nop 1
	v_permlane32_swap_b32_e32 v64, v65
	s_and_saveexec_b64 s[50:51], vcc
	s_cbranch_execz .LBB0_739
	v_lshlrev_b64 v[66:67], 6, v[82:83]
	v_lshl_add_u64 v[66:67], s[96:97], 0, v[66:67]
	v_lshl_add_u64 v[66:67], s[48:49], 2, v[66:67]
	s_lshl_b32 s58, s70, 2
	v_lshl_add_u64 v[66:67], v[66:67], 0, s[58:59]
	v_add_f32_e32 v64, v64, v65
	global_store_dword v[66:67], v64, off
.LBB0_739:
	s_or_b64 exec, exec, s[50:51]
	v_add_u32_e32 v64, 0x80, v148
	v_ashrrev_i32_e32 v65, 31, v64
	v_lshlrev_b64 v[66:67], 11, v[64:65]
	v_lshl_add_u64 v[66:67], s[94:95], 0, v[66:67]
	v_lshl_add_u64 v[70:71], v[146:147], 1, v[66:67]
	s_nop 0
	v_lshlrev_b32_e32 v72, 16, v214
	v_and_b32_e32 v66, 0xffff0000, v214
	v_lshlrev_b32_e32 v73, 16, v215
	v_and_b32_e32 v67, 0xffff0000, v215
	v_lshlrev_b32_e32 v74, 16, v216
	v_and_b32_e32 v68, 0xffff0000, v216
	v_lshlrev_b32_e32 v75, 16, v217
	v_and_b32_e32 v69, 0xffff0000, v217
	v_fmac_f32_e32 v72, 0.5, v60
	v_fmac_f32_e32 v66, 0.5, v61
	v_fmac_f32_e32 v73, 0.5, v62
	v_fmac_f32_e32 v67, 0.5, v63
	v_fmac_f32_e32 v74, 0.5, v56
	v_fmac_f32_e32 v68, 0.5, v57
	v_fmac_f32_e32 v75, 0.5, v58
	v_fmac_f32_e32 v69, 0.5, v59
	v_cvt_pk_bf16_f32 v56, v72, v66
	v_cvt_pk_bf16_f32 v57, v73, v67
	v_cvt_pk_bf16_f32 v58, v74, v68
	v_cvt_pk_bf16_f32 v59, v75, v69
	s_nop 0
	v_lshlrev_b32_e32 v66, 16, v56
	global_store_dwordx4 v[70:71], v[56:59], off
	v_lshlrev_b32_e32 v67, 16, v57
	v_lshlrev_b32_e32 v68, 16, v58
	v_and_b32_e32 v56, 0xffff0000, v56
	v_and_b32_e32 v57, 0xffff0000, v57
	v_and_b32_e32 v58, 0xffff0000, v58
	v_lshlrev_b32_e32 v69, 16, v59
	v_and_b32_e32 v59, 0xffff0000, v59
	v_mul_f32_e32 v56, v56, v56
	v_mul_f32_e32 v57, v57, v57
	v_mul_f32_e32 v58, v58, v58
	v_mul_f32_e32 v59, v59, v59
	v_fmac_f32_e32 v56, v66, v66
	v_fmac_f32_e32 v57, v67, v67
	v_fmac_f32_e32 v58, v68, v68
	v_fmac_f32_e32 v59, v69, v69
	v_add_f32_e32 v56, v56, v57
	v_add_f32_e32 v57, v58, v59
	v_add_f32_e32 v56, v56, v57
	v_lshlrev_b32_e32 v57, 16, v218
	v_and_b32_e32 v58, 0xffff0000, v218
	v_lshlrev_b32_e32 v59, 16, v219
	v_and_b32_e32 v60, 0xffff0000, v219
	v_lshlrev_b32_e32 v61, 16, v220
	v_and_b32_e32 v62, 0xffff0000, v220
	v_lshlrev_b32_e32 v66, 16, v221
	v_and_b32_e32 v63, 0xffff0000, v221
	v_fmac_f32_e32 v57, 0.5, v52
	v_fmac_f32_e32 v58, 0.5, v53
	v_fmac_f32_e32 v59, 0.5, v54
	v_fmac_f32_e32 v60, 0.5, v55
	v_fmac_f32_e32 v61, 0.5, v48
	v_fmac_f32_e32 v62, 0.5, v49
	v_cvt_pk_bf16_f32 v48, v57, v58
	v_cvt_pk_bf16_f32 v49, v59, v60
	v_fmac_f32_e32 v66, 0.5, v50
	v_and_b32_e32 v53, 0xffff0000, v48
	v_and_b32_e32 v55, 0xffff0000, v49
	v_fmac_f32_e32 v63, 0.5, v51
	v_cvt_pk_bf16_f32 v50, v61, v62
	v_cvt_pk_bf16_f32 v51, v66, v63
	v_lshlrev_b32_e32 v52, 16, v48
	v_lshlrev_b32_e32 v54, 16, v49
	v_and_b32_e32 v58, 0xffff0000, v50
	v_and_b32_e32 v60, 0xffff0000, v51
	v_mul_f32_e32 v53, v53, v53
	v_mul_f32_e32 v55, v55, v55
	v_lshlrev_b32_e32 v57, 16, v50
	v_lshlrev_b32_e32 v59, 16, v51
	v_mul_f32_e32 v58, v58, v58
	v_mul_f32_e32 v60, v60, v60
	v_fmac_f32_e32 v53, v52, v52
	v_fmac_f32_e32 v55, v54, v54
	v_fmac_f32_e32 v58, v57, v57
	v_fmac_f32_e32 v60, v59, v59
	v_add_f32_e32 v52, v53, v55
	v_add_f32_e32 v53, v58, v60
	v_add_f32_e32 v52, v56, v52
	v_add_f32_e32 v52, v52, v53
	ds_swizzle_b32 v53, v52 offset:swizzle(SWAP,16)
	global_store_dwordx4 v[70:71], v[48:51], off offset:256
	s_waitcnt lgkmcnt(0)
	s_nop 0
	v_add_f32_e32 v48, v52, v53
	v_mov_b32_e32 v49, v48
	s_nop 1
	v_permlane32_swap_b32_e32 v48, v49
	s_and_saveexec_b64 s[50:51], vcc
	s_cbranch_execz .LBB0_741
; __device__ __forceinline__ unsigned cvt_pk_bf16(float lo, float hi) { unsigned r; asm volatile("v_cvt_pk_bf16_f32 %0, %1, %2" : "=v"(r) : "v"(lo), "v"(hi)); return r; }
; __device__ __forceinline__ float bf_lo(unsigned w) { return __uint_as_float(w << 16); }
; __device__ __forceinline__ float bf_hi(unsigned w) { return __uint_as_float(w & 0xffff0000u); }
;     __device__ __forceinline__ void operator()(const f32x4 (&acc)[2][2][4][2], const Unit& u, int wr, int wc, int fr, int fq, const float (&rs)[2][4]) const {
;     ...
;             for (int m = 0; m < 4; ++m) { bf16_t* rowp = X + (size_t)(row0 + ai * HALF + m * 16) * DM + col0; float ss = 0.f;
; #pragma unroll
;                 for (int bj = 0; bj < 2; ++bj) { const u32x4 bw = *(const u32x4*)(rowp + bj * HALF); const f32x4 a0 = acc[ai][bj][m][0], a1 = acc[ai][bj][m][1];
;                     u32x4 w; w.x = cvt_pk_bf16(bf_lo(bw.x) + alpha * a0[0], bf_hi(bw.x) + alpha * a0[1]); w.y = cvt_pk_bf16(bf_lo(bw.y) + alpha * a0[2], bf_hi(bw.y) + alpha * a0[3]);
;                     w.z = cvt_pk_bf16(bf_lo(bw.z) + alpha * a1[0], bf_hi(bw.z) + alpha * a1[1]); w.w = cvt_pk_bf16(bf_lo(bw.w) + alpha * a1[2], bf_hi(bw.w) + alpha * a1[3]);
;                     *(u32x4*)(rowp + bj * HALF) = w;
;                     ss += (bf_lo(w.x) * bf_lo(w.x) + bf_hi(w.x) * bf_hi(w.x)) + (bf_lo(w.y) * bf_lo(w.y) + bf_hi(w.y) * bf_hi(w.y));
;                     ss += (bf_lo(w.z) * bf_lo(w.z) + bf_hi(w.z) * bf_hi(w.z)) + (bf_lo(w.w) * bf_lo(w.w) + bf_hi(w.w) * bf_hi(w.w)); }
;                 ss = fq_sum(ss);
;                 if (fq == 0) part[(size_t)(row0 + ai * HALF + m * 16) * 16 + u.pn * 4 + wc] = ss; } }
	v_lshlrev_b64 v[50:51], 6, v[64:65]
	v_lshl_add_u64 v[50:51], s[96:97], 0, v[50:51]
	v_lshl_add_u64 v[50:51], s[48:49], 2, v[50:51]
	s_lshl_b32 s58, s70, 2
	v_lshl_add_u64 v[50:51], v[50:51], 0, s[58:59]
	v_add_f32_e32 v48, v48, v49
	global_store_dword v[50:51], v48, off
.LBB0_741:
	s_or_b64 exec, exec, s[50:51]
	v_add_u32_e32 v48, 0x90, v148
	v_ashrrev_i32_e32 v49, 31, v48
	v_lshlrev_b64 v[50:51], 11, v[48:49]
	v_lshl_add_u64 v[50:51], s[94:95], 0, v[50:51]
	v_lshl_add_u64 v[54:55], v[146:147], 1, v[50:51]
	s_nop 0
	v_lshlrev_b32_e32 v56, 16, v222
	v_and_b32_e32 v50, 0xffff0000, v222
	v_lshlrev_b32_e32 v57, 16, v223
	v_and_b32_e32 v51, 0xffff0000, v223
	v_lshlrev_b32_e32 v58, 16, v224
	v_and_b32_e32 v52, 0xffff0000, v224
	v_lshlrev_b32_e32 v59, 16, v225
	v_and_b32_e32 v53, 0xffff0000, v225
	v_fmac_f32_e32 v56, 0.5, v44
	v_fmac_f32_e32 v50, 0.5, v45
	v_fmac_f32_e32 v57, 0.5, v46
	v_fmac_f32_e32 v51, 0.5, v47
	v_fmac_f32_e32 v58, 0.5, v40
	v_fmac_f32_e32 v52, 0.5, v41
	v_fmac_f32_e32 v59, 0.5, v42
	v_fmac_f32_e32 v53, 0.5, v43
	v_cvt_pk_bf16_f32 v40, v56, v50
	v_cvt_pk_bf16_f32 v41, v57, v51
	v_cvt_pk_bf16_f32 v42, v58, v52
	v_cvt_pk_bf16_f32 v43, v59, v53
	s_nop 0
	v_lshlrev_b32_e32 v50, 16, v40
	global_store_dwordx4 v[54:55], v[40:43], off
	v_lshlrev_b32_e32 v51, 16, v41
	v_lshlrev_b32_e32 v52, 16, v42
	v_and_b32_e32 v40, 0xffff0000, v40
	v_and_b32_e32 v41, 0xffff0000, v41
	v_and_b32_e32 v42, 0xffff0000, v42
	v_lshlrev_b32_e32 v53, 16, v43
	v_and_b32_e32 v43, 0xffff0000, v43
	v_mul_f32_e32 v40, v40, v40
	v_mul_f32_e32 v41, v41, v41
	v_mul_f32_e32 v42, v42, v42
	v_mul_f32_e32 v43, v43, v43
	v_fmac_f32_e32 v40, v50, v50
	v_fmac_f32_e32 v41, v51, v51
	v_fmac_f32_e32 v42, v52, v52
	v_fmac_f32_e32 v43, v53, v53
	v_add_f32_e32 v40, v40, v41
	v_add_f32_e32 v41, v42, v43
	v_add_f32_e32 v40, v40, v41
	v_lshlrev_b32_e32 v41, 16, v226
	v_and_b32_e32 v42, 0xffff0000, v226
	v_lshlrev_b32_e32 v43, 16, v227
	v_and_b32_e32 v44, 0xffff0000, v227
	v_lshlrev_b32_e32 v45, 16, v228
	v_and_b32_e32 v46, 0xffff0000, v228
	v_lshlrev_b32_e32 v50, 16, v229
	v_and_b32_e32 v47, 0xffff0000, v229
	v_fmac_f32_e32 v41, 0.5, v36
	v_fmac_f32_e32 v42, 0.5, v37
	v_fmac_f32_e32 v43, 0.5, v38
	v_fmac_f32_e32 v44, 0.5, v39
	v_fmac_f32_e32 v45, 0.5, v32
	v_fmac_f32_e32 v46, 0.5, v33
	v_cvt_pk_bf16_f32 v32, v41, v42
	v_cvt_pk_bf16_f32 v33, v43, v44
	v_fmac_f32_e32 v50, 0.5, v34
	v_and_b32_e32 v37, 0xffff0000, v32
	v_and_b32_e32 v39, 0xffff0000, v33
	v_fmac_f32_e32 v47, 0.5, v35
	v_cvt_pk_bf16_f32 v34, v45, v46
	v_cvt_pk_bf16_f32 v35, v50, v47
	v_lshlrev_b32_e32 v36, 16, v32
	v_lshlrev_b32_e32 v38, 16, v33
	v_and_b32_e32 v42, 0xffff0000, v34
	v_and_b32_e32 v44, 0xffff0000, v35
	v_mul_f32_e32 v37, v37, v37
	v_mul_f32_e32 v39, v39, v39
	v_lshlrev_b32_e32 v41, 16, v34
	v_lshlrev_b32_e32 v43, 16, v35
	v_mul_f32_e32 v42, v42, v42
	v_mul_f32_e32 v44, v44, v44
	v_fmac_f32_e32 v37, v36, v36
	v_fmac_f32_e32 v39, v38, v38
	v_fmac_f32_e32 v42, v41, v41
	v_fmac_f32_e32 v44, v43, v43
	v_add_f32_e32 v36, v37, v39
	v_add_f32_e32 v37, v42, v44
	v_add_f32_e32 v36, v40, v36
	v_add_f32_e32 v36, v36, v37
	ds_swizzle_b32 v37, v36 offset:swizzle(SWAP,16)
	global_store_dwordx4 v[54:55], v[32:35], off offset:256
	s_waitcnt lgkmcnt(0)
	s_nop 0
	v_add_f32_e32 v32, v36, v37
	v_mov_b32_e32 v33, v32
	s_nop 1
	v_permlane32_swap_b32_e32 v32, v33
	s_and_saveexec_b64 s[50:51], vcc
	s_cbranch_execz .LBB0_743
	v_lshlrev_b64 v[34:35], 6, v[48:49]
	v_lshl_add_u64 v[34:35], s[96:97], 0, v[34:35]
	v_lshl_add_u64 v[34:35], s[48:49], 2, v[34:35]
	s_lshl_b32 s58, s70, 2
	v_lshl_add_u64 v[34:35], v[34:35], 0, s[58:59]
	v_add_f32_e32 v32, v32, v33
	global_store_dword v[34:35], v32, off
; __device__ __forceinline__ unsigned cvt_pk_bf16(float lo, float hi) { unsigned r; asm volatile("v_cvt_pk_bf16_f32 %0, %1, %2" : "=v"(r) : "v"(lo), "v"(hi)); return r; }
; __device__ __forceinline__ float bf_lo(unsigned w) { return __uint_as_float(w << 16); }
; __device__ __forceinline__ float bf_hi(unsigned w) { return __uint_as_float(w & 0xffff0000u); }
;     __device__ __forceinline__ void operator()(const f32x4 (&acc)[2][2][4][2], const Unit& u, int wr, int wc, int fr, int fq, const float (&rs)[2][4]) const {
;     ...
;             for (int m = 0; m < 4; ++m) { bf16_t* rowp = X + (size_t)(row0 + ai * HALF + m * 16) * DM + col0; float ss = 0.f;
; #pragma unroll
;                 for (int bj = 0; bj < 2; ++bj) { const u32x4 bw = *(const u32x4*)(rowp + bj * HALF); const f32x4 a0 = acc[ai][bj][m][0], a1 = acc[ai][bj][m][1];
;                     u32x4 w; w.x = cvt_pk_bf16(bf_lo(bw.x) + alpha * a0[0], bf_hi(bw.x) + alpha * a0[1]); w.y = cvt_pk_bf16(bf_lo(bw.y) + alpha * a0[2], bf_hi(bw.y) + alpha * a0[3]);
;                     w.z = cvt_pk_bf16(bf_lo(bw.z) + alpha * a1[0], bf_hi(bw.z) + alpha * a1[1]); w.w = cvt_pk_bf16(bf_lo(bw.w) + alpha * a1[2], bf_hi(bw.w) + alpha * a1[3]);
;                     *(u32x4*)(rowp + bj * HALF) = w;
;                     ss += (bf_lo(w.x) * bf_lo(w.x) + bf_hi(w.x) * bf_hi(w.x)) + (bf_lo(w.y) * bf_lo(w.y) + bf_hi(w.y) * bf_hi(w.y));
;                     ss += (bf_lo(w.z) * bf_lo(w.z) + bf_hi(w.z) * bf_hi(w.z)) + (bf_lo(w.w) * bf_lo(w.w) + bf_hi(w.w) * bf_hi(w.w)); }
;                 ss = fq_sum(ss);
;                 if (fq == 0) part[(size_t)(row0 + ai * HALF + m * 16) * 16 + u.pn * 4 + wc] = ss; } }
.LBB0_743:
	s_or_b64 exec, exec, s[50:51]
	v_add_u32_e32 v32, 0xa0, v148
	v_ashrrev_i32_e32 v33, 31, v32
	v_lshlrev_b64 v[34:35], 11, v[32:33]
	v_lshl_add_u64 v[34:35], s[94:95], 0, v[34:35]
	v_lshl_add_u64 v[38:39], v[146:147], 1, v[34:35]
	s_nop 0
	v_lshlrev_b32_e32 v40, 16, v230
	v_and_b32_e32 v34, 0xffff0000, v230
	v_lshlrev_b32_e32 v41, 16, v231
	v_and_b32_e32 v35, 0xffff0000, v231
	v_lshlrev_b32_e32 v42, 16, v232
	v_and_b32_e32 v36, 0xffff0000, v232
	v_lshlrev_b32_e32 v43, 16, v233
	v_and_b32_e32 v37, 0xffff0000, v233
	v_fmac_f32_e32 v40, 0.5, v28
	v_fmac_f32_e32 v34, 0.5, v29
	v_fmac_f32_e32 v41, 0.5, v30
	v_fmac_f32_e32 v35, 0.5, v31
	v_fmac_f32_e32 v42, 0.5, v24
	v_fmac_f32_e32 v36, 0.5, v25
	v_fmac_f32_e32 v43, 0.5, v26
	v_fmac_f32_e32 v37, 0.5, v27
	v_cvt_pk_bf16_f32 v24, v40, v34
	v_cvt_pk_bf16_f32 v25, v41, v35
	v_cvt_pk_bf16_f32 v26, v42, v36
	v_cvt_pk_bf16_f32 v27, v43, v37
	s_nop 0
	v_lshlrev_b32_e32 v34, 16, v24
	global_store_dwordx4 v[38:39], v[24:27], off
	v_lshlrev_b32_e32 v35, 16, v25
	v_lshlrev_b32_e32 v36, 16, v26
	v_and_b32_e32 v24, 0xffff0000, v24
	v_and_b32_e32 v25, 0xffff0000, v25
	v_and_b32_e32 v26, 0xffff0000, v26
	v_lshlrev_b32_e32 v37, 16, v27
	v_and_b32_e32 v27, 0xffff0000, v27
	v_mul_f32_e32 v24, v24, v24
	v_mul_f32_e32 v25, v25, v25
	v_mul_f32_e32 v26, v26, v26
	v_mul_f32_e32 v27, v27, v27
	v_fmac_f32_e32 v24, v34, v34
	v_fmac_f32_e32 v25, v35, v35
	v_fmac_f32_e32 v26, v36, v36
	v_fmac_f32_e32 v27, v37, v37
	v_add_f32_e32 v24, v24, v25
	v_add_f32_e32 v25, v26, v27
	v_add_f32_e32 v24, v24, v25
	v_lshlrev_b32_e32 v25, 16, v234
	v_and_b32_e32 v26, 0xffff0000, v234
	v_lshlrev_b32_e32 v27, 16, v235
	v_and_b32_e32 v28, 0xffff0000, v235
	v_lshlrev_b32_e32 v29, 16, v236
	v_and_b32_e32 v30, 0xffff0000, v236
	v_lshlrev_b32_e32 v34, 16, v237
	v_and_b32_e32 v31, 0xffff0000, v237
	v_fmac_f32_e32 v25, 0.5, v20
	v_fmac_f32_e32 v26, 0.5, v21
	v_fmac_f32_e32 v27, 0.5, v22
	v_fmac_f32_e32 v28, 0.5, v23
	v_fmac_f32_e32 v29, 0.5, v16
	v_fmac_f32_e32 v30, 0.5, v17
	v_cvt_pk_bf16_f32 v16, v25, v26
	v_cvt_pk_bf16_f32 v17, v27, v28
	v_fmac_f32_e32 v34, 0.5, v18
	v_and_b32_e32 v21, 0xffff0000, v16
	v_and_b32_e32 v23, 0xffff0000, v17
	v_fmac_f32_e32 v31, 0.5, v19
	v_cvt_pk_bf16_f32 v18, v29, v30
	v_cvt_pk_bf16_f32 v19, v34, v31
	v_lshlrev_b32_e32 v20, 16, v16
	v_lshlrev_b32_e32 v22, 16, v17
	v_and_b32_e32 v26, 0xffff0000, v18
	v_and_b32_e32 v28, 0xffff0000, v19
	v_mul_f32_e32 v21, v21, v21
	v_mul_f32_e32 v23, v23, v23
	v_lshlrev_b32_e32 v25, 16, v18
	v_lshlrev_b32_e32 v27, 16, v19
	v_mul_f32_e32 v26, v26, v26
	v_mul_f32_e32 v28, v28, v28
	v_fmac_f32_e32 v21, v20, v20
	v_fmac_f32_e32 v23, v22, v22
	v_fmac_f32_e32 v26, v25, v25
	v_fmac_f32_e32 v28, v27, v27
	v_add_f32_e32 v20, v21, v23
	v_add_f32_e32 v21, v26, v28
	v_add_f32_e32 v20, v24, v20
	v_add_f32_e32 v20, v20, v21
	ds_swizzle_b32 v21, v20 offset:swizzle(SWAP,16)
	global_store_dwordx4 v[38:39], v[16:19], off offset:256
	s_waitcnt lgkmcnt(0)
	s_nop 0
	v_add_f32_e32 v16, v20, v21
	v_mov_b32_e32 v17, v16
	s_nop 1
	v_permlane32_swap_b32_e32 v16, v17
	s_and_saveexec_b64 s[50:51], vcc
	s_cbranch_execz .LBB0_745
	v_lshlrev_b64 v[18:19], 6, v[32:33]
	v_lshl_add_u64 v[18:19], s[96:97], 0, v[18:19]
	v_lshl_add_u64 v[18:19], s[48:49], 2, v[18:19]
	s_lshl_b32 s58, s70, 2
	v_lshl_add_u64 v[18:19], v[18:19], 0, s[58:59]
	v_add_f32_e32 v16, v16, v17
	global_store_dword v[18:19], v16, off
.LBB0_745:
	s_or_b64 exec, exec, s[50:51]
	v_add_u32_e32 v16, 0xb0, v148
	v_ashrrev_i32_e32 v17, 31, v16
	v_lshlrev_b64 v[18:19], 11, v[16:17]
	v_lshl_add_u64 v[18:19], s[94:95], 0, v[18:19]
	v_lshl_add_u64 v[22:23], v[146:147], 1, v[18:19]
	s_nop 0
	v_lshlrev_b32_e32 v24, 16, v238
	v_and_b32_e32 v18, 0xffff0000, v238
	v_lshlrev_b32_e32 v25, 16, v239
	v_and_b32_e32 v19, 0xffff0000, v239
	v_lshlrev_b32_e32 v26, 16, v240
	v_and_b32_e32 v20, 0xffff0000, v240
	v_lshlrev_b32_e32 v27, 16, v241
	v_and_b32_e32 v21, 0xffff0000, v241
	v_fmac_f32_e32 v24, 0.5, v12
	v_fmac_f32_e32 v18, 0.5, v13
	v_fmac_f32_e32 v25, 0.5, v14
	v_fmac_f32_e32 v19, 0.5, v15
	v_fmac_f32_e32 v26, 0.5, v8
	v_fmac_f32_e32 v20, 0.5, v9
	v_fmac_f32_e32 v27, 0.5, v10
	v_fmac_f32_e32 v21, 0.5, v11
	v_cvt_pk_bf16_f32 v8, v24, v18
	v_cvt_pk_bf16_f32 v9, v25, v19
	v_cvt_pk_bf16_f32 v10, v26, v20
	v_cvt_pk_bf16_f32 v11, v27, v21
	s_nop 0
	v_lshlrev_b32_e32 v18, 16, v8
	global_store_dwordx4 v[22:23], v[8:11], off
	v_lshlrev_b32_e32 v19, 16, v9
	v_lshlrev_b32_e32 v20, 16, v10
	v_and_b32_e32 v8, 0xffff0000, v8
	v_and_b32_e32 v9, 0xffff0000, v9
	v_and_b32_e32 v10, 0xffff0000, v10
	v_lshlrev_b32_e32 v21, 16, v11
	v_and_b32_e32 v11, 0xffff0000, v11
	v_mul_f32_e32 v8, v8, v8
	v_mul_f32_e32 v9, v9, v9
	v_mul_f32_e32 v10, v10, v10
	v_mul_f32_e32 v11, v11, v11
	v_fmac_f32_e32 v8, v18, v18
	v_fmac_f32_e32 v9, v19, v19
	v_fmac_f32_e32 v10, v20, v20
	v_fmac_f32_e32 v11, v21, v21
	v_add_f32_e32 v8, v8, v9
	v_add_f32_e32 v9, v10, v11
	v_add_f32_e32 v8, v8, v9
	v_lshlrev_b32_e32 v9, 16, v242
	v_and_b32_e32 v10, 0xffff0000, v242
	v_lshlrev_b32_e32 v11, 16, v243
	v_and_b32_e32 v12, 0xffff0000, v243
	v_lshlrev_b32_e32 v13, 16, v244
	v_and_b32_e32 v14, 0xffff0000, v244
	v_lshlrev_b32_e32 v18, 16, v245
	v_and_b32_e32 v15, 0xffff0000, v245
	v_fmac_f32_e32 v9, 0.5, v4
	v_fmac_f32_e32 v10, 0.5, v5
	v_fmac_f32_e32 v11, 0.5, v6
	v_fmac_f32_e32 v12, 0.5, v7
	v_fmac_f32_e32 v13, 0.5, v0
	v_fmac_f32_e32 v14, 0.5, v1
	v_cvt_pk_bf16_f32 v0, v9, v10
	v_cvt_pk_bf16_f32 v1, v11, v12
	v_fmac_f32_e32 v18, 0.5, v2
	v_and_b32_e32 v5, 0xffff0000, v0
	v_and_b32_e32 v7, 0xffff0000, v1
	v_fmac_f32_e32 v15, 0.5, v3
	v_cvt_pk_bf16_f32 v2, v13, v14
	v_cvt_pk_bf16_f32 v3, v18, v15
	v_lshlrev_b32_e32 v4, 16, v0
	v_lshlrev_b32_e32 v6, 16, v1
	v_and_b32_e32 v10, 0xffff0000, v2
	v_and_b32_e32 v12, 0xffff0000, v3
	v_mul_f32_e32 v5, v5, v5
	v_mul_f32_e32 v7, v7, v7
	v_lshlrev_b32_e32 v9, 16, v2
	v_lshlrev_b32_e32 v11, 16, v3
	v_mul_f32_e32 v10, v10, v10
	v_mul_f32_e32 v12, v12, v12
	v_fmac_f32_e32 v5, v4, v4
	v_fmac_f32_e32 v7, v6, v6
	v_fmac_f32_e32 v10, v9, v9
	v_fmac_f32_e32 v12, v11, v11
	v_add_f32_e32 v4, v5, v7
	v_add_f32_e32 v5, v10, v12
	v_add_f32_e32 v4, v8, v4
	v_add_f32_e32 v4, v4, v5
	ds_swizzle_b32 v5, v4 offset:swizzle(SWAP,16)
	global_store_dwordx4 v[22:23], v[0:3], off offset:256
	s_waitcnt lgkmcnt(0)
	s_nop 0
	v_add_f32_e32 v0, v4, v5
	v_mov_b32_e32 v1, v0
	s_nop 1
	v_permlane32_swap_b32_e32 v0, v1
	s_and_saveexec_b64 s[50:51], vcc
	s_cbranch_execz .LBB0_747
	v_lshlrev_b64 v[2:3], 6, v[16:17]
	v_lshl_add_u64 v[2:3], s[96:97], 0, v[2:3]
	v_lshl_add_u64 v[2:3], s[48:49], 2, v[2:3]
	s_lshl_b32 s58, s70, 2
	v_lshl_add_u64 v[2:3], v[2:3], 0, s[58:59]
	v_add_f32_e32 v0, v0, v1
	global_store_dword v[2:3], v0, off

; __device__ __forceinline__ unsigned cvt_pk_bf16(float lo, float hi) { unsigned r; asm volatile("v_cvt_pk_bf16_f32 %0, %1, %2" : "=v"(r) : "v"(lo), "v"(hi)); return r; }
; __device__ __forceinline__ float bf_lo(unsigned w) { return __uint_as_float(w << 16); }
; __device__ __forceinline__ float bf_hi(unsigned w) { return __uint_as_float(w & 0xffff0000u); }
;     __device__ __forceinline__ void operator()(const f32x4 (&acc)[2][2][4][2], const Unit& u, int wr, int wc, int fr, int fq, const float (&rs)[2][4]) const {
;         asm volatile("" : "+v"(fr), "+v"(fq));
;         const int row0 = u.pm * BM + wr * 64 + fr, col0 = u.pn * BM + wc * 32 + 8 * fq;
; #pragma unroll
;         for (int ai = 0; ai < 2; ++ai) {
; #pragma unroll
;             for (int m = 0; m < 4; ++m) { bf16_t* rowp = X + (size_t)(row0 + ai * HALF + m * 16) * DM + col0; float ss = 0.f;
; #pragma unroll
;                 for (int bj = 0; bj < 2; ++bj) { const u32x4 bw = *(const u32x4*)(rowp + bj * HALF); const f32x4 a0 = acc[ai][bj][m][0], a1 = acc[ai][bj][m][1];
;                     u32x4 w; w.x = cvt_pk_bf16(bf_lo(bw.x) + alpha * a0[0], bf_hi(bw.x) + alpha * a0[1]); w.y = cvt_pk_bf16(bf_lo(bw.y) + alpha * a0[2], bf_hi(bw.y) + alpha * a0[3]);
;                     w.z = cvt_pk_bf16(bf_lo(bw.z) + alpha * a1[0], bf_hi(bw.z) + alpha * a1[1]); w.w = cvt_pk_bf16(bf_lo(bw.w) + alpha * a1[2], bf_hi(bw.w) + alpha * a1[3]);
;                     *(u32x4*)(rowp + bj * HALF) = w;
;                     ss += (bf_lo(w.x) * bf_lo(w.x) + bf_hi(w.x) * bf_hi(w.x)) + (bf_lo(w.y) * bf_lo(w.y) + bf_hi(w.y) * bf_hi(w.y));
;                     ss += (bf_lo(w.z) * bf_lo(w.z) + bf_hi(w.z) * bf_hi(w.z)) + (bf_lo(w.w) * bf_lo(w.w) + bf_hi(w.w) * bf_hi(w.w)); }
;                 ss = fq_sum(ss);
;                 if (fq == 0) part[(size_t)(row0 + ai * HALF + m * 16) * 16 + u.pn * 4 + wc] = ss; } }
.LBB0_1434:
	s_lshl_b32 s0, s58, 8
	v_mov_b32_e32 v130, v151
	v_mov_b32_e32 v134, v150
	s_add_i32 s0, s0, s40
	s_lshl_b32 s44, s54, 2
	v_add_u32_e32 v148, s0, v130
	s_lshl_b32 s0, s54, 8
	s_or_b32 s0, s0, s41
	v_ashrrev_i32_e32 v149, 31, v148
	v_lshl_add_u32 v146, v134, 3, s0
	v_lshlrev_b64 v[130:131], 11, v[148:149]
	v_ashrrev_i32_e32 v147, 31, v146
	v_lshl_add_u64 v[130:131], s[94:95], 0, v[130:131]
	v_lshl_add_u64 v[130:131], v[146:147], 1, v[130:131]
	global_load_dwordx4 v[182:185], v[130:131], off
	global_load_dwordx4 v[186:189], v[130:131], off offset:256
	v_add_u32_e32 v246, 16, v148
	v_ashrrev_i32_e32 v247, 31, v246
	v_lshlrev_b64 v[246:247], 11, v[246:247]
	v_lshl_add_u64 v[246:247], s[94:95], 0, v[246:247]
	v_lshl_add_u64 v[246:247], v[146:147], 1, v[246:247]
	global_load_dwordx4 v[190:193], v[246:247], off
	global_load_dwordx4 v[194:197], v[246:247], off offset:256
	v_add_u32_e32 v248, 32, v148
	v_ashrrev_i32_e32 v249, 31, v248
	v_lshlrev_b64 v[248:249], 11, v[248:249]
	v_lshl_add_u64 v[248:249], s[94:95], 0, v[248:249]
	v_lshl_add_u64 v[248:249], v[146:147], 1, v[248:249]
	global_load_dwordx4 v[198:201], v[248:249], off
	global_load_dwordx4 v[202:205], v[248:249], off offset:256
	v_add_u32_e32 v246, 48, v148
	v_ashrrev_i32_e32 v247, 31, v246
	v_lshlrev_b64 v[246:247], 11, v[246:247]
	v_lshl_add_u64 v[246:247], s[94:95], 0, v[246:247]
	v_lshl_add_u64 v[246:247], v[146:147], 1, v[246:247]
	global_load_dwordx4 v[206:209], v[246:247], off
	global_load_dwordx4 v[210:213], v[246:247], off offset:256
	v_add_u32_e32 v248, 0x80, v148
	v_ashrrev_i32_e32 v249, 31, v248
	v_lshlrev_b64 v[248:249], 11, v[248:249]
	v_lshl_add_u64 v[248:249], s[94:95], 0, v[248:249]
	v_lshl_add_u64 v[248:249], v[146:147], 1, v[248:249]
	global_load_dwordx4 v[214:217], v[248:249], off
	global_load_dwordx4 v[218:221], v[248:249], off offset:256
	v_add_u32_e32 v246, 0x90, v148
	v_ashrrev_i32_e32 v247, 31, v246
	v_lshlrev_b64 v[246:247], 11, v[246:247]
	v_lshl_add_u64 v[246:247], s[94:95], 0, v[246:247]
	v_lshl_add_u64 v[246:247], v[146:147], 1, v[246:247]
	global_load_dwordx4 v[222:225], v[246:247], off
	global_load_dwordx4 v[226:229], v[246:247], off offset:256
	v_add_u32_e32 v248, 0xa0, v148
	v_ashrrev_i32_e32 v249, 31, v248
	v_lshlrev_b64 v[248:249], 11, v[248:249]
	v_lshl_add_u64 v[248:249], s[94:95], 0, v[248:249]
	v_lshl_add_u64 v[248:249], v[146:147], 1, v[248:249]
	global_load_dwordx4 v[230:233], v[248:249], off
	global_load_dwordx4 v[234:237], v[248:249], off offset:256
	v_add_u32_e32 v246, 0xb0, v148
	v_ashrrev_i32_e32 v247, 31, v246
	v_lshlrev_b64 v[246:247], 11, v[246:247]
	v_lshl_add_u64 v[246:247], s[94:95], 0, v[246:247]
	v_lshl_add_u64 v[246:247], v[146:147], 1, v[246:247]
	global_load_dwordx4 v[238:241], v[246:247], off
	global_load_dwordx4 v[242:245], v[246:247], off offset:256
	s_waitcnt vmcnt(0)
	s_ashr_i32 s45, s44, 31
	v_cmp_eq_u32_e32 vcc, 0, v134
	v_lshlrev_b32_e32 v135, 16, v182
	v_and_b32_e32 v154, 0xffff0000, v182
	v_lshlrev_b32_e32 v158, 16, v183
	v_and_b32_e32 v155, 0xffff0000, v183
	v_lshlrev_b32_e32 v160, 16, v185
	v_and_b32_e32 v157, 0xffff0000, v185
	v_lshlrev_b32_e32 v159, 16, v184
	v_and_b32_e32 v156, 0xffff0000, v184
	v_add_f32_e32 v126, v126, v135
	v_add_f32_e32 v127, v127, v154
	v_add_f32_e32 v128, v128, v158
	v_add_f32_e32 v129, v129, v155
	v_add_f32_e32 v125, v125, v157
	v_add_f32_e32 v135, v122, v159
	v_add_f32_e32 v154, v123, v156
	v_add_f32_e32 v155, v124, v160
	v_cvt_pk_bf16_f32 v122, v126, v127
	v_cvt_pk_bf16_f32 v123, v128, v129
	v_cvt_pk_bf16_f32 v124, v135, v154
	v_cvt_pk_bf16_f32 v125, v155, v125
	s_nop 0
	v_lshlrev_b32_e32 v135, 16, v122
	global_store_dwordx4 v[130:131], v[122:125], off
	v_lshlrev_b32_e32 v154, 16, v123
	v_lshlrev_b32_e32 v155, 16, v124
	v_and_b32_e32 v122, 0xffff0000, v122
	v_and_b32_e32 v123, 0xffff0000, v123
	v_and_b32_e32 v124, 0xffff0000, v124
	v_lshlrev_b32_e32 v156, 16, v125
	v_and_b32_e32 v125, 0xffff0000, v125
	v_mul_f32_e32 v122, v122, v122
	v_mul_f32_e32 v123, v123, v123
	v_mul_f32_e32 v124, v124, v124
	v_mul_f32_e32 v125, v125, v125
	v_fmac_f32_e32 v122, v135, v135
	v_fmac_f32_e32 v123, v154, v154
	v_fmac_f32_e32 v124, v155, v155
	v_fmac_f32_e32 v125, v156, v156
	v_add_f32_e32 v122, v122, v123
	v_add_f32_e32 v123, v124, v125
	v_add_f32_e32 v122, v122, v123
	v_lshlrev_b32_e32 v123, 16, v186
	v_and_b32_e32 v124, 0xffff0000, v186
	v_and_b32_e32 v126, 0xffff0000, v187
	v_lshlrev_b32_e32 v125, 16, v187
	v_lshlrev_b32_e32 v127, 16, v188
	v_and_b32_e32 v128, 0xffff0000, v188
	v_lshlrev_b32_e32 v135, 16, v189
	v_and_b32_e32 v129, 0xffff0000, v189
	v_add_f32_e32 v119, v119, v124
	v_add_f32_e32 v121, v121, v126
	v_add_f32_e32 v118, v118, v123
	v_add_f32_e32 v120, v120, v125
	v_add_f32_e32 v123, v114, v127
	v_add_f32_e32 v124, v115, v128
	v_add_f32_e32 v117, v117, v129
	v_cvt_pk_bf16_f32 v114, v118, v119
	v_cvt_pk_bf16_f32 v115, v120, v121
	v_add_f32_e32 v125, v116, v135
	v_and_b32_e32 v119, 0xffff0000, v114
	v_and_b32_e32 v121, 0xffff0000, v115
	v_cvt_pk_bf16_f32 v116, v123, v124
	v_cvt_pk_bf16_f32 v117, v125, v117
	v_lshlrev_b32_e32 v118, 16, v114
	v_lshlrev_b32_e32 v120, 16, v115
	v_and_b32_e32 v124, 0xffff0000, v116
	v_and_b32_e32 v126, 0xffff0000, v117
	v_mul_f32_e32 v119, v119, v119
	v_mul_f32_e32 v121, v121, v121
	v_lshlrev_b32_e32 v123, 16, v116
	v_lshlrev_b32_e32 v125, 16, v117
	v_mul_f32_e32 v124, v124, v124
	v_mul_f32_e32 v126, v126, v126
	v_fmac_f32_e32 v119, v118, v118
	v_fmac_f32_e32 v121, v120, v120
	v_fmac_f32_e32 v124, v123, v123
	v_fmac_f32_e32 v126, v125, v125
	v_add_f32_e32 v118, v119, v121
	v_add_f32_e32 v119, v124, v126
	v_add_f32_e32 v118, v122, v118
	v_add_f32_e32 v118, v118, v119
	ds_swizzle_b32 v119, v118 offset:swizzle(SWAP,16)
	global_store_dwordx4 v[130:131], v[114:117], off offset:256
	s_waitcnt lgkmcnt(0)
	s_nop 0
	v_add_f32_e32 v114, v118, v119
	v_mov_b32_e32 v115, v114
	s_nop 1
	v_permlane32_swap_b32_e32 v114, v115
	s_and_saveexec_b64 s[54:55], vcc
	s_cbranch_execz .LBB0_1436
	v_lshlrev_b64 v[116:117], 6, v[148:149]
	v_lshl_add_u64 v[116:117], s[96:97], 0, v[116:117]
	v_lshl_add_u64 v[116:117], s[44:45], 2, v[116:117]
	s_lshl_b32 s58, s31, 2
	v_lshl_add_u64 v[116:117], v[116:117], 0, s[58:59]
	v_add_f32_e32 v114, v114, v115
	global_store_dword v[116:117], v114, off
; __device__ __forceinline__ unsigned cvt_pk_bf16(float lo, float hi) { unsigned r; asm volatile("v_cvt_pk_bf16_f32 %0, %1, %2" : "=v"(r) : "v"(lo), "v"(hi)); return r; }
; __device__ __forceinline__ float bf_lo(unsigned w) { return __uint_as_float(w << 16); }
; __device__ __forceinline__ float bf_hi(unsigned w) { return __uint_as_float(w & 0xffff0000u); }
;     __device__ __forceinline__ void operator()(const f32x4 (&acc)[2][2][4][2], const Unit& u, int wr, int wc, int fr, int fq, const float (&rs)[2][4]) const {
;     ...
;             for (int m = 0; m < 4; ++m) { bf16_t* rowp = X + (size_t)(row0 + ai * HALF + m * 16) * DM + col0; float ss = 0.f;
; #pragma unroll
;                 for (int bj = 0; bj < 2; ++bj) { const u32x4 bw = *(const u32x4*)(rowp + bj * HALF); const f32x4 a0 = acc[ai][bj][m][0], a1 = acc[ai][bj][m][1];
;                     u32x4 w; w.x = cvt_pk_bf16(bf_lo(bw.x) + alpha * a0[0], bf_hi(bw.x) + alpha * a0[1]); w.y = cvt_pk_bf16(bf_lo(bw.y) + alpha * a0[2], bf_hi(bw.y) + alpha * a0[3]);
;                     w.z = cvt_pk_bf16(bf_lo(bw.z) + alpha * a1[0], bf_hi(bw.z) + alpha * a1[1]); w.w = cvt_pk_bf16(bf_lo(bw.w) + alpha * a1[2], bf_hi(bw.w) + alpha * a1[3]);
;                     *(u32x4*)(rowp + bj * HALF) = w;
;                     ss += (bf_lo(w.x) * bf_lo(w.x) + bf_hi(w.x) * bf_hi(w.x)) + (bf_lo(w.y) * bf_lo(w.y) + bf_hi(w.y) * bf_hi(w.y));
;                     ss += (bf_lo(w.z) * bf_lo(w.z) + bf_hi(w.z) * bf_hi(w.z)) + (bf_lo(w.w) * bf_lo(w.w) + bf_hi(w.w) * bf_hi(w.w)); }
;                 ss = fq_sum(ss);
;                 if (fq == 0) part[(size_t)(row0 + ai * HALF + m * 16) * 16 + u.pn * 4 + wc] = ss; } }
.LBB0_1436:
	s_or_b64 exec, exec, s[54:55]
	v_add_u32_e32 v114, 16, v148
	v_ashrrev_i32_e32 v115, 31, v114
	v_lshlrev_b64 v[116:117], 11, v[114:115]
	v_lshl_add_u64 v[116:117], s[94:95], 0, v[116:117]
	v_lshl_add_u64 v[120:121], v[146:147], 1, v[116:117]
	s_nop 0
	v_lshlrev_b32_e32 v122, 16, v190
	v_and_b32_e32 v116, 0xffff0000, v190
	v_lshlrev_b32_e32 v123, 16, v191
	v_and_b32_e32 v117, 0xffff0000, v191
	v_lshlrev_b32_e32 v125, 16, v193
	v_and_b32_e32 v119, 0xffff0000, v193
	v_lshlrev_b32_e32 v124, 16, v192
	v_and_b32_e32 v118, 0xffff0000, v192
	v_add_f32_e32 v110, v110, v122
	v_add_f32_e32 v111, v111, v116
	v_add_f32_e32 v112, v112, v123
	v_add_f32_e32 v113, v113, v117
	v_add_f32_e32 v109, v109, v119
	v_add_f32_e32 v116, v106, v124
	v_add_f32_e32 v117, v107, v118
	v_add_f32_e32 v118, v108, v125
	v_cvt_pk_bf16_f32 v106, v110, v111
	v_cvt_pk_bf16_f32 v107, v112, v113
	v_cvt_pk_bf16_f32 v108, v116, v117
	v_cvt_pk_bf16_f32 v109, v118, v109
	s_nop 0
	v_lshlrev_b32_e32 v116, 16, v106
	global_store_dwordx4 v[120:121], v[106:109], off
	v_lshlrev_b32_e32 v117, 16, v107
	v_lshlrev_b32_e32 v118, 16, v108
	v_and_b32_e32 v106, 0xffff0000, v106
	v_and_b32_e32 v107, 0xffff0000, v107
	v_and_b32_e32 v108, 0xffff0000, v108
	v_lshlrev_b32_e32 v119, 16, v109
	v_and_b32_e32 v109, 0xffff0000, v109
	v_mul_f32_e32 v106, v106, v106
	v_mul_f32_e32 v107, v107, v107
	v_mul_f32_e32 v108, v108, v108
	v_mul_f32_e32 v109, v109, v109
	v_fmac_f32_e32 v106, v116, v116
	v_fmac_f32_e32 v107, v117, v117
	v_fmac_f32_e32 v108, v118, v118
	v_fmac_f32_e32 v109, v119, v119
	v_add_f32_e32 v106, v106, v107
	v_add_f32_e32 v107, v108, v109
	v_add_f32_e32 v106, v106, v107
	v_lshlrev_b32_e32 v107, 16, v194
	v_and_b32_e32 v108, 0xffff0000, v194
	v_and_b32_e32 v110, 0xffff0000, v195
	v_lshlrev_b32_e32 v109, 16, v195
	v_lshlrev_b32_e32 v111, 16, v196
	v_and_b32_e32 v112, 0xffff0000, v196
	v_lshlrev_b32_e32 v116, 16, v197
	v_and_b32_e32 v113, 0xffff0000, v197
	v_add_f32_e32 v103, v103, v108
	v_add_f32_e32 v105, v105, v110
	v_add_f32_e32 v102, v102, v107
	v_add_f32_e32 v104, v104, v109
	v_add_f32_e32 v107, v98, v111
	v_add_f32_e32 v108, v99, v112
	v_add_f32_e32 v101, v101, v113
	v_cvt_pk_bf16_f32 v98, v102, v103
	v_cvt_pk_bf16_f32 v99, v104, v105
	v_add_f32_e32 v109, v100, v116
	v_and_b32_e32 v103, 0xffff0000, v98
	v_and_b32_e32 v105, 0xffff0000, v99
	v_cvt_pk_bf16_f32 v100, v107, v108
	v_cvt_pk_bf16_f32 v101, v109, v101
	v_lshlrev_b32_e32 v102, 16, v98
	v_lshlrev_b32_e32 v104, 16, v99
	v_and_b32_e32 v108, 0xffff0000, v100
	v_and_b32_e32 v110, 0xffff0000, v101
	v_mul_f32_e32 v103, v103, v103
	v_mul_f32_e32 v105, v105, v105
	v_lshlrev_b32_e32 v107, 16, v100
	v_lshlrev_b32_e32 v109, 16, v101
	v_mul_f32_e32 v108, v108, v108
	v_mul_f32_e32 v110, v110, v110
	v_fmac_f32_e32 v103, v102, v102
	v_fmac_f32_e32 v105, v104, v104
	v_fmac_f32_e32 v108, v107, v107
	v_fmac_f32_e32 v110, v109, v109
	v_add_f32_e32 v102, v103, v105
	v_add_f32_e32 v103, v108, v110
	v_add_f32_e32 v102, v106, v102
	v_add_f32_e32 v102, v102, v103
	ds_swizzle_b32 v103, v102 offset:swizzle(SWAP,16)
	global_store_dwordx4 v[120:121], v[98:101], off offset:256
	s_waitcnt lgkmcnt(0)
	s_nop 0
	v_add_f32_e32 v98, v102, v103
	v_mov_b32_e32 v99, v98
	s_nop 1
	v_permlane32_swap_b32_e32 v98, v99
	s_and_saveexec_b64 s[54:55], vcc
	s_cbranch_execz .LBB0_1438
	v_lshlrev_b64 v[100:101], 6, v[114:115]
	v_lshl_add_u64 v[100:101], s[96:97], 0, v[100:101]
	v_lshl_add_u64 v[100:101], s[44:45], 2, v[100:101]
	s_lshl_b32 s58, s31, 2
	v_lshl_add_u64 v[100:101], v[100:101], 0, s[58:59]
	v_add_f32_e32 v98, v98, v99
	global_store_dword v[100:101], v98, off
.LBB0_1438:
	s_or_b64 exec, exec, s[54:55]
	v_add_u32_e32 v98, 32, v148
	v_ashrrev_i32_e32 v99, 31, v98
	v_lshlrev_b64 v[100:101], 11, v[98:99]
	v_lshl_add_u64 v[100:101], s[94:95], 0, v[100:101]
	v_lshl_add_u64 v[104:105], v[146:147], 1, v[100:101]
	s_nop 0
	v_lshlrev_b32_e32 v106, 16, v198
	v_and_b32_e32 v100, 0xffff0000, v198
	v_lshlrev_b32_e32 v107, 16, v199
	v_and_b32_e32 v101, 0xffff0000, v199
	v_lshlrev_b32_e32 v109, 16, v201
	v_and_b32_e32 v103, 0xffff0000, v201
	v_lshlrev_b32_e32 v108, 16, v200
	v_and_b32_e32 v102, 0xffff0000, v200
	v_add_f32_e32 v94, v94, v106
	v_add_f32_e32 v95, v95, v100
	v_add_f32_e32 v96, v96, v107
	v_add_f32_e32 v97, v97, v101
	v_add_f32_e32 v93, v93, v103
	v_add_f32_e32 v100, v90, v108
	v_add_f32_e32 v101, v91, v102
	v_add_f32_e32 v102, v92, v109
	v_cvt_pk_bf16_f32 v90, v94, v95
	v_cvt_pk_bf16_f32 v91, v96, v97
	v_cvt_pk_bf16_f32 v92, v100, v101
	v_cvt_pk_bf16_f32 v93, v102, v93
	s_nop 0
	v_lshlrev_b32_e32 v100, 16, v90
	global_store_dwordx4 v[104:105], v[90:93], off
	v_lshlrev_b32_e32 v101, 16, v91
	v_lshlrev_b32_e32 v102, 16, v92
	v_and_b32_e32 v90, 0xffff0000, v90
	v_and_b32_e32 v91, 0xffff0000, v91
	v_and_b32_e32 v92, 0xffff0000, v92
	v_lshlrev_b32_e32 v103, 16, v93
	v_and_b32_e32 v93, 0xffff0000, v93
	v_mul_f32_e32 v90, v90, v90
	v_mul_f32_e32 v91, v91, v91
	v_mul_f32_e32 v92, v92, v92
	v_mul_f32_e32 v93, v93, v93
	v_fmac_f32_e32 v90, v100, v100
	v_fmac_f32_e32 v91, v101, v101
	v_fmac_f32_e32 v92, v102, v102
	v_fmac_f32_e32 v93, v103, v103
	v_add_f32_e32 v90, v90, v91
	v_add_f32_e32 v91, v92, v93
	v_add_f32_e32 v90, v90, v91
	v_lshlrev_b32_e32 v91, 16, v202
	v_and_b32_e32 v92, 0xffff0000, v202
	v_and_b32_e32 v94, 0xffff0000, v203
	v_lshlrev_b32_e32 v93, 16, v203
	v_lshlrev_b32_e32 v95, 16, v204
	v_and_b32_e32 v96, 0xffff0000, v204
	v_lshlrev_b32_e32 v100, 16, v205
	v_and_b32_e32 v97, 0xffff0000, v205
	v_add_f32_e32 v87, v87, v92
	v_add_f32_e32 v89, v89, v94
	v_add_f32_e32 v86, v86, v91
	v_add_f32_e32 v88, v88, v93
	v_add_f32_e32 v91, v82, v95
	v_add_f32_e32 v92, v83, v96
	v_add_f32_e32 v85, v85, v97
	v_cvt_pk_bf16_f32 v82, v86, v87
	v_cvt_pk_bf16_f32 v83, v88, v89
	v_add_f32_e32 v93, v84, v100
	v_and_b32_e32 v87, 0xffff0000, v82
	v_and_b32_e32 v89, 0xffff0000, v83
	v_cvt_pk_bf16_f32 v84, v91, v92
	v_cvt_pk_bf16_f32 v85, v93, v85
	v_lshlrev_b32_e32 v86, 16, v82
	v_lshlrev_b32_e32 v88, 16, v83
	v_and_b32_e32 v92, 0xffff0000, v84
	v_and_b32_e32 v94, 0xffff0000, v85
	v_mul_f32_e32 v87, v87, v87
	v_mul_f32_e32 v89, v89, v89
	v_lshlrev_b32_e32 v91, 16, v84
	v_lshlrev_b32_e32 v93, 16, v85
	v_mul_f32_e32 v92, v92, v92
	v_mul_f32_e32 v94, v94, v94
	v_fmac_f32_e32 v87, v86, v86
	v_fmac_f32_e32 v89, v88, v88
	v_fmac_f32_e32 v92, v91, v91
	v_fmac_f32_e32 v94, v93, v93
	v_add_f32_e32 v86, v87, v89
	v_add_f32_e32 v87, v92, v94
	v_add_f32_e32 v86, v90, v86
	v_add_f32_e32 v86, v86, v87
	ds_swizzle_b32 v87, v86 offset:swizzle(SWAP,16)
	global_store_dwordx4 v[104:105], v[82:85], off offset:256
	s_waitcnt lgkmcnt(0)
	s_nop 0
	v_add_f32_e32 v82, v86, v87
	v_mov_b32_e32 v83, v82
	s_nop 1
	v_permlane32_swap_b32_e32 v82, v83
	s_and_saveexec_b64 s[54:55], vcc
	s_cbranch_execz .LBB0_1440
	v_lshlrev_b64 v[84:85], 6, v[98:99]
	v_lshl_add_u64 v[84:85], s[96:97], 0, v[84:85]
	v_lshl_add_u64 v[84:85], s[44:45], 2, v[84:85]
	s_lshl_b32 s58, s31, 2
	v_lshl_add_u64 v[84:85], v[84:85], 0, s[58:59]
	v_add_f32_e32 v82, v82, v83
	global_store_dword v[84:85], v82, off
; __device__ __forceinline__ unsigned cvt_pk_bf16(float lo, float hi) { unsigned r; asm volatile("v_cvt_pk_bf16_f32 %0, %1, %2" : "=v"(r) : "v"(lo), "v"(hi)); return r; }
; __device__ __forceinline__ float bf_lo(unsigned w) { return __uint_as_float(w << 16); }
; __device__ __forceinline__ float bf_hi(unsigned w) { return __uint_as_float(w & 0xffff0000u); }
;     __device__ __forceinline__ void operator()(const f32x4 (&acc)[2][2][4][2], const Unit& u, int wr, int wc, int fr, int fq, const float (&rs)[2][4]) const {
;     ...
;             for (int m = 0; m < 4; ++m) { bf16_t* rowp = X + (size_t)(row0 + ai * HALF + m * 16) * DM + col0; float ss = 0.f;
; #pragma unroll
;                 for (int bj = 0; bj < 2; ++bj) { const u32x4 bw = *(const u32x4*)(rowp + bj * HALF); const f32x4 a0 = acc[ai][bj][m][0], a1 = acc[ai][bj][m][1];
;                     u32x4 w; w.x = cvt_pk_bf16(bf_lo(bw.x) + alpha * a0[0], bf_hi(bw.x) + alpha * a0[1]); w.y = cvt_pk_bf16(bf_lo(bw.y) + alpha * a0[2], bf_hi(bw.y) + alpha * a0[3]);
;                     w.z = cvt_pk_bf16(bf_lo(bw.z) + alpha * a1[0], bf_hi(bw.z) + alpha * a1[1]); w.w = cvt_pk_bf16(bf_lo(bw.w) + alpha * a1[2], bf_hi(bw.w) + alpha * a1[3]);
;                     *(u32x4*)(rowp + bj * HALF) = w;
;                     ss += (bf_lo(w.x) * bf_lo(w.x) + bf_hi(w.x) * bf_hi(w.x)) + (bf_lo(w.y) * bf_lo(w.y) + bf_hi(w.y) * bf_hi(w.y));
;                     ss += (bf_lo(w.z) * bf_lo(w.z) + bf_hi(w.z) * bf_hi(w.z)) + (bf_lo(w.w) * bf_lo(w.w) + bf_hi(w.w) * bf_hi(w.w)); }
;                 ss = fq_sum(ss);
;                 if (fq == 0) part[(size_t)(row0 + ai * HALF + m * 16) * 16 + u.pn * 4 + wc] = ss; } }
.LBB0_1440:
	s_or_b64 exec, exec, s[54:55]
	v_add_u32_e32 v82, 48, v148
	v_ashrrev_i32_e32 v83, 31, v82
	v_lshlrev_b64 v[84:85], 11, v[82:83]
	v_lshl_add_u64 v[84:85], s[94:95], 0, v[84:85]
	v_lshl_add_u64 v[88:89], v[146:147], 1, v[84:85]
	s_nop 0
	v_lshlrev_b32_e32 v90, 16, v206
	v_and_b32_e32 v84, 0xffff0000, v206
	v_lshlrev_b32_e32 v91, 16, v207
	v_and_b32_e32 v85, 0xffff0000, v207
	v_lshlrev_b32_e32 v93, 16, v209
	v_and_b32_e32 v87, 0xffff0000, v209
	v_lshlrev_b32_e32 v92, 16, v208
	v_and_b32_e32 v86, 0xffff0000, v208
	v_add_f32_e32 v76, v76, v90
	v_add_f32_e32 v77, v77, v84
	v_add_f32_e32 v78, v78, v91
	v_add_f32_e32 v79, v79, v85
	v_add_f32_e32 v75, v75, v87
	v_add_f32_e32 v84, v72, v92
	v_add_f32_e32 v85, v73, v86
	v_add_f32_e32 v86, v74, v93
	v_cvt_pk_bf16_f32 v72, v76, v77
	v_cvt_pk_bf16_f32 v73, v78, v79
	v_cvt_pk_bf16_f32 v74, v84, v85
	v_cvt_pk_bf16_f32 v75, v86, v75
	s_nop 0
	v_lshlrev_b32_e32 v84, 16, v72
	global_store_dwordx4 v[88:89], v[72:75], off
	v_lshlrev_b32_e32 v85, 16, v73
	v_lshlrev_b32_e32 v86, 16, v74
	v_and_b32_e32 v72, 0xffff0000, v72
	v_and_b32_e32 v73, 0xffff0000, v73
	v_and_b32_e32 v74, 0xffff0000, v74
	v_lshlrev_b32_e32 v87, 16, v75
	v_and_b32_e32 v75, 0xffff0000, v75
	v_mul_f32_e32 v72, v72, v72
	v_mul_f32_e32 v73, v73, v73
	v_mul_f32_e32 v74, v74, v74
	v_mul_f32_e32 v75, v75, v75
	v_fmac_f32_e32 v72, v84, v84
	v_fmac_f32_e32 v73, v85, v85
	v_fmac_f32_e32 v74, v86, v86
	v_fmac_f32_e32 v75, v87, v87
	v_add_f32_e32 v72, v72, v73
	v_add_f32_e32 v73, v74, v75
	v_add_f32_e32 v72, v72, v73
	v_lshlrev_b32_e32 v73, 16, v210
	v_and_b32_e32 v74, 0xffff0000, v210
	v_and_b32_e32 v76, 0xffff0000, v211
	v_lshlrev_b32_e32 v75, 16, v211
	v_lshlrev_b32_e32 v77, 16, v212
	v_and_b32_e32 v78, 0xffff0000, v212
	v_lshlrev_b32_e32 v84, 16, v213
	v_and_b32_e32 v79, 0xffff0000, v213
	v_add_f32_e32 v69, v69, v74
	v_add_f32_e32 v71, v71, v76
	v_add_f32_e32 v68, v68, v73
	v_add_f32_e32 v70, v70, v75
	v_add_f32_e32 v73, v64, v77
	v_add_f32_e32 v74, v65, v78
	v_add_f32_e32 v67, v67, v79
	v_cvt_pk_bf16_f32 v64, v68, v69
	v_cvt_pk_bf16_f32 v65, v70, v71
	v_add_f32_e32 v75, v66, v84
	v_and_b32_e32 v69, 0xffff0000, v64
	v_and_b32_e32 v71, 0xffff0000, v65
	v_cvt_pk_bf16_f32 v66, v73, v74
	v_cvt_pk_bf16_f32 v67, v75, v67
	v_lshlrev_b32_e32 v68, 16, v64
	v_lshlrev_b32_e32 v70, 16, v65
	v_and_b32_e32 v74, 0xffff0000, v66
	v_and_b32_e32 v76, 0xffff0000, v67
	v_mul_f32_e32 v69, v69, v69
	v_mul_f32_e32 v71, v71, v71
	v_lshlrev_b32_e32 v73, 16, v66
	v_lshlrev_b32_e32 v75, 16, v67
	v_mul_f32_e32 v74, v74, v74
	v_mul_f32_e32 v76, v76, v76
	v_fmac_f32_e32 v69, v68, v68
	v_fmac_f32_e32 v71, v70, v70
	v_fmac_f32_e32 v74, v73, v73
	v_fmac_f32_e32 v76, v75, v75
	v_add_f32_e32 v68, v69, v71
	v_add_f32_e32 v69, v74, v76
	v_add_f32_e32 v68, v72, v68
	v_add_f32_e32 v68, v68, v69
	ds_swizzle_b32 v69, v68 offset:swizzle(SWAP,16)
	global_store_dwordx4 v[88:89], v[64:67], off offset:256
	s_waitcnt lgkmcnt(0)
	s_nop 0
	v_add_f32_e32 v64, v68, v69
	v_mov_b32_e32 v65, v64
	s_nop 1
	v_permlane32_swap_b32_e32 v64, v65
	s_and_saveexec_b64 s[54:55], vcc
	s_cbranch_execz .LBB0_1442
	v_lshlrev_b64 v[66:67], 6, v[82:83]
	v_lshl_add_u64 v[66:67], s[96:97], 0, v[66:67]
	v_lshl_add_u64 v[66:67], s[44:45], 2, v[66:67]
	s_lshl_b32 s58, s31, 2
	v_lshl_add_u64 v[66:67], v[66:67], 0, s[58:59]
	v_add_f32_e32 v64, v64, v65
	global_store_dword v[66:67], v64, off
.LBB0_1442:
	s_or_b64 exec, exec, s[54:55]
	v_add_u32_e32 v64, 0x80, v148
	v_ashrrev_i32_e32 v65, 31, v64
	v_lshlrev_b64 v[66:67], 11, v[64:65]
	v_lshl_add_u64 v[66:67], s[94:95], 0, v[66:67]
	v_lshl_add_u64 v[70:71], v[146:147], 1, v[66:67]
	s_nop 0
	v_lshlrev_b32_e32 v72, 16, v214
	v_and_b32_e32 v66, 0xffff0000, v214
	v_lshlrev_b32_e32 v73, 16, v215
	v_and_b32_e32 v67, 0xffff0000, v215
	v_lshlrev_b32_e32 v75, 16, v217
	v_and_b32_e32 v69, 0xffff0000, v217
	v_lshlrev_b32_e32 v74, 16, v216
	v_and_b32_e32 v68, 0xffff0000, v216
	v_add_f32_e32 v60, v60, v72
	v_add_f32_e32 v61, v61, v66
	v_add_f32_e32 v62, v62, v73
	v_add_f32_e32 v63, v63, v67
	v_add_f32_e32 v59, v59, v69
	v_add_f32_e32 v66, v56, v74
	v_add_f32_e32 v67, v57, v68
	v_add_f32_e32 v68, v58, v75
	v_cvt_pk_bf16_f32 v56, v60, v61
	v_cvt_pk_bf16_f32 v57, v62, v63
	v_cvt_pk_bf16_f32 v58, v66, v67
	v_cvt_pk_bf16_f32 v59, v68, v59
	s_nop 0
	v_lshlrev_b32_e32 v66, 16, v56
	global_store_dwordx4 v[70:71], v[56:59], off
	v_lshlrev_b32_e32 v67, 16, v57
	v_lshlrev_b32_e32 v68, 16, v58
	v_and_b32_e32 v56, 0xffff0000, v56
	v_and_b32_e32 v57, 0xffff0000, v57
	v_and_b32_e32 v58, 0xffff0000, v58
	v_lshlrev_b32_e32 v69, 16, v59
	v_and_b32_e32 v59, 0xffff0000, v59
	v_mul_f32_e32 v56, v56, v56
	v_mul_f32_e32 v57, v57, v57
	v_mul_f32_e32 v58, v58, v58
	v_mul_f32_e32 v59, v59, v59
	v_fmac_f32_e32 v56, v66, v66
	v_fmac_f32_e32 v57, v67, v67
	v_fmac_f32_e32 v58, v68, v68
	v_fmac_f32_e32 v59, v69, v69
	v_add_f32_e32 v56, v56, v57
	v_add_f32_e32 v57, v58, v59
	v_add_f32_e32 v56, v56, v57
	v_lshlrev_b32_e32 v57, 16, v218
	v_and_b32_e32 v58, 0xffff0000, v218
	v_and_b32_e32 v60, 0xffff0000, v219
	v_lshlrev_b32_e32 v59, 16, v219
	v_lshlrev_b32_e32 v61, 16, v220
	v_and_b32_e32 v62, 0xffff0000, v220
	v_lshlrev_b32_e32 v66, 16, v221
	v_and_b32_e32 v63, 0xffff0000, v221
	v_add_f32_e32 v53, v53, v58
	v_add_f32_e32 v55, v55, v60
	v_add_f32_e32 v52, v52, v57
	v_add_f32_e32 v54, v54, v59
	v_add_f32_e32 v57, v48, v61
	v_add_f32_e32 v58, v49, v62
	v_add_f32_e32 v51, v51, v63
	v_cvt_pk_bf16_f32 v48, v52, v53
	v_cvt_pk_bf16_f32 v49, v54, v55
	v_add_f32_e32 v59, v50, v66
	v_and_b32_e32 v53, 0xffff0000, v48
	v_and_b32_e32 v55, 0xffff0000, v49
	v_cvt_pk_bf16_f32 v50, v57, v58
	v_cvt_pk_bf16_f32 v51, v59, v51
	v_lshlrev_b32_e32 v52, 16, v48
	v_lshlrev_b32_e32 v54, 16, v49
	v_and_b32_e32 v58, 0xffff0000, v50
	v_and_b32_e32 v60, 0xffff0000, v51
	v_mul_f32_e32 v53, v53, v53
	v_mul_f32_e32 v55, v55, v55
	v_lshlrev_b32_e32 v57, 16, v50
	v_lshlrev_b32_e32 v59, 16, v51
	v_mul_f32_e32 v58, v58, v58
	v_mul_f32_e32 v60, v60, v60
	v_fmac_f32_e32 v53, v52, v52
	v_fmac_f32_e32 v55, v54, v54
	v_fmac_f32_e32 v58, v57, v57
	v_fmac_f32_e32 v60, v59, v59
	v_add_f32_e32 v52, v53, v55
	v_add_f32_e32 v53, v58, v60
	v_add_f32_e32 v52, v56, v52
	v_add_f32_e32 v52, v52, v53
	ds_swizzle_b32 v53, v52 offset:swizzle(SWAP,16)
	global_store_dwordx4 v[70:71], v[48:51], off offset:256
	s_waitcnt lgkmcnt(0)
	s_nop 0
	v_add_f32_e32 v48, v52, v53
	v_mov_b32_e32 v49, v48
	s_nop 1
	v_permlane32_swap_b32_e32 v48, v49
	s_and_saveexec_b64 s[54:55], vcc
	s_cbranch_execz .LBB0_1444
	v_lshlrev_b64 v[50:51], 6, v[64:65]
	v_lshl_add_u64 v[50:51], s[96:97], 0, v[50:51]
	v_lshl_add_u64 v[50:51], s[44:45], 2, v[50:51]
	s_lshl_b32 s58, s31, 2
	v_lshl_add_u64 v[50:51], v[50:51], 0, s[58:59]
	v_add_f32_e32 v48, v48, v49
	global_store_dword v[50:51], v48, off
; __device__ __forceinline__ unsigned cvt_pk_bf16(float lo, float hi) { unsigned r; asm volatile("v_cvt_pk_bf16_f32 %0, %1, %2" : "=v"(r) : "v"(lo), "v"(hi)); return r; }
; __device__ __forceinline__ float bf_lo(unsigned w) { return __uint_as_float(w << 16); }
; __device__ __forceinline__ float bf_hi(unsigned w) { return __uint_as_float(w & 0xffff0000u); }
;     __device__ __forceinline__ void operator()(const f32x4 (&acc)[2][2][4][2], const Unit& u, int wr, int wc, int fr, int fq, const float (&rs)[2][4]) const {
;     ...
;             for (int m = 0; m < 4; ++m) { bf16_t* rowp = X + (size_t)(row0 + ai * HALF + m * 16) * DM + col0; float ss = 0.f;
; #pragma unroll
;                 for (int bj = 0; bj < 2; ++bj) { const u32x4 bw = *(const u32x4*)(rowp + bj * HALF); const f32x4 a0 = acc[ai][bj][m][0], a1 = acc[ai][bj][m][1];
;                     u32x4 w; w.x = cvt_pk_bf16(bf_lo(bw.x) + alpha * a0[0], bf_hi(bw.x) + alpha * a0[1]); w.y = cvt_pk_bf16(bf_lo(bw.y) + alpha * a0[2], bf_hi(bw.y) + alpha * a0[3]);
;                     w.z = cvt_pk_bf16(bf_lo(bw.z) + alpha * a1[0], bf_hi(bw.z) + alpha * a1[1]); w.w = cvt_pk_bf16(bf_lo(bw.w) + alpha * a1[2], bf_hi(bw.w) + alpha * a1[3]);
;                     *(u32x4*)(rowp + bj * HALF) = w;
;                     ss += (bf_lo(w.x) * bf_lo(w.x) + bf_hi(w.x) * bf_hi(w.x)) + (bf_lo(w.y) * bf_lo(w.y) + bf_hi(w.y) * bf_hi(w.y));
;                     ss += (bf_lo(w.z) * bf_lo(w.z) + bf_hi(w.z) * bf_hi(w.z)) + (bf_lo(w.w) * bf_lo(w.w) + bf_hi(w.w) * bf_hi(w.w)); }
;                 ss = fq_sum(ss);
;                 if (fq == 0) part[(size_t)(row0 + ai * HALF + m * 16) * 16 + u.pn * 4 + wc] = ss; } }
.LBB0_1444:
	s_or_b64 exec, exec, s[54:55]
	v_add_u32_e32 v48, 0x90, v148
	v_ashrrev_i32_e32 v49, 31, v48
	v_lshlrev_b64 v[50:51], 11, v[48:49]
	v_lshl_add_u64 v[50:51], s[94:95], 0, v[50:51]
	v_lshl_add_u64 v[54:55], v[146:147], 1, v[50:51]
	s_nop 0
	v_lshlrev_b32_e32 v56, 16, v222
	v_and_b32_e32 v50, 0xffff0000, v222
	v_lshlrev_b32_e32 v57, 16, v223
	v_and_b32_e32 v51, 0xffff0000, v223
	v_lshlrev_b32_e32 v59, 16, v225
	v_and_b32_e32 v53, 0xffff0000, v225
	v_lshlrev_b32_e32 v58, 16, v224
	v_and_b32_e32 v52, 0xffff0000, v224
	v_add_f32_e32 v44, v44, v56
	v_add_f32_e32 v45, v45, v50
	v_add_f32_e32 v46, v46, v57
	v_add_f32_e32 v47, v47, v51
	v_add_f32_e32 v43, v43, v53
	v_add_f32_e32 v50, v40, v58
	v_add_f32_e32 v51, v41, v52
	v_add_f32_e32 v52, v42, v59
	v_cvt_pk_bf16_f32 v40, v44, v45
	v_cvt_pk_bf16_f32 v41, v46, v47
	v_cvt_pk_bf16_f32 v42, v50, v51
	v_cvt_pk_bf16_f32 v43, v52, v43
	s_nop 0
	v_lshlrev_b32_e32 v50, 16, v40
	global_store_dwordx4 v[54:55], v[40:43], off
	v_lshlrev_b32_e32 v51, 16, v41
	v_lshlrev_b32_e32 v52, 16, v42
	v_and_b32_e32 v40, 0xffff0000, v40
	v_and_b32_e32 v41, 0xffff0000, v41
	v_and_b32_e32 v42, 0xffff0000, v42
	v_lshlrev_b32_e32 v53, 16, v43
	v_and_b32_e32 v43, 0xffff0000, v43
	v_mul_f32_e32 v40, v40, v40
	v_mul_f32_e32 v41, v41, v41
	v_mul_f32_e32 v42, v42, v42
	v_mul_f32_e32 v43, v43, v43
	v_fmac_f32_e32 v40, v50, v50
	v_fmac_f32_e32 v41, v51, v51
	v_fmac_f32_e32 v42, v52, v52
	v_fmac_f32_e32 v43, v53, v53
	v_add_f32_e32 v40, v40, v41
	v_add_f32_e32 v41, v42, v43
	v_add_f32_e32 v40, v40, v41
	v_lshlrev_b32_e32 v41, 16, v226
	v_and_b32_e32 v42, 0xffff0000, v226
	v_and_b32_e32 v44, 0xffff0000, v227
	v_lshlrev_b32_e32 v43, 16, v227
	v_lshlrev_b32_e32 v45, 16, v228
	v_and_b32_e32 v46, 0xffff0000, v228
	v_lshlrev_b32_e32 v50, 16, v229
	v_and_b32_e32 v47, 0xffff0000, v229
	v_add_f32_e32 v37, v37, v42
	v_add_f32_e32 v39, v39, v44
	v_add_f32_e32 v36, v36, v41
	v_add_f32_e32 v38, v38, v43
	v_add_f32_e32 v41, v32, v45
	v_add_f32_e32 v42, v33, v46
	v_add_f32_e32 v35, v35, v47
	v_cvt_pk_bf16_f32 v32, v36, v37
	v_cvt_pk_bf16_f32 v33, v38, v39
	v_add_f32_e32 v43, v34, v50
	v_and_b32_e32 v37, 0xffff0000, v32
	v_and_b32_e32 v39, 0xffff0000, v33
	v_cvt_pk_bf16_f32 v34, v41, v42
	v_cvt_pk_bf16_f32 v35, v43, v35
	v_lshlrev_b32_e32 v36, 16, v32
	v_lshlrev_b32_e32 v38, 16, v33
	v_and_b32_e32 v42, 0xffff0000, v34
	v_and_b32_e32 v44, 0xffff0000, v35
	v_mul_f32_e32 v37, v37, v37
	v_mul_f32_e32 v39, v39, v39
	v_lshlrev_b32_e32 v41, 16, v34
	v_lshlrev_b32_e32 v43, 16, v35
	v_mul_f32_e32 v42, v42, v42
	v_mul_f32_e32 v44, v44, v44
	v_fmac_f32_e32 v37, v36, v36
	v_fmac_f32_e32 v39, v38, v38
	v_fmac_f32_e32 v42, v41, v41
	v_fmac_f32_e32 v44, v43, v43
	v_add_f32_e32 v36, v37, v39
	v_add_f32_e32 v37, v42, v44
	v_add_f32_e32 v36, v40, v36
	v_add_f32_e32 v36, v36, v37
	ds_swizzle_b32 v37, v36 offset:swizzle(SWAP,16)
	global_store_dwordx4 v[54:55], v[32:35], off offset:256
	s_waitcnt lgkmcnt(0)
	s_nop 0
	v_add_f32_e32 v32, v36, v37
	v_mov_b32_e32 v33, v32
	s_nop 1
	v_permlane32_swap_b32_e32 v32, v33
	s_and_saveexec_b64 s[54:55], vcc
	s_cbranch_execz .LBB0_1446
	v_lshlrev_b64 v[34:35], 6, v[48:49]
	v_lshl_add_u64 v[34:35], s[96:97], 0, v[34:35]
	v_lshl_add_u64 v[34:35], s[44:45], 2, v[34:35]
	s_lshl_b32 s58, s31, 2
	v_lshl_add_u64 v[34:35], v[34:35], 0, s[58:59]
	v_add_f32_e32 v32, v32, v33
	global_store_dword v[34:35], v32, off
; __device__ __forceinline__ unsigned cvt_pk_bf16(float lo, float hi) { unsigned r; asm volatile("v_cvt_pk_bf16_f32 %0, %1, %2" : "=v"(r) : "v"(lo), "v"(hi)); return r; }
; __device__ __forceinline__ float bf_lo(unsigned w) { return __uint_as_float(w << 16); }
; __device__ __forceinline__ float bf_hi(unsigned w) { return __uint_as_float(w & 0xffff0000u); }
;     __device__ __forceinline__ void operator()(const f32x4 (&acc)[2][2][4][2], const Unit& u, int wr, int wc, int fr, int fq, const float (&rs)[2][4]) const {
;     ...
;             for (int m = 0; m < 4; ++m) { bf16_t* rowp = X + (size_t)(row0 + ai * HALF + m * 16) * DM + col0; float ss = 0.f;
; #pragma unroll
;                 for (int bj = 0; bj < 2; ++bj) { const u32x4 bw = *(const u32x4*)(rowp + bj * HALF); const f32x4 a0 = acc[ai][bj][m][0], a1 = acc[ai][bj][m][1];
;                     u32x4 w; w.x = cvt_pk_bf16(bf_lo(bw.x) + alpha * a0[0], bf_hi(bw.x) + alpha * a0[1]); w.y = cvt_pk_bf16(bf_lo(bw.y) + alpha * a0[2], bf_hi(bw.y) + alpha * a0[3]);
;                     w.z = cvt_pk_bf16(bf_lo(bw.z) + alpha * a1[0], bf_hi(bw.z) + alpha * a1[1]); w.w = cvt_pk_bf16(bf_lo(bw.w) + alpha * a1[2], bf_hi(bw.w) + alpha * a1[3]);
;                     *(u32x4*)(rowp + bj * HALF) = w;
;                     ss += (bf_lo(w.x) * bf_lo(w.x) + bf_hi(w.x) * bf_hi(w.x)) + (bf_lo(w.y) * bf_lo(w.y) + bf_hi(w.y) * bf_hi(w.y));
;                     ss += (bf_lo(w.z) * bf_lo(w.z) + bf_hi(w.z) * bf_hi(w.z)) + (bf_lo(w.w) * bf_lo(w.w) + bf_hi(w.w) * bf_hi(w.w)); }
;                 ss = fq_sum(ss);
;                 if (fq == 0) part[(size_t)(row0 + ai * HALF + m * 16) * 16 + u.pn * 4 + wc] = ss; } }
.LBB0_1446:
	s_or_b64 exec, exec, s[54:55]
	v_add_u32_e32 v32, 0xa0, v148
	v_ashrrev_i32_e32 v33, 31, v32
	v_lshlrev_b64 v[34:35], 11, v[32:33]
	v_lshl_add_u64 v[34:35], s[94:95], 0, v[34:35]
	v_lshl_add_u64 v[38:39], v[146:147], 1, v[34:35]
	s_nop 0
	v_lshlrev_b32_e32 v40, 16, v230
	v_and_b32_e32 v34, 0xffff0000, v230
	v_lshlrev_b32_e32 v41, 16, v231
	v_and_b32_e32 v35, 0xffff0000, v231
	v_lshlrev_b32_e32 v43, 16, v233
	v_and_b32_e32 v37, 0xffff0000, v233
	v_lshlrev_b32_e32 v42, 16, v232
	v_and_b32_e32 v36, 0xffff0000, v232
	v_add_f32_e32 v28, v28, v40
	v_add_f32_e32 v29, v29, v34
	v_add_f32_e32 v30, v30, v41
	v_add_f32_e32 v31, v31, v35
	v_add_f32_e32 v27, v27, v37
	v_add_f32_e32 v34, v24, v42
	v_add_f32_e32 v35, v25, v36
	v_add_f32_e32 v36, v26, v43
	v_cvt_pk_bf16_f32 v24, v28, v29
	v_cvt_pk_bf16_f32 v25, v30, v31
	v_cvt_pk_bf16_f32 v26, v34, v35
	v_cvt_pk_bf16_f32 v27, v36, v27
	s_nop 0
	v_lshlrev_b32_e32 v34, 16, v24
	global_store_dwordx4 v[38:39], v[24:27], off
	v_lshlrev_b32_e32 v35, 16, v25
	v_lshlrev_b32_e32 v36, 16, v26
	v_and_b32_e32 v24, 0xffff0000, v24
	v_and_b32_e32 v25, 0xffff0000, v25
	v_and_b32_e32 v26, 0xffff0000, v26
	v_lshlrev_b32_e32 v37, 16, v27
	v_and_b32_e32 v27, 0xffff0000, v27
	v_mul_f32_e32 v24, v24, v24
	v_mul_f32_e32 v25, v25, v25
	v_mul_f32_e32 v26, v26, v26
	v_mul_f32_e32 v27, v27, v27
	v_fmac_f32_e32 v24, v34, v34
	v_fmac_f32_e32 v25, v35, v35
	v_fmac_f32_e32 v26, v36, v36
	v_fmac_f32_e32 v27, v37, v37
	v_add_f32_e32 v24, v24, v25
	v_add_f32_e32 v25, v26, v27
	v_add_f32_e32 v24, v24, v25
	v_lshlrev_b32_e32 v25, 16, v234
	v_and_b32_e32 v26, 0xffff0000, v234
	v_and_b32_e32 v28, 0xffff0000, v235
	v_lshlrev_b32_e32 v27, 16, v235
	v_lshlrev_b32_e32 v29, 16, v236
	v_and_b32_e32 v30, 0xffff0000, v236
	v_lshlrev_b32_e32 v34, 16, v237
	v_and_b32_e32 v31, 0xffff0000, v237
	v_add_f32_e32 v21, v21, v26
	v_add_f32_e32 v23, v23, v28
	v_add_f32_e32 v20, v20, v25
	v_add_f32_e32 v22, v22, v27
	v_add_f32_e32 v25, v16, v29
	v_add_f32_e32 v26, v17, v30
	v_add_f32_e32 v19, v19, v31
	v_cvt_pk_bf16_f32 v16, v20, v21
	v_cvt_pk_bf16_f32 v17, v22, v23
	v_add_f32_e32 v27, v18, v34
	v_and_b32_e32 v21, 0xffff0000, v16
	v_and_b32_e32 v23, 0xffff0000, v17
	v_cvt_pk_bf16_f32 v18, v25, v26
	v_cvt_pk_bf16_f32 v19, v27, v19
	v_lshlrev_b32_e32 v20, 16, v16
	v_lshlrev_b32_e32 v22, 16, v17
	v_and_b32_e32 v26, 0xffff0000, v18
	v_and_b32_e32 v28, 0xffff0000, v19
	v_mul_f32_e32 v21, v21, v21
	v_mul_f32_e32 v23, v23, v23
	v_lshlrev_b32_e32 v25, 16, v18
	v_lshlrev_b32_e32 v27, 16, v19
	v_mul_f32_e32 v26, v26, v26
	v_mul_f32_e32 v28, v28, v28
	v_fmac_f32_e32 v21, v20, v20
	v_fmac_f32_e32 v23, v22, v22
	v_fmac_f32_e32 v26, v25, v25
	v_fmac_f32_e32 v28, v27, v27
	v_add_f32_e32 v20, v21, v23
	v_add_f32_e32 v21, v26, v28
	v_add_f32_e32 v20, v24, v20
	v_add_f32_e32 v20, v20, v21
	ds_swizzle_b32 v21, v20 offset:swizzle(SWAP,16)
	global_store_dwordx4 v[38:39], v[16:19], off offset:256
	s_waitcnt lgkmcnt(0)
	s_nop 0
	v_add_f32_e32 v16, v20, v21
	v_mov_b32_e32 v17, v16
	s_nop 1
	v_permlane32_swap_b32_e32 v16, v17
	s_and_saveexec_b64 s[54:55], vcc
	s_cbranch_execz .LBB0_1448
	v_lshlrev_b64 v[18:19], 6, v[32:33]
	v_lshl_add_u64 v[18:19], s[96:97], 0, v[18:19]
	v_lshl_add_u64 v[18:19], s[44:45], 2, v[18:19]
	s_lshl_b32 s58, s31, 2
	v_lshl_add_u64 v[18:19], v[18:19], 0, s[58:59]
	v_add_f32_e32 v16, v16, v17
	global_store_dword v[18:19], v16, off
.LBB0_1448:
	s_or_b64 exec, exec, s[54:55]
	v_add_u32_e32 v16, 0xb0, v148
	v_ashrrev_i32_e32 v17, 31, v16
	v_lshlrev_b64 v[18:19], 11, v[16:17]
	v_lshl_add_u64 v[18:19], s[94:95], 0, v[18:19]
	v_lshl_add_u64 v[22:23], v[146:147], 1, v[18:19]
	s_nop 0
	v_lshlrev_b32_e32 v24, 16, v238
	v_and_b32_e32 v18, 0xffff0000, v238
	v_lshlrev_b32_e32 v25, 16, v239
	v_and_b32_e32 v19, 0xffff0000, v239
	v_lshlrev_b32_e32 v27, 16, v241
	v_and_b32_e32 v21, 0xffff0000, v241
	v_lshlrev_b32_e32 v26, 16, v240
	v_and_b32_e32 v20, 0xffff0000, v240
	v_add_f32_e32 v12, v12, v24
	v_add_f32_e32 v13, v13, v18
	v_add_f32_e32 v14, v14, v25
	v_add_f32_e32 v15, v15, v19
	v_add_f32_e32 v11, v11, v21
	v_add_f32_e32 v18, v8, v26
	v_add_f32_e32 v19, v9, v20
	v_add_f32_e32 v20, v10, v27
	v_cvt_pk_bf16_f32 v8, v12, v13
	v_cvt_pk_bf16_f32 v9, v14, v15
	v_cvt_pk_bf16_f32 v10, v18, v19
	v_cvt_pk_bf16_f32 v11, v20, v11
	s_nop 0
	v_lshlrev_b32_e32 v18, 16, v8
	global_store_dwordx4 v[22:23], v[8:11], off
	v_lshlrev_b32_e32 v19, 16, v9
	v_lshlrev_b32_e32 v20, 16, v10
	v_and_b32_e32 v8, 0xffff0000, v8
	v_and_b32_e32 v9, 0xffff0000, v9
	v_and_b32_e32 v10, 0xffff0000, v10
	v_lshlrev_b32_e32 v21, 16, v11
	v_and_b32_e32 v11, 0xffff0000, v11
	v_mul_f32_e32 v8, v8, v8
	v_mul_f32_e32 v9, v9, v9
	v_mul_f32_e32 v10, v10, v10
	v_mul_f32_e32 v11, v11, v11
	v_fmac_f32_e32 v8, v18, v18
	v_fmac_f32_e32 v9, v19, v19
	v_fmac_f32_e32 v10, v20, v20
	v_fmac_f32_e32 v11, v21, v21
	v_add_f32_e32 v8, v8, v9
	v_add_f32_e32 v9, v10, v11
	v_add_f32_e32 v8, v8, v9
	v_lshlrev_b32_e32 v9, 16, v242
	v_and_b32_e32 v10, 0xffff0000, v242
	v_and_b32_e32 v12, 0xffff0000, v243
	v_lshlrev_b32_e32 v11, 16, v243
	v_lshlrev_b32_e32 v13, 16, v244
	v_and_b32_e32 v14, 0xffff0000, v244
	v_lshlrev_b32_e32 v18, 16, v245
	v_and_b32_e32 v15, 0xffff0000, v245
	v_add_f32_e32 v5, v5, v10
	v_add_f32_e32 v7, v7, v12
	v_add_f32_e32 v4, v4, v9
	v_add_f32_e32 v6, v6, v11
	v_add_f32_e32 v9, v0, v13
	v_add_f32_e32 v10, v1, v14
	v_add_f32_e32 v3, v3, v15
	v_cvt_pk_bf16_f32 v0, v4, v5
	v_cvt_pk_bf16_f32 v1, v6, v7
	v_add_f32_e32 v11, v2, v18
	v_and_b32_e32 v5, 0xffff0000, v0
	v_and_b32_e32 v7, 0xffff0000, v1
	v_cvt_pk_bf16_f32 v2, v9, v10
	v_cvt_pk_bf16_f32 v3, v11, v3
	v_lshlrev_b32_e32 v4, 16, v0
	v_lshlrev_b32_e32 v6, 16, v1
	v_and_b32_e32 v10, 0xffff0000, v2
	v_and_b32_e32 v12, 0xffff0000, v3
	v_mul_f32_e32 v5, v5, v5
	v_mul_f32_e32 v7, v7, v7
	v_lshlrev_b32_e32 v9, 16, v2
	v_lshlrev_b32_e32 v11, 16, v3
	v_mul_f32_e32 v10, v10, v10
	v_mul_f32_e32 v12, v12, v12
	v_fmac_f32_e32 v5, v4, v4
	v_fmac_f32_e32 v7, v6, v6
	v_fmac_f32_e32 v10, v9, v9
	v_fmac_f32_e32 v12, v11, v11
	v_add_f32_e32 v4, v5, v7
	v_add_f32_e32 v5, v10, v12
	v_add_f32_e32 v4, v8, v4
	v_add_f32_e32 v4, v4, v5
	ds_swizzle_b32 v5, v4 offset:swizzle(SWAP,16)
	global_store_dwordx4 v[22:23], v[0:3], off offset:256
	s_waitcnt lgkmcnt(0)
	s_nop 0
	v_add_f32_e32 v0, v4, v5
	v_mov_b32_e32 v1, v0
	s_nop 1
	v_permlane32_swap_b32_e32 v0, v1
	s_and_saveexec_b64 s[54:55], vcc
	s_cbranch_execz .LBB0_1450
	v_lshlrev_b64 v[2:3], 6, v[16:17]
	v_lshl_add_u64 v[2:3], s[96:97], 0, v[2:3]
	v_lshl_add_u64 v[2:3], s[44:45], 2, v[2:3]
	s_lshl_b32 s58, s31, 2
	v_lshl_add_u64 v[2:3], v[2:3], 0, s[58:59]
	v_add_f32_e32 v0, v0, v1
	global_store_dword v[2:3], v0, off

; #define ATT_DMA(t, sk, sv) do { glds16(ksrc + (long)(t) * 64 * a.ldk, (unsigned)__builtin_amdgcn_readfirstlane(kdst + (sk) * KSLOT)); \
;         if (MODE == 0 && wid < 4) glds16(kpsrc + (long)(t) * 64 * 32, (unsigned)__builtin_amdgcn_readfirstlane(kpdst + (sk) * KSLOT)); \
;         glds16(vsrc + (long)(t) * 64 * a.ldv, (unsigned)__builtin_amdgcn_readfirstlane(vdst + (sv) * VSLOT)); } while (0)
; #define ATT_WAIT_BAR() asm volatile("s_waitcnt vmcnt(0) lgkmcnt(0)\n\ts_barrier" ::: "memory")
; template <int MODE> __device__ __forceinline__ void attn_unit(const Unit& a, char* shm) {
;     ...
;     const bf16_t* ksrc = a.K + (long)lane * a.ldk + wid * 8;
;     const bf16_t* kpsrc = a.KPE + (long)lane * 32 + (wid & 3) * 8;
;     const bf16_t* vsrc = a.V + (long)(16 * (wid & 3) + (lane >> 2)) * a.ldv + (wid >> 2) * 32 + (lane & 3) * 8;
;     const unsigned kdst = lds0 + LDS_K + wid * 1024, kpdst = lds0 + LDS_K + (8 + (wid & 3)) * 1024, vdst = lds0 + LDS_V + wid * 1024;
;     ...
;     const int g = wid >> 2;
;     ATT_DMA(a.t_lo, 0, 0);
;     bf16x8 qr[ND];
;     { const bf16_t* Qw = a.Q + (long)(wid * 32 + r32) * a.ldq + hi * 8;
; #pragma unroll
;       for (int d0 = 0; d0 < ND; ++d0) qr[d0] = *(const bf16x8*)(Qw + d0 * 16); }
;     float mhat = (MODE == 1) ? a.sink2 : 0.f;
;     float l_reg = (MODE == 1 && hi == 0) ? 1.f : 0.f;
;     f32x16 o[2]; o[0] = f32x16{}; o[1] = f32x16{};
;     f32x16 negm;
; #pragma unroll
;     for (int r = 0; r < 16; ++r) negm[r] = -mhat;
;     const int tq0 = a.qpos0 + wid * 32, tq = tq0 + r32;
;     const lds_cptr vp0 = shm3 + LDS_V + ((lane >> 4) & 1) * 32 + (lane & 3) * 8 + (4 * hi + ((lane & 15) >> 2)) * 64;
;     u32x4 pw[4]; pw[0] = (u32x4){0u, 0u, 0u, 0u}; pw[1] = pw[0]; pw[2] = pw[0]; pw[3] = pw[0];
;     bool pend = false; int sv = 0, svp = 0;
;     for (int t = a.t_lo; t < a.t_hi; ++t) {
;         const int s = (t - a.t_lo) & 1;
;         ATT_WAIT_BAR();
;         if (t + 1 < a.t_hi) ATT_DMA(t + 1, s ^ 1, (sv == 2 ? 0 : sv + 1));
.LBB0_1905:
	s_lshl_b32 s1, s1, 8
	s_add_u32 s27, s2, s1
	s_addc_u32 s28, s3, 0
	s_mul_i32 s1, s28, 0x600
	s_mul_hi_u32 s2, s27, 0x600
	s_add_i32 s2, s2, s1
	s_mul_i32 s1, s27, 0x600
	s_add_u32 s1, s56, s1
	s_addc_u32 s3, s57, s2
	s_mul_i32 s2, s26, 0xc0
	v_lshlrev_b32_e32 v0, 9, v142
	s_add_u32 s2, s1, s2
	v_and_b32_e32 v0, 0x7800, v0
	s_addc_u32 s3, s3, 0
	v_lshl_or_b32 v80, s15, 15, v0
	s_ashr_i32 s1, s34, 3
	v_lshl_add_u64 v[0:1], s[40:41], 0, v[80:81]
	s_and_b32 s40, s1, 0xffffffe0
	v_lshlrev_b32_e32 v143, 3, v32
	s_ashr_i32 s41, s40, 31
	v_and_b32_e32 v33, 24, v143
	v_lshl_add_u64 v[0:1], s[40:41], 1, v[0:1]
	v_lshlrev_b32_e32 v80, 1, v33
	s_cmp_lg_u32 0, -1
	v_and_b32_e32 v144, 31, v32
	v_lshl_add_u64 v[0:1], v[0:1], 0, v[80:81]
	s_cselect_b32 s1, 0, 0
	s_lshl_b32 s24, s25, 5
	v_lshrrev_b32_e32 v145, 5, v142
	v_lshl_add_u64 v[38:39], v[0:1], 0, s[80:81]
	v_or_b32_e32 v2, s24, v144
	v_mov_b64_e32 v[0:1], s[2:3]
	s_add_i32 s1, s1, s0
	v_mad_i64_i32 v[0:1], s[2:3], v2, s91, v[0:1]
	v_lshlrev_b32_e32 v80, 4, v145
	s_add_i32 s48, s1, 0x6000
	s_mov_b32 s15, m0
	s_mov_b32 m0, s48
	s_nop 0
	global_load_lds_dwordx4 v[38:39], off
	s_mov_b32 m0, s15
	v_lshl_add_u64 v[0:1], v[0:1], 0, v[80:81]
	global_load_dwordx4 v[82:85], v[0:1], off
	global_load_dwordx4 v[86:89], v[0:1], off offset:32
	global_load_dwordx4 v[90:93], v[0:1], off offset:64
	global_load_dwordx4 v[94:97], v[0:1], off offset:96
	global_load_dwordx4 v[98:101], v[0:1], off offset:128
	global_load_dwordx4 v[102:105], v[0:1], off offset:160
	v_lshl_add_u64 v[0:1], v[34:35], 0, s[6:7]
	s_mov_b32 s2, m0
	s_add_i32 s1, s30, 0x3000
	s_mov_b32 m0, s1
	s_nop 0
	global_load_lds_dwordx4 v[0:1], off
	v_lshl_add_u64 v[0:1], v[38:39], 0, s[6:7]
	s_add_i32 s1, s48, 0x2000
	s_mov_b32 m0, s1
	s_nop 0
	global_load_lds_dwordx4 v[0:1], off
	v_cndmask_b32_e64 v0, 0, 1, s[42:43]
	v_cmp_ne_u32_e64 s[40:41], 1, v0
	s_andn2_b64 vcc, exec, s[42:43]
	s_cbranch_vccnz .Lmla_p1
	v_lshl_add_u64 v[0:1], v[36:37], 0, s[86:87]
	s_add_i32 s1, s31, 0x3000
	s_mov_b32 m0, s1
	s_nop 0
	global_load_lds_dwordx4 v[0:1], off
	s_waitcnt vmcnt(3) lgkmcnt(0)
	s_branch .Lmla_p2
.Lmla_p1:
	s_waitcnt vmcnt(2) lgkmcnt(0)
.Lmla_p2:
	s_barrier
	s_mov_b64 s[0:1], 0x40000
	v_lshl_add_u64 v[0:1], v[34:35], 0, s[0:1]
	s_add_i32 s12, s30, 0x14800
	s_mov_b32 m0, s12
	s_nop 0
	global_load_lds_dwordx4 v[0:1], off
	v_lshl_add_u64 v[0:1], v[38:39], 0, s[0:1]
	s_add_i32 s12, s48, 0x4000
	s_mov_b32 m0, s12
	s_nop 0
	global_load_lds_dwordx4 v[0:1], off
	s_andn2_b64 vcc, exec, s[42:43]
	s_cbranch_vccnz .LBB0_1907
	s_mov_b64 s[0:1], 0x2000
	v_lshl_add_u64 v[0:1], v[36:37], 0, s[0:1]
	s_add_i32 s12, s31, 0x14800
	s_mov_b32 m0, s12
	s_nop 0
	global_load_lds_dwordx4 v[0:1], off
; template <int MODE> __device__ __forceinline__ void attn_unit(const Unit& a, char* shm) {
;     ...
;             const lds_cptr kp = shm3 + LDS_K + s * KSLOT + hi * 1024 + r32 * 16;
;             f32x16 p0 = negm, p1 = negm;
; #pragma unroll
;             for (int d0 = 0; d0 < ND; ++d0) {
;                 const bf16x8 b0 = *(const LAS bf16x8*)(kp + d0 * 2048), b1 = *(const LAS bf16x8*)(kp + d0 * 2048 + 512);
;                 p0 = __builtin_amdgcn_mfma_f32_32x32x16_bf16(b0, qr[d0], p0, 0, 0, 0);
;                 p1 = __builtin_amdgcn_mfma_f32_32x32x16_bf16(b1, qr[d0], p1, 0, 0, 0);
;             }
;             if (MODE == 1) {
; #pragma unroll
;                 for (int r = 0; r < 16; ++r) { const int ks = 64 * t + crow(r, hi); const int r0 = abs(tq - ks), r1 = abs(tq - ks - 32);
;                     p0[r] = (r0 <= 128) ? p0[r] - a.slope2 * (float)r0 : -INFINITY; p1[r] = (r1 <= 128) ? p1[r] - a.slope2 * (float)r1 : -INFINITY; }
;             }
;     ...
;             float ra = MX3(p0[0], p0[1], p1[0]), rb = MX3(p0[2], p0[3], p1[1]); ra = MX3(ra, p1[2], p1[3]);
; #pragma unroll
;             for (int r = 4; r < 16; r += 4) { ra = MX3(ra, p0[r], p0[r + 1]); rb = MX3(rb, p0[r + 2], p0[r + 3]); ra = MX3(ra, p1[r], p1[r + 1]); rb = MX3(rb, p1[r + 2], p1[r + 3]); }
;     ...
;             float rm = halfmax(__builtin_fmaxf(ra, rb));
;             const bool first = (MODE == 0) && (t == a.t_lo);
;             if (first || __any(rm > THR)) {
;                 const float dl = first ? rm : fmaxf(rm, 0.f);
;                 mhat += dl;
; #pragma unroll
;                 for (int r = 0; r < 16; ++r) { p0[r] -= dl; p1[r] -= dl; negm[r] = -mhat; }
;                 if (!first) {
;                     const float f = __builtin_amdgcn_exp2f(-dl); l_reg *= f;
;                     if (hi == 0) wsf[r32] = f;
; #pragma unroll
;                     for (int r = 0; r < 16; ++r) { const float fr_ = wsf[crow(r, hi)]; o[0][r] *= fr_; o[1][r] *= fr_; }
;                 }
;             }
; #pragma unroll
;             for (int r = 0; r < 16; ++r) { p0[r] = __builtin_amdgcn_exp2f(p0[r]); p1[r] = __builtin_amdgcn_exp2f(p1[r]); }
;             f32x2 s2a = (f32x2){p0[0], p0[1]}, s2b = (f32x2){p1[0], p1[1]};
; #pragma unroll
;             for (int k2 = 1; k2 < 8; ++k2) { s2a += (f32x2){p0[2 * k2], p0[2 * k2 + 1]}; s2b += (f32x2){p1[2 * k2], p1[2 * k2 + 1]}; }
;             s2a += s2b;
.LBB0_1907:
	s_mov_b32 m0, s2
	s_cmpk_gt_u32 s34, 0xff
	s_cselect_b64 s[2:3], -1, 0
	s_cmpk_lt_u32 s34, 0x100
	s_cselect_b64 s[44:45], -1, 0
	v_lshlrev_b32_e32 v0, 10, v145
	v_lshlrev_b32_e32 v1, 4, v144
	v_add3_u32 v146, 0, v0, v1
	ds_read_b128 v[40:43], v146
	ds_read_b128 v[44:47], v146 offset:512
	s_mov_b32 s61, s60
	s_mov_b32 s62, s60
	s_mov_b32 s63, s60
	s_mov_b32 s64, s60
	s_mov_b32 s65, s60
	s_mov_b32 s66, s60
	s_mov_b32 s67, s60
	s_mov_b32 s68, s60
	s_mov_b32 s69, s60
	s_mov_b32 s70, s60
	s_mov_b32 s71, s60
	s_mov_b32 s72, s60
	s_mov_b32 s73, s60
	s_mov_b32 s74, s60
	s_mov_b32 s75, s60
	v_mov_b64_e32 v[0:1], s[60:61]
	v_mov_b64_e32 v[2:3], s[62:63]
	v_mov_b64_e32 v[4:5], s[64:65]
	v_mov_b64_e32 v[6:7], s[66:67]
	v_mov_b64_e32 v[8:9], s[68:69]
	v_mov_b64_e32 v[10:11], s[70:71]
	v_mov_b64_e32 v[12:13], s[72:73]
	v_mov_b64_e32 v[14:15], s[74:75]
	v_lshlrev_b32_e32 v48, 1, v32
	v_and_b32_e32 v48, 32, v48
	s_waitcnt lgkmcnt(0)
	v_mfma_f32_32x32x16_bf16 v[16:31], v[40:43], v[82:85], v[0:15]
	v_lshlrev_b32_e32 v32, 4, v32
	v_add3_u32 v33, 0, v48, v33
	v_and_b32_e32 v32, 0xc0, v32
	s_and_b64 vcc, exec, s[2:3]
	v_mfma_f32_32x32x16_bf16 v[0:15], v[44:47], v[82:85], v[0:15]
	ds_read_b128 v[40:43], v146 offset:2048
	ds_read_b128 v[44:47], v146 offset:2560
	s_waitcnt lgkmcnt(1)
	v_mfma_f32_32x32x16_bf16 v[16:31], v[40:43], v[86:89], v[16:31]
	s_waitcnt lgkmcnt(0)
	v_mfma_f32_32x32x16_bf16 v[0:15], v[44:47], v[86:89], v[0:15]
	ds_read_b128 v[40:43], v146 offset:4096
	ds_read_b128 v[44:47], v146 offset:4608
	s_waitcnt lgkmcnt(1)
	v_mfma_f32_32x32x16_bf16 v[16:31], v[40:43], v[90:93], v[16:31]
	s_waitcnt lgkmcnt(0)
	v_mfma_f32_32x32x16_bf16 v[0:15], v[44:47], v[90:93], v[0:15]
	ds_read_b128 v[40:43], v146 offset:6144
	ds_read_b128 v[44:47], v146 offset:6656
	s_waitcnt lgkmcnt(1)
	v_mfma_f32_32x32x16_bf16 v[16:31], v[40:43], v[94:97], v[16:31]
	s_waitcnt lgkmcnt(0)
	v_mfma_f32_32x32x16_bf16 v[0:15], v[44:47], v[94:97], v[0:15]
	ds_read_b128 v[40:43], v146 offset:8192
	ds_read_b128 v[44:47], v146 offset:8704
	s_waitcnt lgkmcnt(1)
	v_mfma_f32_32x32x16_bf16 v[16:31], v[40:43], v[98:101], v[16:31]
	s_waitcnt lgkmcnt(0)
	v_mfma_f32_32x32x16_bf16 v[0:15], v[44:47], v[98:101], v[0:15]
	ds_read_b128 v[40:43], v146 offset:10240
	ds_read_b128 v[44:47], v146 offset:10752
	s_waitcnt lgkmcnt(1)
	v_mfma_f32_32x32x16_bf16 v[16:31], v[40:43], v[102:105], v[16:31]
	v_lshlrev_b32_e32 v40, 8, v145
	v_add3_u32 v147, v33, v40, v32
	s_waitcnt lgkmcnt(0)
	v_mfma_f32_32x32x16_bf16 v[0:15], v[44:47], v[102:105], v[0:15]
	s_nop 7
	v_max_f32_e32 v32, v17, v17
	v_max_f32_e32 v33, v16, v16
	v_max_f32_e32 v32, v33, v32
	s_nop 0
	v_max3_f32 v33, v18, v19, v1
	v_max3_f32 v32, v32, v0, v2
	v_max3_f32 v32, v32, v3, v20
	v_max3_f32 v33, v33, v22, v23
	v_max3_f32 v32, v32, v21, v4
	v_max3_f32 v33, v33, v6, v7
	v_max3_f32 v32, v32, v5, v24
	v_max3_f32 v33, v33, v26, v27
	v_max3_f32 v32, v32, v25, v8
	v_max3_f32 v33, v33, v10, v11
	v_max3_f32 v32, v32, v9, v28
	v_max3_f32 v33, v33, v30, v31
	v_max3_f32 v32, v32, v29, v12
	v_max3_f32 v33, v33, v14, v15
	v_max3_f32 v32, v32, v13, v33
	v_mov_b32_e32 v33, v32
	s_nop 1
	v_permlane32_swap_b32_e32 v32, v33
	v_max_f32_e32 v33, v33, v33
	v_max_f32_e32 v32, v32, v32
	v_max_f32_e32 v32, v32, v33
	v_sub_f32_e32 v16, v16, v32
	v_sub_f32_e32 v0, v0, v32
	v_sub_f32_e32 v17, v17, v32
	v_sub_f32_e32 v1, v1, v32
	v_sub_f32_e32 v18, v18, v32
	v_sub_f32_e32 v2, v2, v32
	v_sub_f32_e32 v19, v19, v32
	v_sub_f32_e32 v3, v3, v32
	v_sub_f32_e32 v20, v20, v32
	v_sub_f32_e32 v4, v4, v32
	v_sub_f32_e32 v21, v21, v32
	v_sub_f32_e32 v5, v5, v32
	v_sub_f32_e32 v22, v22, v32
	v_sub_f32_e32 v6, v6, v32
	v_sub_f32_e32 v23, v23, v32
	v_sub_f32_e32 v7, v7, v32
	v_sub_f32_e32 v24, v24, v32
	v_sub_f32_e32 v8, v8, v32
	v_sub_f32_e32 v25, v25, v32
	v_sub_f32_e32 v9, v9, v32
	v_sub_f32_e32 v26, v26, v32
	v_sub_f32_e32 v10, v10, v32
	v_sub_f32_e32 v27, v27, v32
	v_sub_f32_e32 v11, v11, v32
	v_sub_f32_e32 v28, v28, v32
	v_sub_f32_e32 v12, v12, v32
	v_sub_f32_e32 v29, v29, v32
	v_sub_f32_e32 v13, v13, v32
	v_sub_f32_e32 v30, v30, v32
	v_sub_f32_e32 v14, v14, v32
	v_sub_f32_e32 v31, v31, v32
	v_sub_f32_e32 v15, v15, v32
	v_exp_f32_e32 v106, v16
	v_exp_f32_e32 v74, v0
	v_exp_f32_e32 v107, v17
	v_exp_f32_e32 v75, v1
	v_exp_f32_e32 v112, v18
	v_exp_f32_e32 v110, v2
	v_exp_f32_e32 v113, v19
	v_exp_f32_e32 v111, v3
	v_exp_f32_e32 v108, v20
	v_exp_f32_e32 v78, v4
	v_exp_f32_e32 v109, v21
	v_exp_f32_e32 v79, v5
	v_exp_f32_e32 v76, v22
	v_exp_f32_e32 v72, v6
	v_exp_f32_e32 v77, v23
	v_exp_f32_e32 v73, v7
	v_exp_f32_e32 v70, v24
	v_exp_f32_e32 v68, v8
	v_exp_f32_e32 v71, v25
	v_exp_f32_e32 v69, v9
	v_exp_f32_e32 v66, v26
	v_exp_f32_e32 v64, v10
	v_exp_f32_e32 v67, v27
	v_exp_f32_e32 v65, v11
	v_exp_f32_e32 v46, v28
	v_exp_f32_e32 v44, v12
	v_exp_f32_e32 v47, v29
	v_exp_f32_e32 v45, v13
	v_exp_f32_e32 v42, v30
	v_exp_f32_e32 v40, v14
	v_exp_f32_e32 v43, v31
	v_exp_f32_e32 v41, v15
	v_mov_b32_e32 v0, 0
	v_mov_b32_e32 v1, 0
	v_mov_b32_e32 v2, 0
	v_mov_b32_e32 v3, 0
	v_mov_b32_e32 v4, 0
	v_mov_b32_e32 v5, 0
	v_mov_b32_e32 v6, 0
	v_mov_b32_e32 v7, 0
	v_mov_b32_e32 v8, 0
	v_mov_b32_e32 v9, 0
	v_mov_b32_e32 v10, 0
	v_mov_b32_e32 v11, 0
	v_mov_b32_e32 v12, 0
	v_mov_b32_e32 v13, 0
	v_mov_b32_e32 v14, 0
	v_mov_b32_e32 v15, 0
	v_mov_b32_e32 v16, 0
	v_mov_b32_e32 v17, 0
	v_mov_b32_e32 v18, 0
	v_mov_b32_e32 v19, 0
	v_mov_b32_e32 v20, 0
	v_mov_b32_e32 v21, 0
	v_mov_b32_e32 v22, 0
	v_mov_b32_e32 v23, 0
	v_mov_b32_e32 v24, 0
	v_mov_b32_e32 v25, 0
	v_mov_b32_e32 v26, 0
	v_mov_b32_e32 v27, 0
	v_mov_b32_e32 v28, 0
	v_mov_b32_e32 v29, 0
	v_mov_b32_e32 v30, 0
	v_mov_b32_e32 v31, 0
	v_cvt_pk_bf16_f32 v60, v106, v107
	v_cvt_pk_bf16_f32 v56, v70, v71
	v_cvt_pk_bf16_f32 v52, v74, v75
	v_cvt_pk_bf16_f32 v48, v68, v69
	v_cvt_pk_bf16_f32 v61, v112, v113
	v_cvt_pk_bf16_f32 v57, v66, v67
	v_cvt_pk_bf16_f32 v53, v110, v111
	v_cvt_pk_bf16_f32 v49, v64, v65
	v_cvt_pk_bf16_f32 v62, v108, v109
	v_cvt_pk_bf16_f32 v58, v46, v47
	v_cvt_pk_bf16_f32 v54, v78, v79
	v_cvt_pk_bf16_f32 v50, v44, v45
	v_cvt_pk_bf16_f32 v63, v76, v77
	v_cvt_pk_bf16_f32 v59, v42, v43
	v_cvt_pk_bf16_f32 v55, v72, v73
	v_cvt_pk_bf16_f32 v51, v40, v41
	s_cbranch_vccz .Lmla_apv0
	ds_read_b64_tr_b16 v[230:231], v147 offset:24576
	ds_read_b64_tr_b16 v[232:233], v147 offset:25088
	ds_read_b64_tr_b16 v[234:235], v147 offset:25600
	ds_read_b64_tr_b16 v[236:237], v147 offset:26112
	ds_read_b64_tr_b16 v[238:239], v147 offset:26624
	ds_read_b64_tr_b16 v[240:241], v147 offset:27136
	ds_read_b64_tr_b16 v[242:243], v147 offset:27648
	ds_read_b64_tr_b16 v[244:245], v147 offset:28160
	ds_read_b64_tr_b16 v[246:247], v147 offset:28672
	ds_read_b64_tr_b16 v[248:249], v147 offset:29184
	ds_read_b64_tr_b16 v[150:151], v147 offset:29696
	ds_read_b64_tr_b16 v[152:153], v147 offset:30208
	ds_read_b64_tr_b16 v[154:155], v147 offset:30720
	ds_read_b64_tr_b16 v[156:157], v147 offset:31232
	ds_read_b64_tr_b16 v[158:159], v147 offset:31744
	ds_read_b64_tr_b16 v[160:161], v147 offset:32256
	s_branch .LBB0_1909

; #define ATT_DMA(t, sk, sv) do { glds16(ksrc + (long)(t) * 64 * a.ldk, (unsigned)__builtin_amdgcn_readfirstlane(kdst + (sk) * KSLOT)); \
;         if (MODE == 0 && wid < 4) glds16(kpsrc + (long)(t) * 64 * 32, (unsigned)__builtin_amdgcn_readfirstlane(kpdst + (sk) * KSLOT)); \
;         glds16(vsrc + (long)(t) * 64 * a.ldv, (unsigned)__builtin_amdgcn_readfirstlane(vdst + (sv) * VSLOT)); } while (0)
; #define ATT_WAIT_BAR() asm volatile("s_waitcnt vmcnt(0) lgkmcnt(0)\n\ts_barrier" ::: "memory")
; template <int MODE> __device__ __forceinline__ void attn_unit(const Unit& a, char* shm) {
;     ...
;     for (int t = a.t_lo; t < a.t_hi; ++t) {
;         const int s = (t - a.t_lo) & 1;
;         ATT_WAIT_BAR();
;         if (t + 1 < a.t_hi) ATT_DMA(t + 1, s ^ 1, (sv == 2 ? 0 : sv + 1));
;     ...
;             f32x2 s2a = (f32x2){p0[0], p0[1]}, s2b = (f32x2){p1[0], p1[1]};
; #pragma unroll
;             for (int k2 = 1; k2 < 8; ++k2) { s2a += (f32x2){p0[2 * k2], p0[2 * k2 + 1]}; s2b += (f32x2){p1[2 * k2], p1[2 * k2 + 1]}; }
;             s2a += s2b;
;             l_reg += s2a.x + s2a.y;
.LBB0_1909:
	v_pk_add_f32 v[106:107], v[106:107], v[112:113]
	v_pk_add_f32 v[74:75], v[74:75], v[110:111]
	v_pk_add_f32 v[106:107], v[108:109], v[106:107]
	v_pk_add_f32 v[74:75], v[78:79], v[74:75]
	v_pk_add_f32 v[76:77], v[76:77], v[106:107]
	v_pk_add_f32 v[72:73], v[72:73], v[74:75]
	v_pk_add_f32 v[70:71], v[70:71], v[76:77]
	v_pk_add_f32 v[68:69], v[68:69], v[72:73]
	v_pk_add_f32 v[66:67], v[66:67], v[70:71]
	v_pk_add_f32 v[64:65], v[64:65], v[68:69]
	v_pk_add_f32 v[46:47], v[46:47], v[66:67]
	v_pk_add_f32 v[44:45], v[44:45], v[64:65]
	v_pk_add_f32 v[42:43], v[42:43], v[46:47]
	v_pk_add_f32 v[40:41], v[40:41], v[44:45]
	s_and_b32 s0, s34, 0x3fffffc0
	v_pk_add_f32 v[40:41], v[42:43], v[40:41]
	s_lshl_b32 s0, s0, 2
	v_pk_add_f32 v[40:41], v[40:41], v[40:41] op_sel_hi:[0,1]
	v_mov_b32_e32 v33, v41
	v_pk_add_f32 v[112:113], v[32:33], 0 op_sel_hi:[1,0]
	s_add_i32 s49, s0, 0
	s_mov_b64 s[0:1], 0x60000
	v_pk_add_f32 v[32:33], v[112:113], 0 neg_lo:[1,1] neg_hi:[1,1]
	v_lshl_add_u64 v[106:107], v[38:39], 0, s[0:1]
	v_lshl_add_u64 v[108:109], v[34:35], 0, s[0:1]
	s_mov_b64 s[0:1], 0x3000
	v_readlane_b32 s74, v255, 8
	v_cmp_gt_u32_e64 s[42:43], 32, v142
	v_lshl_add_u32 v148, v144, 2, s49
	v_lshl_add_u64 v[110:111], v[36:37], 0, s[0:1]
	s_mov_b32 s35, 0
	s_mov_b32 s0, 1
	s_mov_b32 s50, 1
	v_mov_b32_e32 v33, v32
	v_mov_b32_e32 v34, v32
	v_mov_b32_e32 v35, v32
	v_mov_b32_e32 v36, v32
	v_mov_b32_e32 v37, v32
	v_mov_b32_e32 v38, v32
	v_mov_b32_e32 v39, v32
	v_mov_b32_e32 v40, v32
	v_mov_b32_e32 v41, v32
	v_mov_b32_e32 v42, v32
	v_mov_b32_e32 v43, v32
	v_mov_b32_e32 v44, v32
	v_mov_b32_e32 v45, v32
	v_mov_b32_e32 v46, v32
	v_mov_b32_e32 v47, v32
	v_readlane_b32 s75, v255, 9
.LBB0_1910:
	s_add_i32 s50, s50, 1
	s_mov_b32 s51, s0
	s_and_b64 vcc, exec, s[40:41]
	s_cbranch_vccnz .Lmla_w2
	s_waitcnt vmcnt(3) lgkmcnt(0)
	s_branch .Lmla_wd

; #define LAS __attribute__((address_space(3)))
; __device__ __forceinline__ int crow(int r, int hi) { return (r & 3) + 8 * (r >> 2) + 4 * hi; }
; __device__ __forceinline__ float halfmax(float m) { auto rr = __builtin_amdgcn_permlane32_swap(__float_as_uint(m), __float_as_uint(m), false, false); return fmaxf(__uint_as_float(rr[0]), __uint_as_float(rr[1])); }
; #define ATT_DMA(t, sk, sv) do { glds16(ksrc + (long)(t) * 64 * a.ldk, (unsigned)__builtin_amdgcn_readfirstlane(kdst + (sk) * KSLOT)); \
;         if (MODE == 0 && wid < 4) glds16(kpsrc + (long)(t) * 64 * 32, (unsigned)__builtin_amdgcn_readfirstlane(kpdst + (sk) * KSLOT)); \
;         glds16(vsrc + (long)(t) * 64 * a.ldv, (unsigned)__builtin_amdgcn_readfirstlane(vdst + (sv) * VSLOT)); } while (0)
; template <int MODE> __device__ __forceinline__ void attn_unit(const Unit& a, char* shm) {
;     ...
;         if (t + 1 < a.t_hi) ATT_DMA(t + 1, s ^ 1, (sv == 2 ? 0 : sv + 1));
;         if (pend) { ATT_PV(pw, svp); pend = false; }
;         bool active = true;
;         if (MODE == 1) active = (64 * t + 63 >= tq0 - 128) && (64 * t <= tq0 + 31 + 128);
;         if (active) {
;             const lds_cptr kp = shm3 + LDS_K + s * KSLOT + hi * 1024 + r32 * 16;
;             f32x16 p0 = negm, p1 = negm;
; #pragma unroll
;             for (int d0 = 0; d0 < ND; ++d0) {
;                 const bf16x8 b0 = *(const LAS bf16x8*)(kp + d0 * 2048), b1 = *(const LAS bf16x8*)(kp + d0 * 2048 + 512);
;                 p0 = __builtin_amdgcn_mfma_f32_32x32x16_bf16(b0, qr[d0], p0, 0, 0, 0);
;                 p1 = __builtin_amdgcn_mfma_f32_32x32x16_bf16(b1, qr[d0], p1, 0, 0, 0);
;             }
;             if (MODE == 1) {
; #pragma unroll
;                 for (int r = 0; r < 16; ++r) { const int ks = 64 * t + crow(r, hi); const int r0 = abs(tq - ks), r1 = abs(tq - ks - 32);
;                     p0[r] = (r0 <= 128) ? p0[r] - a.slope2 * (float)r0 : -INFINITY; p1[r] = (r1 <= 128) ? p1[r] - a.slope2 * (float)r1 : -INFINITY; }
;             }
;     ...
;             float ra = MX3(p0[0], p0[1], p1[0]), rb = MX3(p0[2], p0[3], p1[1]); ra = MX3(ra, p1[2], p1[3]);
; #pragma unroll
;             for (int r = 4; r < 16; r += 4) { ra = MX3(ra, p0[r], p0[r + 1]); rb = MX3(rb, p0[r + 2], p0[r + 3]); ra = MX3(ra, p1[r], p1[r + 1]); rb = MX3(rb, p1[r + 2], p1[r + 3]); }
;     ...
;             float rm = halfmax(__builtin_fmaxf(ra, rb));
.Lmla_wd:
	s_barrier
	s_mov_b32 s34, s51
	s_mulk_i32 s34, 0x3000
	s_cmp_eq_u32 s51, 2
	s_cselect_b32 s34, 0x14800, s34
	v_add_u32_e32 v118, s34, v146
	ds_read_b128 v[182:185], v118
	ds_read_b128 v[186:189], v118 offset:512
	ds_read_b128 v[190:193], v118 offset:2048
	ds_read_b128 v[194:197], v118 offset:2560
	ds_read_b128 v[198:201], v118 offset:4096
	ds_read_b128 v[202:205], v118 offset:4608
	ds_read_b128 v[206:209], v118 offset:6144
	ds_read_b128 v[210:213], v118 offset:6656
	ds_read_b128 v[214:217], v118 offset:8192
	ds_read_b128 v[218:221], v118 offset:8704
	ds_read_b128 v[222:225], v118 offset:10240
	ds_read_b128 v[226:229], v118 offset:10752
	v_lshl_add_u32 v149, s51, 13, v147
	s_mov_b32 s12, m0
	s_add_i32 s35, s51, -1
	s_cmp_eq_u32 s51, 0
	s_cselect_b32 s35, 2, s35
	s_mul_i32 s0, s35, 0x3000
	s_cmp_eq_u32 s35, 2
	s_cselect_b32 s0, 0x14800, s0
	s_andn2_b64 vcc, exec, s[2:3]
	s_cbranch_vccnz .Lmla_aprio
	v_mfma_f32_32x32x16_bf16 v[0:15], v[60:63], v[230:233], v[0:15]
	v_mfma_f32_32x32x16_bf16 v[0:15], v[56:59], v[234:237], v[0:15]
	v_mfma_f32_32x32x16_bf16 v[0:15], v[52:55], v[238:241], v[0:15]
	v_mfma_f32_32x32x16_bf16 v[0:15], v[48:51], v[242:245], v[0:15]
	v_mfma_f32_32x32x16_bf16 v[16:31], v[60:63], v[246:249], v[16:31]
	v_mfma_f32_32x32x16_bf16 v[16:31], v[56:59], v[150:153], v[16:31]
	v_mfma_f32_32x32x16_bf16 v[16:31], v[52:55], v[154:157], v[16:31]
	v_mfma_f32_32x32x16_bf16 v[16:31], v[48:51], v[158:161], v[16:31]
	s_branch .LBB0_1916
.Lmla_aprio:
	s_setprio 1
.LBB0_1916:
	s_waitcnt lgkmcnt(11)
	v_mfma_f32_32x32x16_bf16 v[48:63], v[182:185], v[82:85], v[32:47]
	s_add_i32 s1, s0, s30
	s_mov_b32 m0, s1
	s_nop 0
	global_load_lds_dwordx4 v[108:109], off
	s_waitcnt lgkmcnt(10)
	v_mfma_f32_32x32x16_bf16 v[64:79], v[186:189], v[82:85], v[32:47]
	s_and_b64 vcc, exec, s[40:41]
	s_cbranch_vccnz .Lmla_nokpe
	s_add_i32 s1, s0, s31
	s_mov_b32 m0, s1
	s_nop 0
	global_load_lds_dwordx4 v[110:111], off
.Lmla_nokpe:
	s_waitcnt lgkmcnt(9)
	v_mfma_f32_32x32x16_bf16 v[48:63], v[190:193], v[86:89], v[48:63]
	s_lshl_b32 s0, s35, 13
	s_add_i32 s1, s0, s48
	s_mov_b32 m0, s1
	s_nop 0
	global_load_lds_dwordx4 v[106:107], off
	s_mov_b32 m0, s12
	s_waitcnt lgkmcnt(8)
	v_mfma_f32_32x32x16_bf16 v[64:79], v[194:197], v[86:89], v[64:79]
	s_waitcnt lgkmcnt(7)
	v_mfma_f32_32x32x16_bf16 v[48:63], v[198:201], v[90:93], v[48:63]
	s_waitcnt lgkmcnt(6)
	v_mfma_f32_32x32x16_bf16 v[64:79], v[202:205], v[90:93], v[64:79]
	s_waitcnt lgkmcnt(5)
	v_mfma_f32_32x32x16_bf16 v[48:63], v[206:209], v[94:97], v[48:63]
	s_waitcnt lgkmcnt(4)
	v_mfma_f32_32x32x16_bf16 v[64:79], v[210:213], v[94:97], v[64:79]
	s_waitcnt lgkmcnt(3)
	v_mfma_f32_32x32x16_bf16 v[48:63], v[214:217], v[98:101], v[48:63]
	s_waitcnt lgkmcnt(2)
	v_mfma_f32_32x32x16_bf16 v[64:79], v[218:221], v[98:101], v[64:79]
	s_waitcnt lgkmcnt(1)
	v_mfma_f32_32x32x16_bf16 v[48:63], v[222:225], v[102:105], v[48:63]
	s_waitcnt lgkmcnt(0)
	v_mfma_f32_32x32x16_bf16 v[64:79], v[226:229], v[102:105], v[64:79]
	s_setprio 0
	ds_read_b64_tr_b16 v[230:231], v149 offset:24576
	ds_read_b64_tr_b16 v[232:233], v149 offset:25088
	ds_read_b64_tr_b16 v[234:235], v149 offset:25600
	ds_read_b64_tr_b16 v[236:237], v149 offset:26112
	ds_read_b64_tr_b16 v[238:239], v149 offset:26624
	ds_read_b64_tr_b16 v[240:241], v149 offset:27136
	ds_read_b64_tr_b16 v[242:243], v149 offset:27648
	ds_read_b64_tr_b16 v[244:245], v149 offset:28160
	ds_read_b64_tr_b16 v[246:247], v149 offset:28672
	ds_read_b64_tr_b16 v[248:249], v149 offset:29184
	ds_read_b64_tr_b16 v[150:151], v149 offset:29696
	ds_read_b64_tr_b16 v[152:153], v149 offset:30208
	ds_read_b64_tr_b16 v[154:155], v149 offset:30720
	ds_read_b64_tr_b16 v[156:157], v149 offset:31232
	v_max_f32_e32 v118, v49, v49
	v_max_f32_e32 v119, v48, v48
	v_max_f32_e32 v118, v119, v118
	v_max3_f32 v114, v50, v51, v65
	v_max3_f32 v115, v118, v64, v66
	v_max3_f32 v115, v115, v67, v52
	v_max3_f32 v114, v114, v54, v55
	v_max3_f32 v115, v115, v53, v68
	v_max3_f32 v114, v114, v70, v71
	v_max3_f32 v115, v115, v69, v56
	v_max3_f32 v114, v114, v58, v59
	v_max3_f32 v115, v115, v57, v72
	v_max3_f32 v114, v114, v74, v75
	v_max3_f32 v115, v115, v73, v60
	v_max3_f32 v114, v114, v62, v63
	v_max3_f32 v115, v115, v61, v76
	v_max3_f32 v114, v114, v78, v79
	v_max3_f32 v114, v115, v77, v114
	v_mov_b32_e32 v115, v114
	s_nop 1
	v_permlane32_swap_b32_e32 v114, v115
	v_max_f32_e32 v115, v115, v115
	v_max_f32_e32 v114, v114, v114
	v_max_f32_e32 v114, v114, v115
	v_cmp_lt_f32_e32 vcc, s19, v114
	s_cbranch_vccz .LBB0_1920
; __device__ __forceinline__ int crow(int r, int hi) { return (r & 3) + 8 * (r >> 2) + 4 * hi; }
; template <int MODE> __device__ __forceinline__ void attn_unit(const Unit& a, char* shm) {
;     ...
;             if (first || __any(rm > THR)) {
;                 const float dl = first ? rm : fmaxf(rm, 0.f);
;                 mhat += dl;
; #pragma unroll
;                 for (int r = 0; r < 16; ++r) { p0[r] -= dl; p1[r] -= dl; negm[r] = -mhat; }
;                 if (!first) {
;                     const float f = __builtin_amdgcn_exp2f(-dl); l_reg *= f;
;                     if (hi == 0) wsf[r32] = f;
; #pragma unroll
;                     for (int r = 0; r < 16; ++r) { const float fr_ = wsf[crow(r, hi)]; o[0][r] *= fr_; o[1][r] *= fr_; }
;                 }
	v_max_f32_e32 v32, v114, v114
	v_max_f32_e32 v32, 0, v32
	v_exp_f32_e64 v33, -v32
	s_and_saveexec_b64 s[46:47], s[42:43]
	ds_write_b32 v148, v33 offset:49152
	s_or_b64 exec, exec, s[46:47]
	v_pk_add_f32 v[114:115], v[112:113], v[32:33]
	v_pk_mul_f32 v[40:41], v[112:113], v[32:33]
	v_add_u32_e32 v44, s49, v80
	v_pk_add_f32 v[48:49], v[48:49], v[32:33] op_sel_hi:[1,0] neg_lo:[0,1] neg_hi:[0,1]
	v_pk_add_f32 v[64:65], v[64:65], v[32:33] op_sel_hi:[1,0] neg_lo:[0,1] neg_hi:[0,1]
	v_pk_add_f32 v[50:51], v[50:51], v[32:33] op_sel_hi:[1,0] neg_lo:[0,1] neg_hi:[0,1]
	v_pk_add_f32 v[66:67], v[66:67], v[32:33] op_sel_hi:[1,0] neg_lo:[0,1] neg_hi:[0,1]
	v_pk_add_f32 v[52:53], v[52:53], v[32:33] op_sel_hi:[1,0] neg_lo:[0,1] neg_hi:[0,1]
	v_pk_add_f32 v[68:69], v[68:69], v[32:33] op_sel_hi:[1,0] neg_lo:[0,1] neg_hi:[0,1]
	v_pk_add_f32 v[54:55], v[54:55], v[32:33] op_sel_hi:[1,0] neg_lo:[0,1] neg_hi:[0,1]
	v_pk_add_f32 v[70:71], v[70:71], v[32:33] op_sel_hi:[1,0] neg_lo:[0,1] neg_hi:[0,1]
	v_pk_add_f32 v[56:57], v[56:57], v[32:33] op_sel_hi:[1,0] neg_lo:[0,1] neg_hi:[0,1]
	v_pk_add_f32 v[72:73], v[72:73], v[32:33] op_sel_hi:[1,0] neg_lo:[0,1] neg_hi:[0,1]
	v_pk_add_f32 v[58:59], v[58:59], v[32:33] op_sel_hi:[1,0] neg_lo:[0,1] neg_hi:[0,1]
	v_pk_add_f32 v[74:75], v[74:75], v[32:33] op_sel_hi:[1,0] neg_lo:[0,1] neg_hi:[0,1]
	v_pk_add_f32 v[60:61], v[60:61], v[32:33] op_sel_hi:[1,0] neg_lo:[0,1] neg_hi:[0,1]
	v_pk_add_f32 v[76:77], v[76:77], v[32:33] op_sel_hi:[1,0] neg_lo:[0,1] neg_hi:[0,1]
	v_pk_add_f32 v[62:63], v[62:63], v[32:33] op_sel_hi:[1,0] neg_lo:[0,1] neg_hi:[0,1]
	v_pk_add_f32 v[78:79], v[78:79], v[32:33] op_sel_hi:[1,0] neg_lo:[0,1] neg_hi:[0,1]
	ds_read_b128 v[32:35], v44 offset:49216
	ds_read_b128 v[36:39], v44 offset:49248
	v_mov_b32_e32 v115, v41
	ds_read_b128 v[40:43], v44 offset:49152
	ds_read_b128 v[116:119], v44 offset:49184
	v_pk_add_f32 v[46:47], v[114:115], 0 neg_lo:[1,1] neg_hi:[1,1]
	s_waitcnt lgkmcnt(3)
	v_pk_mul_f32 v[26:27], v[26:27], v[34:35]
	s_waitcnt lgkmcnt(2)
	v_pk_mul_f32 v[30:31], v[30:31], v[38:39]
	v_pk_mul_f32 v[28:29], v[28:29], v[36:37]
	v_pk_mul_f32 v[24:25], v[24:25], v[32:33]
	s_waitcnt lgkmcnt(0)
	v_pk_mul_f32 v[22:23], v[22:23], v[118:119]
	v_pk_mul_f32 v[20:21], v[20:21], v[116:117]
	v_pk_mul_f32 v[18:19], v[18:19], v[42:43]
	v_pk_mul_f32 v[16:17], v[16:17], v[40:41]
	v_pk_mul_f32 v[14:15], v[14:15], v[38:39]
	v_pk_mul_f32 v[12:13], v[12:13], v[36:37]
	v_pk_mul_f32 v[10:11], v[10:11], v[34:35]
	v_pk_mul_f32 v[8:9], v[8:9], v[32:33]
	v_pk_mul_f32 v[6:7], v[6:7], v[118:119]
	v_pk_mul_f32 v[4:5], v[4:5], v[116:117]
	v_pk_mul_f32 v[2:3], v[2:3], v[42:43]
	v_pk_mul_f32 v[0:1], v[0:1], v[40:41]
	v_mov_b32_e32 v47, v46
	v_mov_b32_e32 v45, v46
	v_mov_b32_e32 v44, v46
	v_mov_b32_e32 v43, v46
	v_mov_b32_e32 v42, v46
	v_mov_b32_e32 v41, v46
	v_mov_b32_e32 v40, v46
	v_mov_b32_e32 v39, v46
	v_mov_b32_e32 v38, v46
	v_mov_b32_e32 v37, v46
	v_mov_b32_e32 v36, v46
	v_mov_b32_e32 v35, v46
	v_mov_b32_e32 v34, v46
	v_mov_b32_e32 v33, v46
	v_mov_b32_e32 v32, v46
	v_mov_b64_e32 v[112:113], v[114:115]
; __device__ __forceinline__ unsigned cvt_pk_bf16(float lo, float hi) { unsigned r; asm volatile("v_cvt_pk_bf16_f32 %0, %1, %2" : "=v"(r) : "v"(lo), "v"(hi)); return r; }
; template <int MODE> __device__ __forceinline__ void attn_unit(const Unit& a, char* shm) {
;     ...
; #pragma unroll
;             for (int r = 0; r < 16; ++r) { p0[r] = __builtin_amdgcn_exp2f(p0[r]); p1[r] = __builtin_amdgcn_exp2f(p1[r]); }
;             f32x2 s2a = (f32x2){p0[0], p0[1]}, s2b = (f32x2){p1[0], p1[1]};
; #pragma unroll
;             for (int k2 = 1; k2 < 8; ++k2) { s2a += (f32x2){p0[2 * k2], p0[2 * k2 + 1]}; s2b += (f32x2){p1[2 * k2], p1[2 * k2 + 1]}; }
;             s2a += s2b;
;             l_reg += s2a.x + s2a.y;
; #pragma unroll
;             for (int kk = 0; kk < 4; ++kk) { pw[0][kk] = cvt_pk_bf16(p0[2 * kk], p0[2 * kk + 1]); pw[1][kk] = cvt_pk_bf16(p0[8 + 2 * kk], p0[8 + 2 * kk + 1]);
;                 pw[2][kk] = cvt_pk_bf16(p1[2 * kk], p1[2 * kk + 1]); pw[3][kk] = cvt_pk_bf16(p1[8 + 2 * kk], p1[8 + 2 * kk + 1]); }
;             if (g == 0) ATT_PV(pw, sv); else pend = true;
;         }
;         svp = sv; sv = (sv == 2) ? 0 : sv + 1;
.LBB0_1920:
	ds_read_b64_tr_b16 v[158:159], v149 offset:31744
	ds_read_b64_tr_b16 v[160:161], v149 offset:32256
	v_exp_f32_e32 v128, v48
	v_exp_f32_e32 v122, v64
	v_exp_f32_e32 v129, v49
	v_exp_f32_e32 v123, v65
	v_exp_f32_e32 v140, v50
	v_exp_f32_e32 v138, v66
	v_exp_f32_e32 v141, v51
	v_exp_f32_e32 v139, v67
	v_exp_f32_e32 v136, v52
	v_exp_f32_e32 v126, v68
	v_exp_f32_e32 v137, v53
	v_exp_f32_e32 v127, v69
	v_exp_f32_e32 v124, v54
	v_exp_f32_e32 v120, v70
	v_exp_f32_e32 v125, v55
	v_exp_f32_e32 v121, v71
	v_exp_f32_e32 v118, v56
	v_exp_f32_e32 v116, v72
	v_exp_f32_e32 v119, v57
	v_exp_f32_e32 v117, v73
	v_exp_f32_e32 v114, v58
	v_exp_f32_e32 v72, v74
	v_exp_f32_e32 v115, v59
	v_exp_f32_e32 v73, v75
	v_exp_f32_e32 v70, v60
	v_exp_f32_e32 v68, v76
	v_exp_f32_e32 v71, v61
	v_exp_f32_e32 v69, v77
	v_exp_f32_e32 v66, v62
	v_exp_f32_e32 v64, v78
	v_exp_f32_e32 v67, v63
	v_exp_f32_e32 v65, v79
	s_andn2_b64 vcc, exec, s[44:45]
	v_cvt_pk_bf16_f32 v60, v128, v129
	v_cvt_pk_bf16_f32 v56, v118, v119
	v_cvt_pk_bf16_f32 v52, v122, v123
	v_cvt_pk_bf16_f32 v48, v116, v117
	v_cvt_pk_bf16_f32 v61, v140, v141
	v_cvt_pk_bf16_f32 v57, v114, v115
	v_cvt_pk_bf16_f32 v53, v138, v139
	v_cvt_pk_bf16_f32 v49, v72, v73
	v_cvt_pk_bf16_f32 v62, v136, v137
	v_cvt_pk_bf16_f32 v58, v70, v71
	v_cvt_pk_bf16_f32 v54, v126, v127
	v_cvt_pk_bf16_f32 v50, v68, v69
	v_cvt_pk_bf16_f32 v63, v124, v125
	v_cvt_pk_bf16_f32 v59, v66, v67
	v_cvt_pk_bf16_f32 v55, v120, v121
	v_cvt_pk_bf16_f32 v51, v64, v65
	s_cbranch_vccnz .LBB0_1922
	s_waitcnt lgkmcnt(0)
	v_mfma_f32_32x32x16_bf16 v[0:15], v[60:63], v[230:233], v[0:15]
	v_pk_add_f32 v[74:75], v[128:129], v[140:141]
	v_pk_add_f32 v[76:77], v[122:123], v[138:139]
	v_mfma_f32_32x32x16_bf16 v[0:15], v[56:59], v[234:237], v[0:15]
	v_pk_add_f32 v[74:75], v[136:137], v[74:75]
	v_pk_add_f32 v[76:77], v[126:127], v[76:77]
	v_mfma_f32_32x32x16_bf16 v[0:15], v[52:55], v[238:241], v[0:15]
	v_pk_add_f32 v[74:75], v[124:125], v[74:75]
	v_pk_add_f32 v[76:77], v[120:121], v[76:77]
	v_mfma_f32_32x32x16_bf16 v[0:15], v[48:51], v[242:245], v[0:15]
	v_pk_add_f32 v[74:75], v[118:119], v[74:75]
	v_pk_add_f32 v[76:77], v[116:117], v[76:77]
	v_mfma_f32_32x32x16_bf16 v[16:31], v[60:63], v[246:249], v[16:31]
	v_pk_add_f32 v[74:75], v[114:115], v[74:75]
	v_pk_add_f32 v[72:73], v[72:73], v[76:77]
	v_mfma_f32_32x32x16_bf16 v[16:31], v[56:59], v[150:153], v[16:31]
	v_pk_add_f32 v[70:71], v[70:71], v[74:75]
	v_pk_add_f32 v[68:69], v[68:69], v[72:73]
	v_mfma_f32_32x32x16_bf16 v[16:31], v[52:55], v[154:157], v[16:31]
	v_pk_add_f32 v[66:67], v[66:67], v[70:71]
	v_pk_add_f32 v[64:65], v[64:65], v[68:69]
	v_mfma_f32_32x32x16_bf16 v[16:31], v[48:51], v[158:161], v[16:31]
	v_pk_add_f32 v[64:65], v[64:65], v[66:67]
	v_pk_add_f32 v[64:65], v[64:65], v[64:65] op_sel:[0,1] op_sel_hi:[1,0]
	v_pk_add_f32 v[64:65], v[112:113], v[64:65] op_sel:[1,0] op_sel_hi:[0,1]
	s_branch .Lmla_sumdone
.LBB0_1922:
	v_pk_add_f32 v[74:75], v[128:129], v[140:141]
	v_pk_add_f32 v[76:77], v[122:123], v[138:139]
	v_pk_add_f32 v[74:75], v[136:137], v[74:75]
	v_pk_add_f32 v[76:77], v[126:127], v[76:77]
	v_pk_add_f32 v[74:75], v[124:125], v[74:75]
	v_pk_add_f32 v[76:77], v[120:121], v[76:77]
	v_pk_add_f32 v[74:75], v[118:119], v[74:75]
	v_pk_add_f32 v[76:77], v[116:117], v[76:77]
	v_pk_add_f32 v[74:75], v[114:115], v[74:75]
	v_pk_add_f32 v[72:73], v[72:73], v[76:77]
	v_pk_add_f32 v[70:71], v[70:71], v[74:75]
	v_pk_add_f32 v[68:69], v[68:69], v[72:73]
	v_pk_add_f32 v[66:67], v[66:67], v[70:71]
	v_pk_add_f32 v[64:65], v[64:65], v[68:69]
	v_pk_add_f32 v[64:65], v[64:65], v[66:67]
	v_pk_add_f32 v[64:65], v[64:65], v[64:65] op_sel:[0,1] op_sel_hi:[1,0]
	v_pk_add_f32 v[64:65], v[112:113], v[64:65] op_sel:[1,0] op_sel_hi:[0,1]
.Lmla_sumdone:
	s_add_i32 s0, s51, 1
	s_cmp_lg_u32 s51, 2
	s_cselect_b32 s0, s0, 0
	v_lshl_add_u64 v[106:107], v[106:107], 0, s[6:7]
	v_lshl_add_u64 v[108:109], v[108:109], 0, s[6:7]
	s_cmp_eq_u32 s29, s50
	v_lshl_add_u64 v[110:111], v[110:111], 0, s[86:87]
	s_cbranch_scc1 .LBB0_1924
	v_mov_b32_e32 v113, v64
	s_branch .LBB0_1910

; __device__ __forceinline__ unsigned cvt_pk_bf16(float lo, float hi) { unsigned r; asm volatile("v_cvt_pk_bf16_f32 %0, %1, %2" : "=v"(r) : "v"(lo), "v"(hi)); return r; }
; __device__ __forceinline__ float bf_lo(unsigned w) { return __uint_as_float(w << 16); }
; __device__ __forceinline__ float bf_hi(unsigned w) { return __uint_as_float(w & 0xffff0000u); }
;     __device__ __forceinline__ void operator()(const f32x4 (&acc)[2][2][4][2], const Unit& u, int wr, int wc, int fr, int fq, const float (&rs)[2][4]) const {
;     ...
;             for (int m = 0; m < 4; ++m) { bf16_t* rowp = X + (size_t)(row0 + ai * HALF + m * 16) * DM + col0; float ss = 0.f;
; #pragma unroll
;                 for (int bj = 0; bj < 2; ++bj) { const u32x4 bw = *(const u32x4*)(rowp + bj * HALF); const f32x4 a0 = acc[ai][bj][m][0], a1 = acc[ai][bj][m][1];
;                     u32x4 w; w.x = cvt_pk_bf16(bf_lo(bw.x) + alpha * a0[0], bf_hi(bw.x) + alpha * a0[1]); w.y = cvt_pk_bf16(bf_lo(bw.y) + alpha * a0[2], bf_hi(bw.y) + alpha * a0[3]);
;                     w.z = cvt_pk_bf16(bf_lo(bw.z) + alpha * a1[0], bf_hi(bw.z) + alpha * a1[1]); w.w = cvt_pk_bf16(bf_lo(bw.w) + alpha * a1[2], bf_hi(bw.w) + alpha * a1[3]);
;                     *(u32x4*)(rowp + bj * HALF) = w;
;                     ss += (bf_lo(w.x) * bf_lo(w.x) + bf_hi(w.x) * bf_hi(w.x)) + (bf_lo(w.y) * bf_lo(w.y) + bf_hi(w.y) * bf_hi(w.y));
;                     ss += (bf_lo(w.z) * bf_lo(w.z) + bf_hi(w.z) * bf_hi(w.z)) + (bf_lo(w.w) * bf_lo(w.w) + bf_hi(w.w) * bf_hi(w.w)); }
;                 ss = fq_sum(ss);
;                 if (fq == 0) part[(size_t)(row0 + ai * HALF + m * 16) * 16 + u.pn * 4 + wc] = ss; } }
.LBB0_2018:
	s_lshl_b32 s0, s58, 8
	v_mov_b32_e32 v130, v151
	v_mov_b32_e32 v131, v150
	s_add_i32 s0, s0, s61
	s_lshl_b32 s42, s52, 2
	v_add_u32_e32 v148, s0, v130
	s_lshl_b32 s0, s52, 8
	s_or_b32 s0, s0, s66
	v_ashrrev_i32_e32 v149, 31, v148
	v_lshl_add_u32 v146, v131, 3, s0
	v_lshlrev_b64 v[154:155], 11, v[148:149]
	v_ashrrev_i32_e32 v147, 31, v146
	v_lshl_add_u64 v[154:155], s[94:95], 0, v[154:155]
	v_lshl_add_u64 v[158:159], v[146:147], 1, v[154:155]
	global_load_dwordx4 v[182:185], v[158:159], off
	global_load_dwordx4 v[186:189], v[158:159], off offset:256
	v_add_u32_e32 v246, 16, v148
	v_ashrrev_i32_e32 v247, 31, v246
	v_lshlrev_b64 v[246:247], 11, v[246:247]
	v_lshl_add_u64 v[246:247], s[94:95], 0, v[246:247]
	v_lshl_add_u64 v[246:247], v[146:147], 1, v[246:247]
	global_load_dwordx4 v[190:193], v[246:247], off
	global_load_dwordx4 v[194:197], v[246:247], off offset:256
	v_add_u32_e32 v248, 32, v148
	v_ashrrev_i32_e32 v249, 31, v248
	v_lshlrev_b64 v[248:249], 11, v[248:249]
	v_lshl_add_u64 v[248:249], s[94:95], 0, v[248:249]
	v_lshl_add_u64 v[248:249], v[146:147], 1, v[248:249]
	global_load_dwordx4 v[198:201], v[248:249], off
	global_load_dwordx4 v[202:205], v[248:249], off offset:256
	v_add_u32_e32 v246, 48, v148
	v_ashrrev_i32_e32 v247, 31, v246
	v_lshlrev_b64 v[246:247], 11, v[246:247]
	v_lshl_add_u64 v[246:247], s[94:95], 0, v[246:247]
	v_lshl_add_u64 v[246:247], v[146:147], 1, v[246:247]
	global_load_dwordx4 v[206:209], v[246:247], off
	global_load_dwordx4 v[210:213], v[246:247], off offset:256
	v_add_u32_e32 v248, 0x80, v148
	v_ashrrev_i32_e32 v249, 31, v248
	v_lshlrev_b64 v[248:249], 11, v[248:249]
	v_lshl_add_u64 v[248:249], s[94:95], 0, v[248:249]
	v_lshl_add_u64 v[248:249], v[146:147], 1, v[248:249]
	global_load_dwordx4 v[214:217], v[248:249], off
	global_load_dwordx4 v[218:221], v[248:249], off offset:256
	v_add_u32_e32 v246, 0x90, v148
	v_ashrrev_i32_e32 v247, 31, v246
	v_lshlrev_b64 v[246:247], 11, v[246:247]
	v_lshl_add_u64 v[246:247], s[94:95], 0, v[246:247]
	v_lshl_add_u64 v[246:247], v[146:147], 1, v[246:247]
	global_load_dwordx4 v[222:225], v[246:247], off
	global_load_dwordx4 v[226:229], v[246:247], off offset:256
	v_add_u32_e32 v248, 0xa0, v148
	v_ashrrev_i32_e32 v249, 31, v248
	v_lshlrev_b64 v[248:249], 11, v[248:249]
	v_lshl_add_u64 v[248:249], s[94:95], 0, v[248:249]
	v_lshl_add_u64 v[248:249], v[146:147], 1, v[248:249]
	global_load_dwordx4 v[230:233], v[248:249], off
	global_load_dwordx4 v[234:237], v[248:249], off offset:256
	v_add_u32_e32 v246, 0xb0, v148
	v_ashrrev_i32_e32 v247, 31, v246
	v_lshlrev_b64 v[246:247], 11, v[246:247]
	v_lshl_add_u64 v[246:247], s[94:95], 0, v[246:247]
	v_lshl_add_u64 v[246:247], v[146:147], 1, v[246:247]
	global_load_dwordx4 v[238:241], v[246:247], off
	global_load_dwordx4 v[242:245], v[246:247], off offset:256
	s_waitcnt vmcnt(0)
	s_ashr_i32 s43, s42, 31
	v_cmp_eq_u32_e32 vcc, 0, v131
	v_lshlrev_b32_e32 v130, 16, v182
	v_and_b32_e32 v134, 0xffff0000, v182
	v_lshlrev_b32_e32 v135, 16, v183
	v_and_b32_e32 v154, 0xffff0000, v183
	v_lshlrev_b32_e32 v160, 16, v185
	v_and_b32_e32 v157, 0xffff0000, v185
	v_lshlrev_b32_e32 v155, 16, v184
	v_and_b32_e32 v156, 0xffff0000, v184
	v_add_f32_e32 v126, v126, v130
	v_add_f32_e32 v127, v127, v134
	v_add_f32_e32 v128, v128, v135
	v_add_f32_e32 v129, v129, v154
	v_add_f32_e32 v125, v125, v157
	v_add_f32_e32 v130, v122, v155
	v_add_f32_e32 v134, v123, v156
	v_add_f32_e32 v135, v124, v160
	v_cvt_pk_bf16_f32 v122, v126, v127
	v_cvt_pk_bf16_f32 v123, v128, v129
	v_cvt_pk_bf16_f32 v124, v130, v134
	v_cvt_pk_bf16_f32 v125, v135, v125
	s_nop 0
	v_lshlrev_b32_e32 v130, 16, v122
	global_store_dwordx4 v[158:159], v[122:125], off
	v_lshlrev_b32_e32 v134, 16, v123
	v_lshlrev_b32_e32 v135, 16, v124
	v_and_b32_e32 v122, 0xffff0000, v122
	v_and_b32_e32 v123, 0xffff0000, v123
	v_and_b32_e32 v124, 0xffff0000, v124
	v_lshlrev_b32_e32 v154, 16, v125
	v_and_b32_e32 v125, 0xffff0000, v125
	v_mul_f32_e32 v122, v122, v122
	v_mul_f32_e32 v123, v123, v123
	v_mul_f32_e32 v124, v124, v124
	v_mul_f32_e32 v125, v125, v125
	v_fmac_f32_e32 v122, v130, v130
	v_fmac_f32_e32 v123, v134, v134
	v_fmac_f32_e32 v124, v135, v135
	v_fmac_f32_e32 v125, v154, v154
	v_add_f32_e32 v122, v122, v123
	v_add_f32_e32 v123, v124, v125
	v_add_f32_e32 v122, v122, v123
	v_lshlrev_b32_e32 v123, 16, v186
	v_and_b32_e32 v124, 0xffff0000, v186
	v_and_b32_e32 v126, 0xffff0000, v187
	v_lshlrev_b32_e32 v125, 16, v187
	v_lshlrev_b32_e32 v127, 16, v188
	v_and_b32_e32 v128, 0xffff0000, v188
	v_lshlrev_b32_e32 v130, 16, v189
	v_and_b32_e32 v129, 0xffff0000, v189
	v_add_f32_e32 v119, v119, v124
	v_add_f32_e32 v121, v121, v126
	v_add_f32_e32 v118, v118, v123
	v_add_f32_e32 v120, v120, v125
	v_add_f32_e32 v123, v114, v127
	v_add_f32_e32 v124, v115, v128
	v_add_f32_e32 v117, v117, v129
	v_cvt_pk_bf16_f32 v114, v118, v119
	v_cvt_pk_bf16_f32 v115, v120, v121
	v_add_f32_e32 v125, v116, v130
	v_and_b32_e32 v119, 0xffff0000, v114
	v_and_b32_e32 v121, 0xffff0000, v115
	v_cvt_pk_bf16_f32 v116, v123, v124
	v_cvt_pk_bf16_f32 v117, v125, v117
	v_lshlrev_b32_e32 v118, 16, v114
	v_lshlrev_b32_e32 v120, 16, v115
	v_and_b32_e32 v124, 0xffff0000, v116
	v_and_b32_e32 v126, 0xffff0000, v117
	v_mul_f32_e32 v119, v119, v119
	v_mul_f32_e32 v121, v121, v121
	v_lshlrev_b32_e32 v123, 16, v116
	v_lshlrev_b32_e32 v125, 16, v117
	v_mul_f32_e32 v124, v124, v124
	v_mul_f32_e32 v126, v126, v126
	v_fmac_f32_e32 v119, v118, v118
	v_fmac_f32_e32 v121, v120, v120
	v_fmac_f32_e32 v124, v123, v123
	v_fmac_f32_e32 v126, v125, v125
	v_add_f32_e32 v118, v119, v121
	v_add_f32_e32 v119, v124, v126
	v_add_f32_e32 v118, v122, v118
	v_add_f32_e32 v118, v118, v119
	ds_swizzle_b32 v119, v118 offset:swizzle(SWAP,16)
	global_store_dwordx4 v[158:159], v[114:117], off offset:256
	s_waitcnt lgkmcnt(0)
	s_nop 0
	v_add_f32_e32 v114, v118, v119
	v_mov_b32_e32 v115, v114
	s_nop 1
	v_permlane32_swap_b32_e32 v114, v115
	s_and_saveexec_b64 s[52:53], vcc
	s_cbranch_execz .LBB0_2020
	v_lshlrev_b64 v[116:117], 6, v[148:149]
	v_lshl_add_u64 v[116:117], s[96:97], 0, v[116:117]
	v_lshl_add_u64 v[116:117], s[42:43], 2, v[116:117]
	s_lshl_b32 s58, s31, 2
	v_lshl_add_u64 v[116:117], v[116:117], 0, s[58:59]
	v_add_f32_e32 v114, v114, v115
	global_store_dword v[116:117], v114, off
; __device__ __forceinline__ unsigned cvt_pk_bf16(float lo, float hi) { unsigned r; asm volatile("v_cvt_pk_bf16_f32 %0, %1, %2" : "=v"(r) : "v"(lo), "v"(hi)); return r; }
; __device__ __forceinline__ float bf_lo(unsigned w) { return __uint_as_float(w << 16); }
; __device__ __forceinline__ float bf_hi(unsigned w) { return __uint_as_float(w & 0xffff0000u); }
;     __device__ __forceinline__ void operator()(const f32x4 (&acc)[2][2][4][2], const Unit& u, int wr, int wc, int fr, int fq, const float (&rs)[2][4]) const {
;     ...
;             for (int m = 0; m < 4; ++m) { bf16_t* rowp = X + (size_t)(row0 + ai * HALF + m * 16) * DM + col0; float ss = 0.f;
; #pragma unroll
;                 for (int bj = 0; bj < 2; ++bj) { const u32x4 bw = *(const u32x4*)(rowp + bj * HALF); const f32x4 a0 = acc[ai][bj][m][0], a1 = acc[ai][bj][m][1];
;                     u32x4 w; w.x = cvt_pk_bf16(bf_lo(bw.x) + alpha * a0[0], bf_hi(bw.x) + alpha * a0[1]); w.y = cvt_pk_bf16(bf_lo(bw.y) + alpha * a0[2], bf_hi(bw.y) + alpha * a0[3]);
;                     w.z = cvt_pk_bf16(bf_lo(bw.z) + alpha * a1[0], bf_hi(bw.z) + alpha * a1[1]); w.w = cvt_pk_bf16(bf_lo(bw.w) + alpha * a1[2], bf_hi(bw.w) + alpha * a1[3]);
;                     *(u32x4*)(rowp + bj * HALF) = w;
;                     ss += (bf_lo(w.x) * bf_lo(w.x) + bf_hi(w.x) * bf_hi(w.x)) + (bf_lo(w.y) * bf_lo(w.y) + bf_hi(w.y) * bf_hi(w.y));
;                     ss += (bf_lo(w.z) * bf_lo(w.z) + bf_hi(w.z) * bf_hi(w.z)) + (bf_lo(w.w) * bf_lo(w.w) + bf_hi(w.w) * bf_hi(w.w)); }
;                 ss = fq_sum(ss);
;                 if (fq == 0) part[(size_t)(row0 + ai * HALF + m * 16) * 16 + u.pn * 4 + wc] = ss; } }
.LBB0_2020:
	s_or_b64 exec, exec, s[52:53]
	v_add_u32_e32 v114, 16, v148
	v_ashrrev_i32_e32 v115, 31, v114
	v_lshlrev_b64 v[116:117], 11, v[114:115]
	v_lshl_add_u64 v[116:117], s[94:95], 0, v[116:117]
	v_lshl_add_u64 v[120:121], v[146:147], 1, v[116:117]
	s_nop 0
	v_lshlrev_b32_e32 v122, 16, v190
	v_and_b32_e32 v116, 0xffff0000, v190
	v_lshlrev_b32_e32 v123, 16, v191
	v_and_b32_e32 v117, 0xffff0000, v191
	v_lshlrev_b32_e32 v125, 16, v193
	v_and_b32_e32 v119, 0xffff0000, v193
	v_lshlrev_b32_e32 v124, 16, v192
	v_and_b32_e32 v118, 0xffff0000, v192
	v_add_f32_e32 v110, v110, v122
	v_add_f32_e32 v111, v111, v116
	v_add_f32_e32 v112, v112, v123
	v_add_f32_e32 v113, v113, v117
	v_add_f32_e32 v109, v109, v119
	v_add_f32_e32 v116, v106, v124
	v_add_f32_e32 v117, v107, v118
	v_add_f32_e32 v118, v108, v125
	v_cvt_pk_bf16_f32 v106, v110, v111
	v_cvt_pk_bf16_f32 v107, v112, v113
	v_cvt_pk_bf16_f32 v108, v116, v117
	v_cvt_pk_bf16_f32 v109, v118, v109
	s_nop 0
	v_lshlrev_b32_e32 v116, 16, v106
	global_store_dwordx4 v[120:121], v[106:109], off
	v_lshlrev_b32_e32 v117, 16, v107
	v_lshlrev_b32_e32 v118, 16, v108
	v_and_b32_e32 v106, 0xffff0000, v106
	v_and_b32_e32 v107, 0xffff0000, v107
	v_and_b32_e32 v108, 0xffff0000, v108
	v_lshlrev_b32_e32 v119, 16, v109
	v_and_b32_e32 v109, 0xffff0000, v109
	v_mul_f32_e32 v106, v106, v106
	v_mul_f32_e32 v107, v107, v107
	v_mul_f32_e32 v108, v108, v108
	v_mul_f32_e32 v109, v109, v109
	v_fmac_f32_e32 v106, v116, v116
	v_fmac_f32_e32 v107, v117, v117
	v_fmac_f32_e32 v108, v118, v118
	v_fmac_f32_e32 v109, v119, v119
	v_add_f32_e32 v106, v106, v107
	v_add_f32_e32 v107, v108, v109
	v_add_f32_e32 v106, v106, v107
	v_lshlrev_b32_e32 v107, 16, v194
	v_and_b32_e32 v108, 0xffff0000, v194
	v_and_b32_e32 v110, 0xffff0000, v195
	v_lshlrev_b32_e32 v109, 16, v195
	v_lshlrev_b32_e32 v111, 16, v196
	v_and_b32_e32 v112, 0xffff0000, v196
	v_lshlrev_b32_e32 v116, 16, v197
	v_and_b32_e32 v113, 0xffff0000, v197
	v_add_f32_e32 v103, v103, v108
	v_add_f32_e32 v105, v105, v110
	v_add_f32_e32 v102, v102, v107
	v_add_f32_e32 v104, v104, v109
	v_add_f32_e32 v107, v98, v111
	v_add_f32_e32 v108, v99, v112
	v_add_f32_e32 v101, v101, v113
	v_cvt_pk_bf16_f32 v98, v102, v103
	v_cvt_pk_bf16_f32 v99, v104, v105
	v_add_f32_e32 v109, v100, v116
	v_and_b32_e32 v103, 0xffff0000, v98
	v_and_b32_e32 v105, 0xffff0000, v99
	v_cvt_pk_bf16_f32 v100, v107, v108
	v_cvt_pk_bf16_f32 v101, v109, v101
	v_lshlrev_b32_e32 v102, 16, v98
	v_lshlrev_b32_e32 v104, 16, v99
	v_and_b32_e32 v108, 0xffff0000, v100
	v_and_b32_e32 v110, 0xffff0000, v101
	v_mul_f32_e32 v103, v103, v103
	v_mul_f32_e32 v105, v105, v105
	v_lshlrev_b32_e32 v107, 16, v100
	v_lshlrev_b32_e32 v109, 16, v101
	v_mul_f32_e32 v108, v108, v108
	v_mul_f32_e32 v110, v110, v110
	v_fmac_f32_e32 v103, v102, v102
	v_fmac_f32_e32 v105, v104, v104
	v_fmac_f32_e32 v108, v107, v107
	v_fmac_f32_e32 v110, v109, v109
	v_add_f32_e32 v102, v103, v105
	v_add_f32_e32 v103, v108, v110
	v_add_f32_e32 v102, v106, v102
	v_add_f32_e32 v102, v102, v103
	ds_swizzle_b32 v103, v102 offset:swizzle(SWAP,16)
	global_store_dwordx4 v[120:121], v[98:101], off offset:256
	s_waitcnt lgkmcnt(0)
	s_nop 0
	v_add_f32_e32 v98, v102, v103
	v_mov_b32_e32 v99, v98
	s_nop 1
	v_permlane32_swap_b32_e32 v98, v99
	s_and_saveexec_b64 s[52:53], vcc
	s_cbranch_execz .LBB0_2022
	v_lshlrev_b64 v[100:101], 6, v[114:115]
	v_lshl_add_u64 v[100:101], s[96:97], 0, v[100:101]
	v_lshl_add_u64 v[100:101], s[42:43], 2, v[100:101]
	s_lshl_b32 s58, s31, 2
	v_lshl_add_u64 v[100:101], v[100:101], 0, s[58:59]
	v_add_f32_e32 v98, v98, v99
	global_store_dword v[100:101], v98, off
.LBB0_2022:
	s_or_b64 exec, exec, s[52:53]
	v_add_u32_e32 v98, 32, v148
	v_ashrrev_i32_e32 v99, 31, v98
	v_lshlrev_b64 v[100:101], 11, v[98:99]
	v_lshl_add_u64 v[100:101], s[94:95], 0, v[100:101]
	v_lshl_add_u64 v[104:105], v[146:147], 1, v[100:101]
	s_nop 0
	v_lshlrev_b32_e32 v106, 16, v198
	v_and_b32_e32 v100, 0xffff0000, v198
	v_lshlrev_b32_e32 v107, 16, v199
	v_and_b32_e32 v101, 0xffff0000, v199
	v_lshlrev_b32_e32 v109, 16, v201
	v_and_b32_e32 v103, 0xffff0000, v201
	v_lshlrev_b32_e32 v108, 16, v200
	v_and_b32_e32 v102, 0xffff0000, v200
	v_add_f32_e32 v94, v94, v106
	v_add_f32_e32 v95, v95, v100
	v_add_f32_e32 v96, v96, v107
	v_add_f32_e32 v97, v97, v101
	v_add_f32_e32 v93, v93, v103
	v_add_f32_e32 v100, v90, v108
	v_add_f32_e32 v101, v91, v102
	v_add_f32_e32 v102, v92, v109
	v_cvt_pk_bf16_f32 v90, v94, v95
	v_cvt_pk_bf16_f32 v91, v96, v97
	v_cvt_pk_bf16_f32 v92, v100, v101
	v_cvt_pk_bf16_f32 v93, v102, v93
	s_nop 0
	v_lshlrev_b32_e32 v100, 16, v90
	global_store_dwordx4 v[104:105], v[90:93], off
	v_lshlrev_b32_e32 v101, 16, v91
	v_lshlrev_b32_e32 v102, 16, v92
	v_and_b32_e32 v90, 0xffff0000, v90
	v_and_b32_e32 v91, 0xffff0000, v91
	v_and_b32_e32 v92, 0xffff0000, v92
	v_lshlrev_b32_e32 v103, 16, v93
	v_and_b32_e32 v93, 0xffff0000, v93
	v_mul_f32_e32 v90, v90, v90
	v_mul_f32_e32 v91, v91, v91
	v_mul_f32_e32 v92, v92, v92
	v_mul_f32_e32 v93, v93, v93
	v_fmac_f32_e32 v90, v100, v100
	v_fmac_f32_e32 v91, v101, v101
	v_fmac_f32_e32 v92, v102, v102
	v_fmac_f32_e32 v93, v103, v103
	v_add_f32_e32 v90, v90, v91
	v_add_f32_e32 v91, v92, v93
	v_add_f32_e32 v90, v90, v91
	v_lshlrev_b32_e32 v91, 16, v202
	v_and_b32_e32 v92, 0xffff0000, v202
	v_and_b32_e32 v94, 0xffff0000, v203
	v_lshlrev_b32_e32 v93, 16, v203
	v_lshlrev_b32_e32 v95, 16, v204
	v_and_b32_e32 v96, 0xffff0000, v204
	v_lshlrev_b32_e32 v100, 16, v205
	v_and_b32_e32 v97, 0xffff0000, v205
	v_add_f32_e32 v87, v87, v92
	v_add_f32_e32 v89, v89, v94
	v_add_f32_e32 v86, v86, v91
	v_add_f32_e32 v88, v88, v93
	v_add_f32_e32 v91, v82, v95
	v_add_f32_e32 v92, v83, v96
	v_add_f32_e32 v85, v85, v97
	v_cvt_pk_bf16_f32 v82, v86, v87
	v_cvt_pk_bf16_f32 v83, v88, v89
	v_add_f32_e32 v93, v84, v100
	v_and_b32_e32 v87, 0xffff0000, v82
	v_and_b32_e32 v89, 0xffff0000, v83
	v_cvt_pk_bf16_f32 v84, v91, v92
	v_cvt_pk_bf16_f32 v85, v93, v85
	v_lshlrev_b32_e32 v86, 16, v82
	v_lshlrev_b32_e32 v88, 16, v83
	v_and_b32_e32 v92, 0xffff0000, v84
	v_and_b32_e32 v94, 0xffff0000, v85
	v_mul_f32_e32 v87, v87, v87
	v_mul_f32_e32 v89, v89, v89
	v_lshlrev_b32_e32 v91, 16, v84
	v_lshlrev_b32_e32 v93, 16, v85
	v_mul_f32_e32 v92, v92, v92
	v_mul_f32_e32 v94, v94, v94
	v_fmac_f32_e32 v87, v86, v86
	v_fmac_f32_e32 v89, v88, v88
	v_fmac_f32_e32 v92, v91, v91
	v_fmac_f32_e32 v94, v93, v93
	v_add_f32_e32 v86, v87, v89
	v_add_f32_e32 v87, v92, v94
	v_add_f32_e32 v86, v90, v86
	v_add_f32_e32 v86, v86, v87
	ds_swizzle_b32 v87, v86 offset:swizzle(SWAP,16)
	global_store_dwordx4 v[104:105], v[82:85], off offset:256
	s_waitcnt lgkmcnt(0)
	s_nop 0
	v_add_f32_e32 v82, v86, v87
	v_mov_b32_e32 v83, v82
	s_nop 1
	v_permlane32_swap_b32_e32 v82, v83
	s_and_saveexec_b64 s[52:53], vcc
	s_cbranch_execz .LBB0_2024
	v_lshlrev_b64 v[84:85], 6, v[98:99]
	v_lshl_add_u64 v[84:85], s[96:97], 0, v[84:85]
	v_lshl_add_u64 v[84:85], s[42:43], 2, v[84:85]
	s_lshl_b32 s58, s31, 2
	v_lshl_add_u64 v[84:85], v[84:85], 0, s[58:59]
	v_add_f32_e32 v82, v82, v83
	global_store_dword v[84:85], v82, off
; __device__ __forceinline__ unsigned cvt_pk_bf16(float lo, float hi) { unsigned r; asm volatile("v_cvt_pk_bf16_f32 %0, %1, %2" : "=v"(r) : "v"(lo), "v"(hi)); return r; }
; __device__ __forceinline__ float bf_lo(unsigned w) { return __uint_as_float(w << 16); }
; __device__ __forceinline__ float bf_hi(unsigned w) { return __uint_as_float(w & 0xffff0000u); }
;     __device__ __forceinline__ void operator()(const f32x4 (&acc)[2][2][4][2], const Unit& u, int wr, int wc, int fr, int fq, const float (&rs)[2][4]) const {
;     ...
;             for (int m = 0; m < 4; ++m) { bf16_t* rowp = X + (size_t)(row0 + ai * HALF + m * 16) * DM + col0; float ss = 0.f;
; #pragma unroll
;                 for (int bj = 0; bj < 2; ++bj) { const u32x4 bw = *(const u32x4*)(rowp + bj * HALF); const f32x4 a0 = acc[ai][bj][m][0], a1 = acc[ai][bj][m][1];
;                     u32x4 w; w.x = cvt_pk_bf16(bf_lo(bw.x) + alpha * a0[0], bf_hi(bw.x) + alpha * a0[1]); w.y = cvt_pk_bf16(bf_lo(bw.y) + alpha * a0[2], bf_hi(bw.y) + alpha * a0[3]);
;                     w.z = cvt_pk_bf16(bf_lo(bw.z) + alpha * a1[0], bf_hi(bw.z) + alpha * a1[1]); w.w = cvt_pk_bf16(bf_lo(bw.w) + alpha * a1[2], bf_hi(bw.w) + alpha * a1[3]);
;                     *(u32x4*)(rowp + bj * HALF) = w;
;                     ss += (bf_lo(w.x) * bf_lo(w.x) + bf_hi(w.x) * bf_hi(w.x)) + (bf_lo(w.y) * bf_lo(w.y) + bf_hi(w.y) * bf_hi(w.y));
;                     ss += (bf_lo(w.z) * bf_lo(w.z) + bf_hi(w.z) * bf_hi(w.z)) + (bf_lo(w.w) * bf_lo(w.w) + bf_hi(w.w) * bf_hi(w.w)); }
;                 ss = fq_sum(ss);
;                 if (fq == 0) part[(size_t)(row0 + ai * HALF + m * 16) * 16 + u.pn * 4 + wc] = ss; } }
.LBB0_2024:
	s_or_b64 exec, exec, s[52:53]
	v_add_u32_e32 v82, 48, v148
	v_ashrrev_i32_e32 v83, 31, v82
	v_lshlrev_b64 v[84:85], 11, v[82:83]
	v_lshl_add_u64 v[84:85], s[94:95], 0, v[84:85]
	v_lshl_add_u64 v[88:89], v[146:147], 1, v[84:85]
	s_nop 0
	v_lshlrev_b32_e32 v90, 16, v206
	v_and_b32_e32 v84, 0xffff0000, v206
	v_lshlrev_b32_e32 v91, 16, v207
	v_and_b32_e32 v85, 0xffff0000, v207
	v_lshlrev_b32_e32 v93, 16, v209
	v_and_b32_e32 v87, 0xffff0000, v209
	v_lshlrev_b32_e32 v92, 16, v208
	v_and_b32_e32 v86, 0xffff0000, v208
	v_add_f32_e32 v76, v76, v90
	v_add_f32_e32 v77, v77, v84
	v_add_f32_e32 v78, v78, v91
	v_add_f32_e32 v79, v79, v85
	v_add_f32_e32 v75, v75, v87
	v_add_f32_e32 v84, v72, v92
	v_add_f32_e32 v85, v73, v86
	v_add_f32_e32 v86, v74, v93
	v_cvt_pk_bf16_f32 v72, v76, v77
	v_cvt_pk_bf16_f32 v73, v78, v79
	v_cvt_pk_bf16_f32 v74, v84, v85
	v_cvt_pk_bf16_f32 v75, v86, v75
	s_nop 0
	v_lshlrev_b32_e32 v84, 16, v72
	global_store_dwordx4 v[88:89], v[72:75], off
	v_lshlrev_b32_e32 v85, 16, v73
	v_lshlrev_b32_e32 v86, 16, v74
	v_and_b32_e32 v72, 0xffff0000, v72
	v_and_b32_e32 v73, 0xffff0000, v73
	v_and_b32_e32 v74, 0xffff0000, v74
	v_lshlrev_b32_e32 v87, 16, v75
	v_and_b32_e32 v75, 0xffff0000, v75
	v_mul_f32_e32 v72, v72, v72
	v_mul_f32_e32 v73, v73, v73
	v_mul_f32_e32 v74, v74, v74
	v_mul_f32_e32 v75, v75, v75
	v_fmac_f32_e32 v72, v84, v84
	v_fmac_f32_e32 v73, v85, v85
	v_fmac_f32_e32 v74, v86, v86
	v_fmac_f32_e32 v75, v87, v87
	v_add_f32_e32 v72, v72, v73
	v_add_f32_e32 v73, v74, v75
	v_add_f32_e32 v72, v72, v73
	v_lshlrev_b32_e32 v73, 16, v210
	v_and_b32_e32 v74, 0xffff0000, v210
	v_and_b32_e32 v76, 0xffff0000, v211
	v_lshlrev_b32_e32 v75, 16, v211
	v_lshlrev_b32_e32 v77, 16, v212
	v_and_b32_e32 v78, 0xffff0000, v212
	v_lshlrev_b32_e32 v84, 16, v213
	v_and_b32_e32 v79, 0xffff0000, v213
	v_add_f32_e32 v69, v69, v74
	v_add_f32_e32 v71, v71, v76
	v_add_f32_e32 v68, v68, v73
	v_add_f32_e32 v70, v70, v75
	v_add_f32_e32 v73, v64, v77
	v_add_f32_e32 v74, v65, v78
	v_add_f32_e32 v67, v67, v79
	v_cvt_pk_bf16_f32 v64, v68, v69
	v_cvt_pk_bf16_f32 v65, v70, v71
	v_add_f32_e32 v75, v66, v84
	v_and_b32_e32 v69, 0xffff0000, v64
	v_and_b32_e32 v71, 0xffff0000, v65
	v_cvt_pk_bf16_f32 v66, v73, v74
	v_cvt_pk_bf16_f32 v67, v75, v67
	v_lshlrev_b32_e32 v68, 16, v64
	v_lshlrev_b32_e32 v70, 16, v65
	v_and_b32_e32 v74, 0xffff0000, v66
	v_and_b32_e32 v76, 0xffff0000, v67
	v_mul_f32_e32 v69, v69, v69
	v_mul_f32_e32 v71, v71, v71
	v_lshlrev_b32_e32 v73, 16, v66
	v_lshlrev_b32_e32 v75, 16, v67
	v_mul_f32_e32 v74, v74, v74
	v_mul_f32_e32 v76, v76, v76
	v_fmac_f32_e32 v69, v68, v68
	v_fmac_f32_e32 v71, v70, v70
	v_fmac_f32_e32 v74, v73, v73
	v_fmac_f32_e32 v76, v75, v75
	v_add_f32_e32 v68, v69, v71
	v_add_f32_e32 v69, v74, v76
	v_add_f32_e32 v68, v72, v68
	v_add_f32_e32 v68, v68, v69
	ds_swizzle_b32 v69, v68 offset:swizzle(SWAP,16)
	global_store_dwordx4 v[88:89], v[64:67], off offset:256
	s_waitcnt lgkmcnt(0)
	s_nop 0
	v_add_f32_e32 v64, v68, v69
	v_mov_b32_e32 v65, v64
	s_nop 1
	v_permlane32_swap_b32_e32 v64, v65
	s_and_saveexec_b64 s[52:53], vcc
	s_cbranch_execz .LBB0_2026
	v_lshlrev_b64 v[66:67], 6, v[82:83]
	v_lshl_add_u64 v[66:67], s[96:97], 0, v[66:67]
	v_lshl_add_u64 v[66:67], s[42:43], 2, v[66:67]
	s_lshl_b32 s58, s31, 2
	v_lshl_add_u64 v[66:67], v[66:67], 0, s[58:59]
	v_add_f32_e32 v64, v64, v65
	global_store_dword v[66:67], v64, off
.LBB0_2026:
	s_or_b64 exec, exec, s[52:53]
	v_add_u32_e32 v64, 0x80, v148
	v_ashrrev_i32_e32 v65, 31, v64
	v_lshlrev_b64 v[66:67], 11, v[64:65]
	v_lshl_add_u64 v[66:67], s[94:95], 0, v[66:67]
	v_lshl_add_u64 v[70:71], v[146:147], 1, v[66:67]
	s_nop 0
	v_lshlrev_b32_e32 v72, 16, v214
	v_and_b32_e32 v66, 0xffff0000, v214
	v_lshlrev_b32_e32 v73, 16, v215
	v_and_b32_e32 v67, 0xffff0000, v215
	v_lshlrev_b32_e32 v75, 16, v217
	v_and_b32_e32 v69, 0xffff0000, v217
	v_lshlrev_b32_e32 v74, 16, v216
	v_and_b32_e32 v68, 0xffff0000, v216
	v_add_f32_e32 v60, v60, v72
	v_add_f32_e32 v61, v61, v66
	v_add_f32_e32 v62, v62, v73
	v_add_f32_e32 v63, v63, v67
	v_add_f32_e32 v59, v59, v69
	v_add_f32_e32 v66, v56, v74
	v_add_f32_e32 v67, v57, v68
	v_add_f32_e32 v68, v58, v75
	v_cvt_pk_bf16_f32 v56, v60, v61
	v_cvt_pk_bf16_f32 v57, v62, v63
	v_cvt_pk_bf16_f32 v58, v66, v67
	v_cvt_pk_bf16_f32 v59, v68, v59
	s_nop 0
	v_lshlrev_b32_e32 v66, 16, v56
	global_store_dwordx4 v[70:71], v[56:59], off
	v_lshlrev_b32_e32 v67, 16, v57
	v_lshlrev_b32_e32 v68, 16, v58
	v_and_b32_e32 v56, 0xffff0000, v56
	v_and_b32_e32 v57, 0xffff0000, v57
	v_and_b32_e32 v58, 0xffff0000, v58
	v_lshlrev_b32_e32 v69, 16, v59
	v_and_b32_e32 v59, 0xffff0000, v59
	v_mul_f32_e32 v56, v56, v56
	v_mul_f32_e32 v57, v57, v57
	v_mul_f32_e32 v58, v58, v58
	v_mul_f32_e32 v59, v59, v59
	v_fmac_f32_e32 v56, v66, v66
	v_fmac_f32_e32 v57, v67, v67
	v_fmac_f32_e32 v58, v68, v68
	v_fmac_f32_e32 v59, v69, v69
	v_add_f32_e32 v56, v56, v57
	v_add_f32_e32 v57, v58, v59
	v_add_f32_e32 v56, v56, v57
	v_lshlrev_b32_e32 v57, 16, v218
	v_and_b32_e32 v58, 0xffff0000, v218
	v_and_b32_e32 v60, 0xffff0000, v219
	v_lshlrev_b32_e32 v59, 16, v219
	v_lshlrev_b32_e32 v61, 16, v220
	v_and_b32_e32 v62, 0xffff0000, v220
	v_lshlrev_b32_e32 v66, 16, v221
	v_and_b32_e32 v63, 0xffff0000, v221
	v_add_f32_e32 v53, v53, v58
	v_add_f32_e32 v55, v55, v60
	v_add_f32_e32 v52, v52, v57
	v_add_f32_e32 v54, v54, v59
	v_add_f32_e32 v57, v48, v61
	v_add_f32_e32 v58, v49, v62
	v_add_f32_e32 v51, v51, v63
	v_cvt_pk_bf16_f32 v48, v52, v53
	v_cvt_pk_bf16_f32 v49, v54, v55
	v_add_f32_e32 v59, v50, v66
	v_and_b32_e32 v53, 0xffff0000, v48
	v_and_b32_e32 v55, 0xffff0000, v49
	v_cvt_pk_bf16_f32 v50, v57, v58
	v_cvt_pk_bf16_f32 v51, v59, v51
	v_lshlrev_b32_e32 v52, 16, v48
	v_lshlrev_b32_e32 v54, 16, v49
	v_and_b32_e32 v58, 0xffff0000, v50
	v_and_b32_e32 v60, 0xffff0000, v51
	v_mul_f32_e32 v53, v53, v53
	v_mul_f32_e32 v55, v55, v55
	v_lshlrev_b32_e32 v57, 16, v50
	v_lshlrev_b32_e32 v59, 16, v51
	v_mul_f32_e32 v58, v58, v58
	v_mul_f32_e32 v60, v60, v60
	v_fmac_f32_e32 v53, v52, v52
	v_fmac_f32_e32 v55, v54, v54
	v_fmac_f32_e32 v58, v57, v57
	v_fmac_f32_e32 v60, v59, v59
	v_add_f32_e32 v52, v53, v55
	v_add_f32_e32 v53, v58, v60
	v_add_f32_e32 v52, v56, v52
	v_add_f32_e32 v52, v52, v53
	ds_swizzle_b32 v53, v52 offset:swizzle(SWAP,16)
	global_store_dwordx4 v[70:71], v[48:51], off offset:256
	s_waitcnt lgkmcnt(0)
	s_nop 0
	v_add_f32_e32 v48, v52, v53
	v_mov_b32_e32 v49, v48
	s_nop 1
	v_permlane32_swap_b32_e32 v48, v49
	s_and_saveexec_b64 s[52:53], vcc
	s_cbranch_execz .LBB0_2028
	v_lshlrev_b64 v[50:51], 6, v[64:65]
	v_lshl_add_u64 v[50:51], s[96:97], 0, v[50:51]
	v_lshl_add_u64 v[50:51], s[42:43], 2, v[50:51]
	s_lshl_b32 s58, s31, 2
	v_lshl_add_u64 v[50:51], v[50:51], 0, s[58:59]
	v_add_f32_e32 v48, v48, v49
	global_store_dword v[50:51], v48, off
; __device__ __forceinline__ unsigned cvt_pk_bf16(float lo, float hi) { unsigned r; asm volatile("v_cvt_pk_bf16_f32 %0, %1, %2" : "=v"(r) : "v"(lo), "v"(hi)); return r; }
; __device__ __forceinline__ float bf_lo(unsigned w) { return __uint_as_float(w << 16); }
; __device__ __forceinline__ float bf_hi(unsigned w) { return __uint_as_float(w & 0xffff0000u); }
;     __device__ __forceinline__ void operator()(const f32x4 (&acc)[2][2][4][2], const Unit& u, int wr, int wc, int fr, int fq, const float (&rs)[2][4]) const {
;     ...
;             for (int m = 0; m < 4; ++m) { bf16_t* rowp = X + (size_t)(row0 + ai * HALF + m * 16) * DM + col0; float ss = 0.f;
; #pragma unroll
;                 for (int bj = 0; bj < 2; ++bj) { const u32x4 bw = *(const u32x4*)(rowp + bj * HALF); const f32x4 a0 = acc[ai][bj][m][0], a1 = acc[ai][bj][m][1];
;                     u32x4 w; w.x = cvt_pk_bf16(bf_lo(bw.x) + alpha * a0[0], bf_hi(bw.x) + alpha * a0[1]); w.y = cvt_pk_bf16(bf_lo(bw.y) + alpha * a0[2], bf_hi(bw.y) + alpha * a0[3]);
;                     w.z = cvt_pk_bf16(bf_lo(bw.z) + alpha * a1[0], bf_hi(bw.z) + alpha * a1[1]); w.w = cvt_pk_bf16(bf_lo(bw.w) + alpha * a1[2], bf_hi(bw.w) + alpha * a1[3]);
;                     *(u32x4*)(rowp + bj * HALF) = w;
;                     ss += (bf_lo(w.x) * bf_lo(w.x) + bf_hi(w.x) * bf_hi(w.x)) + (bf_lo(w.y) * bf_lo(w.y) + bf_hi(w.y) * bf_hi(w.y));
;                     ss += (bf_lo(w.z) * bf_lo(w.z) + bf_hi(w.z) * bf_hi(w.z)) + (bf_lo(w.w) * bf_lo(w.w) + bf_hi(w.w) * bf_hi(w.w)); }
;                 ss = fq_sum(ss);
;                 if (fq == 0) part[(size_t)(row0 + ai * HALF + m * 16) * 16 + u.pn * 4 + wc] = ss; } }
.LBB0_2028:
	s_or_b64 exec, exec, s[52:53]
	v_add_u32_e32 v48, 0x90, v148
	v_ashrrev_i32_e32 v49, 31, v48
	v_lshlrev_b64 v[50:51], 11, v[48:49]
	v_lshl_add_u64 v[50:51], s[94:95], 0, v[50:51]
	v_lshl_add_u64 v[54:55], v[146:147], 1, v[50:51]
	s_nop 0
	v_lshlrev_b32_e32 v56, 16, v222
	v_and_b32_e32 v50, 0xffff0000, v222
	v_lshlrev_b32_e32 v57, 16, v223
	v_and_b32_e32 v51, 0xffff0000, v223
	v_lshlrev_b32_e32 v59, 16, v225
	v_and_b32_e32 v53, 0xffff0000, v225
	v_lshlrev_b32_e32 v58, 16, v224
	v_and_b32_e32 v52, 0xffff0000, v224
	v_add_f32_e32 v44, v44, v56
	v_add_f32_e32 v45, v45, v50
	v_add_f32_e32 v46, v46, v57
	v_add_f32_e32 v47, v47, v51
	v_add_f32_e32 v43, v43, v53
	v_add_f32_e32 v50, v40, v58
	v_add_f32_e32 v51, v41, v52
	v_add_f32_e32 v52, v42, v59
	v_cvt_pk_bf16_f32 v40, v44, v45
	v_cvt_pk_bf16_f32 v41, v46, v47
	v_cvt_pk_bf16_f32 v42, v50, v51
	v_cvt_pk_bf16_f32 v43, v52, v43
	s_nop 0
	v_lshlrev_b32_e32 v50, 16, v40
	global_store_dwordx4 v[54:55], v[40:43], off
	v_lshlrev_b32_e32 v51, 16, v41
	v_lshlrev_b32_e32 v52, 16, v42
	v_and_b32_e32 v40, 0xffff0000, v40
	v_and_b32_e32 v41, 0xffff0000, v41
	v_and_b32_e32 v42, 0xffff0000, v42
	v_lshlrev_b32_e32 v53, 16, v43
	v_and_b32_e32 v43, 0xffff0000, v43
	v_mul_f32_e32 v40, v40, v40
	v_mul_f32_e32 v41, v41, v41
	v_mul_f32_e32 v42, v42, v42
	v_mul_f32_e32 v43, v43, v43
	v_fmac_f32_e32 v40, v50, v50
	v_fmac_f32_e32 v41, v51, v51
	v_fmac_f32_e32 v42, v52, v52
	v_fmac_f32_e32 v43, v53, v53
	v_add_f32_e32 v40, v40, v41
	v_add_f32_e32 v41, v42, v43
	v_add_f32_e32 v40, v40, v41
	v_lshlrev_b32_e32 v41, 16, v226
	v_and_b32_e32 v42, 0xffff0000, v226
	v_and_b32_e32 v44, 0xffff0000, v227
	v_lshlrev_b32_e32 v43, 16, v227
	v_lshlrev_b32_e32 v45, 16, v228
	v_and_b32_e32 v46, 0xffff0000, v228
	v_lshlrev_b32_e32 v50, 16, v229
	v_and_b32_e32 v47, 0xffff0000, v229
	v_add_f32_e32 v37, v37, v42
	v_add_f32_e32 v39, v39, v44
	v_add_f32_e32 v36, v36, v41
	v_add_f32_e32 v38, v38, v43
	v_add_f32_e32 v41, v32, v45
	v_add_f32_e32 v42, v33, v46
	v_add_f32_e32 v35, v35, v47
	v_cvt_pk_bf16_f32 v32, v36, v37
	v_cvt_pk_bf16_f32 v33, v38, v39
	v_add_f32_e32 v43, v34, v50
	v_and_b32_e32 v37, 0xffff0000, v32
	v_and_b32_e32 v39, 0xffff0000, v33
	v_cvt_pk_bf16_f32 v34, v41, v42
	v_cvt_pk_bf16_f32 v35, v43, v35
	v_lshlrev_b32_e32 v36, 16, v32
	v_lshlrev_b32_e32 v38, 16, v33
	v_and_b32_e32 v42, 0xffff0000, v34
	v_and_b32_e32 v44, 0xffff0000, v35
	v_mul_f32_e32 v37, v37, v37
	v_mul_f32_e32 v39, v39, v39
	v_lshlrev_b32_e32 v41, 16, v34
	v_lshlrev_b32_e32 v43, 16, v35
	v_mul_f32_e32 v42, v42, v42
	v_mul_f32_e32 v44, v44, v44
	v_fmac_f32_e32 v37, v36, v36
	v_fmac_f32_e32 v39, v38, v38
	v_fmac_f32_e32 v42, v41, v41
	v_fmac_f32_e32 v44, v43, v43
	v_add_f32_e32 v36, v37, v39
	v_add_f32_e32 v37, v42, v44
	v_add_f32_e32 v36, v40, v36
	v_add_f32_e32 v36, v36, v37
	ds_swizzle_b32 v37, v36 offset:swizzle(SWAP,16)
	global_store_dwordx4 v[54:55], v[32:35], off offset:256
	s_waitcnt lgkmcnt(0)
	s_nop 0
	v_add_f32_e32 v32, v36, v37
	v_mov_b32_e32 v33, v32
	s_nop 1
	v_permlane32_swap_b32_e32 v32, v33
	s_and_saveexec_b64 s[52:53], vcc
	s_cbranch_execz .LBB0_2030
	v_lshlrev_b64 v[34:35], 6, v[48:49]
	v_lshl_add_u64 v[34:35], s[96:97], 0, v[34:35]
	v_lshl_add_u64 v[34:35], s[42:43], 2, v[34:35]
	s_lshl_b32 s58, s31, 2
	v_lshl_add_u64 v[34:35], v[34:35], 0, s[58:59]
	v_add_f32_e32 v32, v32, v33
	global_store_dword v[34:35], v32, off
; __device__ __forceinline__ unsigned cvt_pk_bf16(float lo, float hi) { unsigned r; asm volatile("v_cvt_pk_bf16_f32 %0, %1, %2" : "=v"(r) : "v"(lo), "v"(hi)); return r; }
; __device__ __forceinline__ float bf_lo(unsigned w) { return __uint_as_float(w << 16); }
; __device__ __forceinline__ float bf_hi(unsigned w) { return __uint_as_float(w & 0xffff0000u); }
;     __device__ __forceinline__ void operator()(const f32x4 (&acc)[2][2][4][2], const Unit& u, int wr, int wc, int fr, int fq, const float (&rs)[2][4]) const {
;     ...
;             for (int m = 0; m < 4; ++m) { bf16_t* rowp = X + (size_t)(row0 + ai * HALF + m * 16) * DM + col0; float ss = 0.f;
; #pragma unroll
;                 for (int bj = 0; bj < 2; ++bj) { const u32x4 bw = *(const u32x4*)(rowp + bj * HALF); const f32x4 a0 = acc[ai][bj][m][0], a1 = acc[ai][bj][m][1];
;                     u32x4 w; w.x = cvt_pk_bf16(bf_lo(bw.x) + alpha * a0[0], bf_hi(bw.x) + alpha * a0[1]); w.y = cvt_pk_bf16(bf_lo(bw.y) + alpha * a0[2], bf_hi(bw.y) + alpha * a0[3]);
;                     w.z = cvt_pk_bf16(bf_lo(bw.z) + alpha * a1[0], bf_hi(bw.z) + alpha * a1[1]); w.w = cvt_pk_bf16(bf_lo(bw.w) + alpha * a1[2], bf_hi(bw.w) + alpha * a1[3]);
;                     *(u32x4*)(rowp + bj * HALF) = w;
;                     ss += (bf_lo(w.x) * bf_lo(w.x) + bf_hi(w.x) * bf_hi(w.x)) + (bf_lo(w.y) * bf_lo(w.y) + bf_hi(w.y) * bf_hi(w.y));
;                     ss += (bf_lo(w.z) * bf_lo(w.z) + bf_hi(w.z) * bf_hi(w.z)) + (bf_lo(w.w) * bf_lo(w.w) + bf_hi(w.w) * bf_hi(w.w)); }
;                 ss = fq_sum(ss);
;                 if (fq == 0) part[(size_t)(row0 + ai * HALF + m * 16) * 16 + u.pn * 4 + wc] = ss; } }
.LBB0_2030:
	s_or_b64 exec, exec, s[52:53]
	v_add_u32_e32 v32, 0xa0, v148
	v_ashrrev_i32_e32 v33, 31, v32
	v_lshlrev_b64 v[34:35], 11, v[32:33]
	v_lshl_add_u64 v[34:35], s[94:95], 0, v[34:35]
	v_lshl_add_u64 v[38:39], v[146:147], 1, v[34:35]
	s_nop 0
	v_lshlrev_b32_e32 v40, 16, v230
	v_and_b32_e32 v34, 0xffff0000, v230
	v_lshlrev_b32_e32 v41, 16, v231
	v_and_b32_e32 v35, 0xffff0000, v231
	v_lshlrev_b32_e32 v43, 16, v233
	v_and_b32_e32 v37, 0xffff0000, v233
	v_lshlrev_b32_e32 v42, 16, v232
	v_and_b32_e32 v36, 0xffff0000, v232
	v_add_f32_e32 v28, v28, v40
	v_add_f32_e32 v29, v29, v34
	v_add_f32_e32 v30, v30, v41
	v_add_f32_e32 v31, v31, v35
	v_add_f32_e32 v27, v27, v37
	v_add_f32_e32 v34, v24, v42
	v_add_f32_e32 v35, v25, v36
	v_add_f32_e32 v36, v26, v43
	v_cvt_pk_bf16_f32 v24, v28, v29
	v_cvt_pk_bf16_f32 v25, v30, v31
	v_cvt_pk_bf16_f32 v26, v34, v35
	v_cvt_pk_bf16_f32 v27, v36, v27
	s_nop 0
	v_lshlrev_b32_e32 v34, 16, v24
	global_store_dwordx4 v[38:39], v[24:27], off
	v_lshlrev_b32_e32 v35, 16, v25
	v_lshlrev_b32_e32 v36, 16, v26
	v_and_b32_e32 v24, 0xffff0000, v24
	v_and_b32_e32 v25, 0xffff0000, v25
	v_and_b32_e32 v26, 0xffff0000, v26
	v_lshlrev_b32_e32 v37, 16, v27
	v_and_b32_e32 v27, 0xffff0000, v27
	v_mul_f32_e32 v24, v24, v24
	v_mul_f32_e32 v25, v25, v25
	v_mul_f32_e32 v26, v26, v26
	v_mul_f32_e32 v27, v27, v27
	v_fmac_f32_e32 v24, v34, v34
	v_fmac_f32_e32 v25, v35, v35
	v_fmac_f32_e32 v26, v36, v36
	v_fmac_f32_e32 v27, v37, v37
	v_add_f32_e32 v24, v24, v25
	v_add_f32_e32 v25, v26, v27
	v_add_f32_e32 v24, v24, v25
	v_lshlrev_b32_e32 v25, 16, v234
	v_and_b32_e32 v26, 0xffff0000, v234
	v_and_b32_e32 v28, 0xffff0000, v235
	v_lshlrev_b32_e32 v27, 16, v235
	v_lshlrev_b32_e32 v29, 16, v236
	v_and_b32_e32 v30, 0xffff0000, v236
	v_lshlrev_b32_e32 v34, 16, v237
	v_and_b32_e32 v31, 0xffff0000, v237
	v_add_f32_e32 v21, v21, v26
	v_add_f32_e32 v23, v23, v28
	v_add_f32_e32 v20, v20, v25
	v_add_f32_e32 v22, v22, v27
	v_add_f32_e32 v25, v16, v29
	v_add_f32_e32 v26, v17, v30
	v_add_f32_e32 v19, v19, v31
	v_cvt_pk_bf16_f32 v16, v20, v21
	v_cvt_pk_bf16_f32 v17, v22, v23
	v_add_f32_e32 v27, v18, v34
	v_and_b32_e32 v21, 0xffff0000, v16
	v_and_b32_e32 v23, 0xffff0000, v17
	v_cvt_pk_bf16_f32 v18, v25, v26
	v_cvt_pk_bf16_f32 v19, v27, v19
	v_lshlrev_b32_e32 v20, 16, v16
	v_lshlrev_b32_e32 v22, 16, v17
	v_and_b32_e32 v26, 0xffff0000, v18
	v_and_b32_e32 v28, 0xffff0000, v19
	v_mul_f32_e32 v21, v21, v21
	v_mul_f32_e32 v23, v23, v23
	v_lshlrev_b32_e32 v25, 16, v18
	v_lshlrev_b32_e32 v27, 16, v19
	v_mul_f32_e32 v26, v26, v26
	v_mul_f32_e32 v28, v28, v28
	v_fmac_f32_e32 v21, v20, v20
	v_fmac_f32_e32 v23, v22, v22
	v_fmac_f32_e32 v26, v25, v25
	v_fmac_f32_e32 v28, v27, v27
	v_add_f32_e32 v20, v21, v23
	v_add_f32_e32 v21, v26, v28
	v_add_f32_e32 v20, v24, v20
	v_add_f32_e32 v20, v20, v21
	ds_swizzle_b32 v21, v20 offset:swizzle(SWAP,16)
	global_store_dwordx4 v[38:39], v[16:19], off offset:256
	s_waitcnt lgkmcnt(0)
	s_nop 0
	v_add_f32_e32 v16, v20, v21
	v_mov_b32_e32 v17, v16
	s_nop 1
	v_permlane32_swap_b32_e32 v16, v17
	s_and_saveexec_b64 s[52:53], vcc
	s_cbranch_execz .LBB0_2032
	v_lshlrev_b64 v[18:19], 6, v[32:33]
	v_lshl_add_u64 v[18:19], s[96:97], 0, v[18:19]
	v_lshl_add_u64 v[18:19], s[42:43], 2, v[18:19]
	s_lshl_b32 s58, s31, 2
	v_lshl_add_u64 v[18:19], v[18:19], 0, s[58:59]
	v_add_f32_e32 v16, v16, v17
	global_store_dword v[18:19], v16, off
.LBB0_2032:
	s_or_b64 exec, exec, s[52:53]
	v_add_u32_e32 v16, 0xb0, v148
	v_ashrrev_i32_e32 v17, 31, v16
	v_lshlrev_b64 v[18:19], 11, v[16:17]
	v_lshl_add_u64 v[18:19], s[94:95], 0, v[18:19]
	v_lshl_add_u64 v[22:23], v[146:147], 1, v[18:19]
	s_nop 0
	v_lshlrev_b32_e32 v24, 16, v238
	v_and_b32_e32 v18, 0xffff0000, v238
	v_lshlrev_b32_e32 v25, 16, v239
	v_and_b32_e32 v19, 0xffff0000, v239
	v_lshlrev_b32_e32 v27, 16, v241
	v_and_b32_e32 v21, 0xffff0000, v241
	v_lshlrev_b32_e32 v26, 16, v240
	v_and_b32_e32 v20, 0xffff0000, v240
	v_add_f32_e32 v12, v12, v24
	v_add_f32_e32 v13, v13, v18
	v_add_f32_e32 v14, v14, v25
	v_add_f32_e32 v15, v15, v19
	v_add_f32_e32 v11, v11, v21
	v_add_f32_e32 v18, v8, v26
	v_add_f32_e32 v19, v9, v20
	v_add_f32_e32 v20, v10, v27
	v_cvt_pk_bf16_f32 v8, v12, v13
	v_cvt_pk_bf16_f32 v9, v14, v15
	v_cvt_pk_bf16_f32 v10, v18, v19
	v_cvt_pk_bf16_f32 v11, v20, v11
	s_nop 0
	v_lshlrev_b32_e32 v18, 16, v8
	global_store_dwordx4 v[22:23], v[8:11], off
	v_lshlrev_b32_e32 v19, 16, v9
	v_lshlrev_b32_e32 v20, 16, v10
	v_and_b32_e32 v8, 0xffff0000, v8
	v_and_b32_e32 v9, 0xffff0000, v9
	v_and_b32_e32 v10, 0xffff0000, v10
	v_lshlrev_b32_e32 v21, 16, v11
	v_and_b32_e32 v11, 0xffff0000, v11
	v_mul_f32_e32 v8, v8, v8
	v_mul_f32_e32 v9, v9, v9
	v_mul_f32_e32 v10, v10, v10
	v_mul_f32_e32 v11, v11, v11
	v_fmac_f32_e32 v8, v18, v18
	v_fmac_f32_e32 v9, v19, v19
	v_fmac_f32_e32 v10, v20, v20
	v_fmac_f32_e32 v11, v21, v21
	v_add_f32_e32 v8, v8, v9
	v_add_f32_e32 v9, v10, v11
	v_add_f32_e32 v8, v8, v9
	v_lshlrev_b32_e32 v9, 16, v242
	v_and_b32_e32 v10, 0xffff0000, v242
	v_and_b32_e32 v12, 0xffff0000, v243
	v_lshlrev_b32_e32 v11, 16, v243
	v_lshlrev_b32_e32 v13, 16, v244
	v_and_b32_e32 v14, 0xffff0000, v244
	v_lshlrev_b32_e32 v18, 16, v245
	v_and_b32_e32 v15, 0xffff0000, v245
	v_add_f32_e32 v5, v5, v10
	v_add_f32_e32 v7, v7, v12
	v_add_f32_e32 v4, v4, v9
	v_add_f32_e32 v6, v6, v11
	v_add_f32_e32 v9, v0, v13
	v_add_f32_e32 v10, v1, v14
	v_add_f32_e32 v3, v3, v15
	v_cvt_pk_bf16_f32 v0, v4, v5
	v_cvt_pk_bf16_f32 v1, v6, v7
	v_add_f32_e32 v11, v2, v18
	v_and_b32_e32 v5, 0xffff0000, v0
	v_and_b32_e32 v7, 0xffff0000, v1
	v_cvt_pk_bf16_f32 v2, v9, v10
	v_cvt_pk_bf16_f32 v3, v11, v3
	v_lshlrev_b32_e32 v4, 16, v0
	v_lshlrev_b32_e32 v6, 16, v1
	v_and_b32_e32 v10, 0xffff0000, v2
	v_and_b32_e32 v12, 0xffff0000, v3
	v_mul_f32_e32 v5, v5, v5
	v_mul_f32_e32 v7, v7, v7
	v_lshlrev_b32_e32 v9, 16, v2
	v_lshlrev_b32_e32 v11, 16, v3
	v_mul_f32_e32 v10, v10, v10
	v_mul_f32_e32 v12, v12, v12
	v_fmac_f32_e32 v5, v4, v4
	v_fmac_f32_e32 v7, v6, v6
	v_fmac_f32_e32 v10, v9, v9
	v_fmac_f32_e32 v12, v11, v11
	v_add_f32_e32 v4, v5, v7
	v_add_f32_e32 v5, v10, v12
	v_add_f32_e32 v4, v8, v4
	v_add_f32_e32 v4, v4, v5
	ds_swizzle_b32 v5, v4 offset:swizzle(SWAP,16)
	global_store_dwordx4 v[22:23], v[0:3], off offset:256
	s_waitcnt lgkmcnt(0)
	s_nop 0
	v_add_f32_e32 v0, v4, v5
	v_mov_b32_e32 v1, v0
	s_nop 1
	v_permlane32_swap_b32_e32 v0, v1
	s_and_saveexec_b64 s[52:53], vcc
	s_cbranch_execz .LBB0_2034
	v_lshlrev_b64 v[2:3], 6, v[16:17]
	v_lshl_add_u64 v[2:3], s[96:97], 0, v[2:3]
	v_lshl_add_u64 v[2:3], s[42:43], 2, v[2:3]
	s_lshl_b32 s58, s31, 2
	v_lshl_add_u64 v[2:3], v[2:3], 0, s[58:59]
	v_add_f32_e32 v0, v0, v1
	global_store_dword v[2:3], v0, off
